# v71 (DMA split 2+6+2+6, no rebalancing) + DMA-first load segments
# baseline (speedup 1.0000x reference)
.LBB0_163:
	s_add_u32 s26, s24, 0xfffc0080
	s_addc_u32 s27, s25, -1
	s_cmp_eq_u32 s55, 12
	s_cselect_b32 s29, s19, s27
	s_cselect_b32 s28, s51, s26
	s_cselect_b32 s27, s17, s54
	s_cselect_b32 s26, s52, s53
	s_add_i32 m0, s38, 0xc000
	s_nop 0
	global_load_lds_dwordx4 v138, s[24:25]
	s_add_i32 m0, s38, 0xe000
	s_nop 0
	global_load_lds_dwordx4 v136, s[24:25]
	ds_read_b128 v[144:147], v151
	ds_read_b128 v[156:159], v151 offset:1024
	ds_read_b128 v[160:163], v151 offset:2048
	ds_read_b128 v[164:167], v151 offset:3072
	ds_read_b128 v[168:171], v152
	ds_read_b128 v[172:175], v152 offset:1024
	ds_read_b128 v[176:179], v152 offset:2048
	ds_read_b128 v[180:183], v152 offset:3072
	ds_read_b128 v[184:187], v153
	ds_read_b128 v[188:191], v153 offset:1024
	ds_read_b128 v[192:195], v153 offset:2048
	ds_read_b128 v[196:199], v153 offset:3072
	ds_read_b128 v[200:203], v153 offset:4096
	ds_read_b128 v[208:211], v153 offset:5120
	ds_read_b128 v[212:215], v153 offset:6144
	ds_read_b128 v[216:219], v153 offset:7168
	s_waitcnt vmcnt(8)
	s_waitcnt lgkmcnt(0)
	s_barrier
	s_waitcnt lgkmcnt(0)
	v_mfma_f32_16x16x32_bf16 v[124:127], v[144:147], v[184:187], v[124:127]
	v_mfma_f32_16x16x32_bf16 v[120:123], v[160:163], v[184:187], v[120:123]
	v_mfma_f32_16x16x32_bf16 v[108:111], v[144:147], v[192:195], v[108:111]
	v_mfma_f32_16x16x32_bf16 v[104:107], v[160:163], v[192:195], v[104:107]
	v_mfma_f32_16x16x32_bf16 v[92:95], v[144:147], v[200:203], v[92:95]
	v_mfma_f32_16x16x32_bf16 v[88:91], v[160:163], v[200:203], v[88:91]
	v_mfma_f32_16x16x32_bf16 v[76:79], v[144:147], v[212:215], v[76:79]
	v_mfma_f32_16x16x32_bf16 v[72:75], v[160:163], v[212:215], v[72:75]
	v_mfma_f32_16x16x32_bf16 v[124:127], v[156:159], v[188:191], v[124:127]
	v_mfma_f32_16x16x32_bf16 v[120:123], v[164:167], v[188:191], v[120:123]
	v_mfma_f32_16x16x32_bf16 v[108:111], v[156:159], v[196:199], v[108:111]
	v_mfma_f32_16x16x32_bf16 v[104:107], v[164:167], v[196:199], v[104:107]
	v_mfma_f32_16x16x32_bf16 v[92:95], v[156:159], v[208:211], v[92:95]
	v_mfma_f32_16x16x32_bf16 v[88:91], v[164:167], v[208:211], v[88:91]
	v_mfma_f32_16x16x32_bf16 v[76:79], v[156:159], v[216:219], v[76:79]
	v_mfma_f32_16x16x32_bf16 v[72:75], v[164:167], v[216:219], v[72:75]
	v_mfma_f32_16x16x32_bf16 v[116:119], v[168:171], v[184:187], v[116:119]
	v_mfma_f32_16x16x32_bf16 v[112:115], v[176:179], v[184:187], v[112:115]
	v_mfma_f32_16x16x32_bf16 v[100:103], v[168:171], v[192:195], v[100:103]
	v_mfma_f32_16x16x32_bf16 v[96:99], v[176:179], v[192:195], v[96:99]
	v_mfma_f32_16x16x32_bf16 v[84:87], v[168:171], v[200:203], v[84:87]
	v_mfma_f32_16x16x32_bf16 v[80:83], v[176:179], v[200:203], v[80:83]
	v_mfma_f32_16x16x32_bf16 v[68:71], v[168:171], v[212:215], v[68:71]
	v_mfma_f32_16x16x32_bf16 v[64:67], v[176:179], v[212:215], v[64:67]
	v_mfma_f32_16x16x32_bf16 v[116:119], v[172:175], v[188:191], v[116:119]
	v_mfma_f32_16x16x32_bf16 v[112:115], v[180:183], v[188:191], v[112:115]
	v_mfma_f32_16x16x32_bf16 v[100:103], v[172:175], v[196:199], v[100:103]
	v_mfma_f32_16x16x32_bf16 v[96:99], v[180:183], v[196:199], v[96:99]
	v_mfma_f32_16x16x32_bf16 v[84:87], v[172:175], v[208:211], v[84:87]
	v_mfma_f32_16x16x32_bf16 v[80:83], v[180:183], v[208:211], v[80:83]
	v_mfma_f32_16x16x32_bf16 v[68:71], v[172:175], v[216:219], v[68:71]
	v_mfma_f32_16x16x32_bf16 v[64:67], v[180:183], v[216:219], v[64:67]
	s_barrier
	s_add_i32 s56, s48, s35
	s_mov_b32 m0, s56
	s_nop 0
	global_load_lds_dwordx4 v132, s[26:27]
	s_add_i32 m0, s56, 0x2000
	s_add_u32 s56, s26, 0x40000
	s_mov_b64 s[98:99], s[26:27]
	s_addc_u32 s57, s27, 0
	s_add_i32 s58, s49, s35
	global_load_lds_dwordx4 v128, s[26:27]
	s_mov_b32 m0, s58
	s_mov_b64 s[100:101], s[28:29]
	global_load_lds_dwordx4 v132, s[56:57]
	s_add_i32 m0, s58, 0x2000
	s_nop 0
	global_load_lds_dwordx4 v128, s[56:57]
	s_mov_b32 m0, s38
	s_nop 0
	global_load_lds_dwordx4 v134, s[28:29]
	s_mov_b32 m0, s39
	s_nop 0
	global_load_lds_dwordx4 v130, s[28:29]
	ds_read_b128 v[184:187], v153 offset:16384
	ds_read_b128 v[188:191], v153 offset:17408
	ds_read_b128 v[192:195], v153 offset:18432
	ds_read_b128 v[196:199], v153 offset:19456
	ds_read_b128 v[200:203], v153 offset:20480
	ds_read_b128 v[208:211], v153 offset:21504
	ds_read_b128 v[212:215], v153 offset:22528
	ds_read_b128 v[216:219], v153 offset:23552
	s_waitcnt vmcnt(8)
	s_waitcnt lgkmcnt(0)
	s_barrier
	s_waitcnt lgkmcnt(0)
	v_mfma_f32_16x16x32_bf16 v[60:63], v[144:147], v[184:187], v[60:63]
	v_mfma_f32_16x16x32_bf16 v[56:59], v[160:163], v[184:187], v[56:59]
	v_mfma_f32_16x16x32_bf16 v[44:47], v[144:147], v[192:195], v[44:47]
	v_mfma_f32_16x16x32_bf16 v[40:43], v[160:163], v[192:195], v[40:43]
	v_mfma_f32_16x16x32_bf16 v[28:31], v[144:147], v[200:203], v[28:31]
	v_mfma_f32_16x16x32_bf16 v[24:27], v[160:163], v[200:203], v[24:27]
	v_mfma_f32_16x16x32_bf16 v[12:15], v[144:147], v[212:215], v[12:15]
	v_mfma_f32_16x16x32_bf16 v[8:11], v[160:163], v[212:215], v[8:11]
	v_mfma_f32_16x16x32_bf16 v[60:63], v[156:159], v[188:191], v[60:63]
	v_mfma_f32_16x16x32_bf16 v[56:59], v[164:167], v[188:191], v[56:59]
	v_mfma_f32_16x16x32_bf16 v[44:47], v[156:159], v[196:199], v[44:47]
	v_mfma_f32_16x16x32_bf16 v[40:43], v[164:167], v[196:199], v[40:43]
	v_mfma_f32_16x16x32_bf16 v[28:31], v[156:159], v[208:211], v[28:31]
	v_mfma_f32_16x16x32_bf16 v[24:27], v[164:167], v[208:211], v[24:27]
	v_mfma_f32_16x16x32_bf16 v[12:15], v[156:159], v[216:219], v[12:15]
	v_mfma_f32_16x16x32_bf16 v[8:11], v[164:167], v[216:219], v[8:11]
	v_mfma_f32_16x16x32_bf16 v[52:55], v[168:171], v[184:187], v[52:55]
	v_mfma_f32_16x16x32_bf16 v[48:51], v[176:179], v[184:187], v[48:51]
	v_mfma_f32_16x16x32_bf16 v[36:39], v[168:171], v[192:195], v[36:39]
	v_mfma_f32_16x16x32_bf16 v[32:35], v[176:179], v[192:195], v[32:35]
	v_mfma_f32_16x16x32_bf16 v[20:23], v[168:171], v[200:203], v[20:23]
	v_mfma_f32_16x16x32_bf16 v[16:19], v[176:179], v[200:203], v[16:19]
	v_mfma_f32_16x16x32_bf16 v[4:7], v[168:171], v[212:215], v[4:7]
	v_mfma_f32_16x16x32_bf16 v[0:3], v[176:179], v[212:215], v[0:3]
	v_mfma_f32_16x16x32_bf16 v[52:55], v[172:175], v[188:191], v[52:55]
	v_mfma_f32_16x16x32_bf16 v[48:51], v[180:183], v[188:191], v[48:51]
	v_mfma_f32_16x16x32_bf16 v[36:39], v[172:175], v[196:199], v[36:39]
	v_mfma_f32_16x16x32_bf16 v[32:35], v[180:183], v[196:199], v[32:35]
	v_mfma_f32_16x16x32_bf16 v[20:23], v[172:175], v[208:211], v[20:23]
	v_mfma_f32_16x16x32_bf16 v[16:19], v[180:183], v[208:211], v[16:19]
	v_mfma_f32_16x16x32_bf16 v[4:7], v[172:175], v[216:219], v[4:7]
	v_mfma_f32_16x16x32_bf16 v[0:3], v[180:183], v[216:219], v[0:3]
	s_barrier
	s_add_i32 s56, 0, 0x18000
	s_add_i32 s57, 0, 0x1c000
	s_add_u32 s28, s28, 0x40000
	s_addc_u32 s29, s29, 0
	s_mov_b32 m0, s40
	s_nop 0
	global_load_lds_dwordx4 v134, s[28:29]
	s_mov_b32 m0, s41
	s_nop 0
	global_load_lds_dwordx4 v130, s[28:29]
	v_add_u32_e32 v164, s56, v149
	v_add_u32_e32 v180, s57, v149
	ds_read_b128 v[144:147], v164
	ds_read_b128 v[156:159], v164 offset:1024
	ds_read_b128 v[160:163], v164 offset:2048
	ds_read_b128 v[164:167], v164 offset:3072
	ds_read_b128 v[168:171], v180
	ds_read_b128 v[172:175], v180 offset:1024
	ds_read_b128 v[176:179], v180 offset:2048
	ds_read_b128 v[180:183], v180 offset:3072
	ds_read_b128 v[184:187], v153 offset:32768
	ds_read_b128 v[188:191], v153 offset:33792
	ds_read_b128 v[192:195], v153 offset:34816
	ds_read_b128 v[196:199], v153 offset:35840
	ds_read_b128 v[200:203], v153 offset:36864
	ds_read_b128 v[208:211], v153 offset:37888
	ds_read_b128 v[212:215], v153 offset:38912
	ds_read_b128 v[216:219], v153 offset:39936
	s_waitcnt vmcnt(8)
	s_waitcnt lgkmcnt(0)
	s_barrier
	s_waitcnt lgkmcnt(0)
	v_mfma_f32_16x16x32_bf16 v[124:127], v[144:147], v[184:187], v[124:127]
	v_mfma_f32_16x16x32_bf16 v[120:123], v[160:163], v[184:187], v[120:123]
	v_mfma_f32_16x16x32_bf16 v[108:111], v[144:147], v[192:195], v[108:111]
	v_mfma_f32_16x16x32_bf16 v[104:107], v[160:163], v[192:195], v[104:107]
	v_mfma_f32_16x16x32_bf16 v[92:95], v[144:147], v[200:203], v[92:95]
	v_mfma_f32_16x16x32_bf16 v[88:91], v[160:163], v[200:203], v[88:91]
	v_mfma_f32_16x16x32_bf16 v[76:79], v[144:147], v[212:215], v[76:79]
	v_mfma_f32_16x16x32_bf16 v[72:75], v[160:163], v[212:215], v[72:75]
	v_mfma_f32_16x16x32_bf16 v[124:127], v[156:159], v[188:191], v[124:127]
	v_mfma_f32_16x16x32_bf16 v[120:123], v[164:167], v[188:191], v[120:123]
	v_mfma_f32_16x16x32_bf16 v[108:111], v[156:159], v[196:199], v[108:111]
	v_mfma_f32_16x16x32_bf16 v[104:107], v[164:167], v[196:199], v[104:107]
	v_mfma_f32_16x16x32_bf16 v[92:95], v[156:159], v[208:211], v[92:95]
	v_mfma_f32_16x16x32_bf16 v[88:91], v[164:167], v[208:211], v[88:91]
	v_mfma_f32_16x16x32_bf16 v[76:79], v[156:159], v[216:219], v[76:79]
	v_mfma_f32_16x16x32_bf16 v[72:75], v[164:167], v[216:219], v[72:75]
	v_mfma_f32_16x16x32_bf16 v[116:119], v[168:171], v[184:187], v[116:119]
	v_mfma_f32_16x16x32_bf16 v[112:115], v[176:179], v[184:187], v[112:115]
	v_mfma_f32_16x16x32_bf16 v[100:103], v[168:171], v[192:195], v[100:103]
	v_mfma_f32_16x16x32_bf16 v[96:99], v[176:179], v[192:195], v[96:99]
	v_mfma_f32_16x16x32_bf16 v[84:87], v[168:171], v[200:203], v[84:87]
	v_mfma_f32_16x16x32_bf16 v[80:83], v[176:179], v[200:203], v[80:83]
	v_mfma_f32_16x16x32_bf16 v[68:71], v[168:171], v[212:215], v[68:71]
	v_mfma_f32_16x16x32_bf16 v[64:67], v[176:179], v[212:215], v[64:67]
	v_mfma_f32_16x16x32_bf16 v[116:119], v[172:175], v[188:191], v[116:119]
	v_mfma_f32_16x16x32_bf16 v[112:115], v[180:183], v[188:191], v[112:115]
	v_mfma_f32_16x16x32_bf16 v[100:103], v[172:175], v[196:199], v[100:103]
	v_mfma_f32_16x16x32_bf16 v[96:99], v[180:183], v[196:199], v[96:99]
	v_mfma_f32_16x16x32_bf16 v[84:87], v[172:175], v[208:211], v[84:87]
	v_mfma_f32_16x16x32_bf16 v[80:83], v[180:183], v[208:211], v[80:83]
	v_mfma_f32_16x16x32_bf16 v[68:71], v[172:175], v[216:219], v[68:71]
	v_mfma_f32_16x16x32_bf16 v[64:67], v[180:183], v[216:219], v[64:67]
	s_barrier
	s_add_i32 s28, s56, s35
	s_mov_b32 m0, s28
	s_nop 0
	global_load_lds_dwordx4 v220, s[26:27]
	s_add_i32 m0, s28, 0x2000
	s_add_u32 s26, s26, 0x40080
	s_addc_u32 s27, s27, 0
	s_add_i32 s28, s57, s35
	global_load_lds_dwordx4 v204, s[98:99]
	s_mov_b32 m0, s28
	s_nop 0
	global_load_lds_dwordx4 v132, s[26:27]
	s_add_i32 m0, s28, 0x2000
	s_nop 0
	global_load_lds_dwordx4 v128, s[26:27]
	s_mov_b32 m0, s45
	s_nop 0
	global_load_lds_dwordx4 v221, s[100:101]
	s_mov_b32 m0, s46
	s_nop 0
	global_load_lds_dwordx4 v205, s[100:101]
	ds_read_b128 v[184:187], v153 offset:49152
	ds_read_b128 v[188:191], v153 offset:50176
	ds_read_b128 v[192:195], v153 offset:51200
	ds_read_b128 v[196:199], v153 offset:52224
	ds_read_b128 v[200:203], v153 offset:53248
	ds_read_b128 v[208:211], v153 offset:54272
	ds_read_b128 v[212:215], v153 offset:55296
	ds_read_b128 v[216:219], v153 offset:56320
	s_waitcnt vmcnt(8)
	s_waitcnt lgkmcnt(0)
	s_barrier
	s_waitcnt lgkmcnt(0)
	v_mfma_f32_16x16x32_bf16 v[60:63], v[144:147], v[184:187], v[60:63]
	v_mfma_f32_16x16x32_bf16 v[56:59], v[160:163], v[184:187], v[56:59]
	v_mfma_f32_16x16x32_bf16 v[44:47], v[144:147], v[192:195], v[44:47]
	v_mfma_f32_16x16x32_bf16 v[40:43], v[160:163], v[192:195], v[40:43]
	v_mfma_f32_16x16x32_bf16 v[28:31], v[144:147], v[200:203], v[28:31]
	v_mfma_f32_16x16x32_bf16 v[24:27], v[160:163], v[200:203], v[24:27]
	v_mfma_f32_16x16x32_bf16 v[12:15], v[144:147], v[212:215], v[12:15]
	v_mfma_f32_16x16x32_bf16 v[8:11], v[160:163], v[212:215], v[8:11]
	v_mfma_f32_16x16x32_bf16 v[60:63], v[156:159], v[188:191], v[60:63]
	v_mfma_f32_16x16x32_bf16 v[56:59], v[164:167], v[188:191], v[56:59]
	v_mfma_f32_16x16x32_bf16 v[44:47], v[156:159], v[196:199], v[44:47]
	v_mfma_f32_16x16x32_bf16 v[40:43], v[164:167], v[196:199], v[40:43]
	v_mfma_f32_16x16x32_bf16 v[28:31], v[156:159], v[208:211], v[28:31]
	v_mfma_f32_16x16x32_bf16 v[24:27], v[164:167], v[208:211], v[24:27]
	v_mfma_f32_16x16x32_bf16 v[12:15], v[156:159], v[216:219], v[12:15]
	v_mfma_f32_16x16x32_bf16 v[8:11], v[164:167], v[216:219], v[8:11]
	v_mfma_f32_16x16x32_bf16 v[52:55], v[168:171], v[184:187], v[52:55]
	v_mfma_f32_16x16x32_bf16 v[48:51], v[176:179], v[184:187], v[48:51]
	v_mfma_f32_16x16x32_bf16 v[36:39], v[168:171], v[192:195], v[36:39]
	v_mfma_f32_16x16x32_bf16 v[32:35], v[176:179], v[192:195], v[32:35]
	v_mfma_f32_16x16x32_bf16 v[20:23], v[168:171], v[200:203], v[20:23]
	v_mfma_f32_16x16x32_bf16 v[16:19], v[176:179], v[200:203], v[16:19]
	v_mfma_f32_16x16x32_bf16 v[4:7], v[168:171], v[212:215], v[4:7]
	v_mfma_f32_16x16x32_bf16 v[0:3], v[176:179], v[212:215], v[0:3]
	v_mfma_f32_16x16x32_bf16 v[52:55], v[172:175], v[188:191], v[52:55]
	v_mfma_f32_16x16x32_bf16 v[48:51], v[180:183], v[188:191], v[48:51]
	v_mfma_f32_16x16x32_bf16 v[36:39], v[172:175], v[196:199], v[36:39]
	v_mfma_f32_16x16x32_bf16 v[32:35], v[180:183], v[196:199], v[32:35]
	v_mfma_f32_16x16x32_bf16 v[20:23], v[172:175], v[208:211], v[20:23]
	v_mfma_f32_16x16x32_bf16 v[16:19], v[180:183], v[208:211], v[16:19]
	v_mfma_f32_16x16x32_bf16 v[4:7], v[172:175], v[216:219], v[4:7]
	v_mfma_f32_16x16x32_bf16 v[0:3], v[180:183], v[216:219], v[0:3]
	s_barrier
	s_add_i32 s55, s55, 2
	s_add_u32 s53, s53, 0x100
	s_addc_u32 s54, s54, 0
	s_add_u32 s24, s24, 0x100
	s_addc_u32 s25, s25, 0
	s_cmp_gt_u32 s55, 13
	s_cbranch_scc0 .LBB0_163
	s_setprio 0
	s_and_b64 vcc, exec, s[14:15]
	s_cbranch_vccz .LBB0_166
	s_barrier

.LBB0_606:
	s_add_u32 s30, s28, 0x100
	s_addc_u32 s31, s29, 0
	s_cmp_eq_u32 s58, 12
	s_cselect_b32 s37, s21, s31
	s_cselect_b32 s36, s27, s30
	s_cselect_b32 s35, s19, s57
	s_cselect_b32 s34, s55, s56
	s_add_i32 m0, s44, 0xc000
	s_nop 0
	global_load_lds_dwordx4 v134, s[28:29]
	s_add_i32 m0, s44, 0xe000
	s_nop 0
	global_load_lds_dwordx4 v132, s[28:29]
	ds_read_b128 v[140:143], v147
	ds_read_b128 v[150:153], v147 offset:1024
	ds_read_b128 v[154:157], v147 offset:2048
	ds_read_b128 v[158:161], v147 offset:3072
	ds_read_b128 v[162:165], v148
	ds_read_b128 v[166:169], v148 offset:1024
	ds_read_b128 v[170:173], v148 offset:2048
	ds_read_b128 v[174:177], v148 offset:3072
	ds_read_b128 v[178:181], v149
	ds_read_b128 v[182:185], v149 offset:1024
	ds_read_b128 v[186:189], v149 offset:2048
	ds_read_b128 v[190:193], v149 offset:3072
	ds_read_b128 v[194:197], v149 offset:4096
	ds_read_b128 v[198:201], v149 offset:5120
	ds_read_b128 v[202:205], v149 offset:6144
	ds_read_b128 v[208:211], v149 offset:7168
	s_waitcnt vmcnt(8)
	s_waitcnt lgkmcnt(0)
	s_barrier
	s_waitcnt lgkmcnt(0)
	v_mfma_f32_16x16x32_bf16 v[124:127], v[140:143], v[178:181], v[124:127]
	v_mfma_f32_16x16x32_bf16 v[120:123], v[154:157], v[178:181], v[120:123]
	v_mfma_f32_16x16x32_bf16 v[108:111], v[140:143], v[186:189], v[108:111]
	v_mfma_f32_16x16x32_bf16 v[104:107], v[154:157], v[186:189], v[104:107]
	v_mfma_f32_16x16x32_bf16 v[92:95], v[140:143], v[194:197], v[92:95]
	v_mfma_f32_16x16x32_bf16 v[88:91], v[154:157], v[194:197], v[88:91]
	v_mfma_f32_16x16x32_bf16 v[76:79], v[140:143], v[202:205], v[76:79]
	v_mfma_f32_16x16x32_bf16 v[72:75], v[154:157], v[202:205], v[72:75]
	v_mfma_f32_16x16x32_bf16 v[124:127], v[150:153], v[182:185], v[124:127]
	v_mfma_f32_16x16x32_bf16 v[120:123], v[158:161], v[182:185], v[120:123]
	v_mfma_f32_16x16x32_bf16 v[108:111], v[150:153], v[190:193], v[108:111]
	v_mfma_f32_16x16x32_bf16 v[104:107], v[158:161], v[190:193], v[104:107]
	v_mfma_f32_16x16x32_bf16 v[92:95], v[150:153], v[198:201], v[92:95]
	v_mfma_f32_16x16x32_bf16 v[88:91], v[158:161], v[198:201], v[88:91]
	v_mfma_f32_16x16x32_bf16 v[76:79], v[150:153], v[208:211], v[76:79]
	v_mfma_f32_16x16x32_bf16 v[72:75], v[158:161], v[208:211], v[72:75]
	v_mfma_f32_16x16x32_bf16 v[116:119], v[162:165], v[178:181], v[116:119]
	v_mfma_f32_16x16x32_bf16 v[112:115], v[170:173], v[178:181], v[112:115]
	v_mfma_f32_16x16x32_bf16 v[100:103], v[162:165], v[186:189], v[100:103]
	v_mfma_f32_16x16x32_bf16 v[96:99], v[170:173], v[186:189], v[96:99]
	v_mfma_f32_16x16x32_bf16 v[84:87], v[162:165], v[194:197], v[84:87]
	v_mfma_f32_16x16x32_bf16 v[80:83], v[170:173], v[194:197], v[80:83]
	v_mfma_f32_16x16x32_bf16 v[68:71], v[162:165], v[202:205], v[68:71]
	v_mfma_f32_16x16x32_bf16 v[64:67], v[170:173], v[202:205], v[64:67]
	v_mfma_f32_16x16x32_bf16 v[116:119], v[166:169], v[182:185], v[116:119]
	v_mfma_f32_16x16x32_bf16 v[112:115], v[174:177], v[182:185], v[112:115]
	v_mfma_f32_16x16x32_bf16 v[100:103], v[166:169], v[190:193], v[100:103]
	v_mfma_f32_16x16x32_bf16 v[96:99], v[174:177], v[190:193], v[96:99]
	v_mfma_f32_16x16x32_bf16 v[84:87], v[166:169], v[198:201], v[84:87]
	v_mfma_f32_16x16x32_bf16 v[80:83], v[174:177], v[198:201], v[80:83]
	v_mfma_f32_16x16x32_bf16 v[68:71], v[166:169], v[208:211], v[68:71]
	v_mfma_f32_16x16x32_bf16 v[64:67], v[174:177], v[208:211], v[64:67]
	s_barrier
	s_add_i32 s28, s52, s43
	s_mov_b32 m0, s28
	s_nop 0
	global_load_lds_dwordx4 v128, s[34:35]
	s_add_i32 m0, s28, 0x2000
	s_add_u32 s28, s34, 0x40000
	s_mov_b64 s[98:99], s[34:35]
	s_addc_u32 s29, s35, 0
	s_add_i32 s59, s53, s43
	global_load_lds_dwordx4 v130, s[34:35]
	s_mov_b32 m0, s59
	s_nop 0
	global_load_lds_dwordx4 v128, s[28:29]
	s_add_i32 m0, s59, 0x2000
	s_nop 0
	global_load_lds_dwordx4 v130, s[28:29]
	s_mov_b32 m0, s44
	s_nop 0
	global_load_lds_dwordx4 v128, s[36:37]
	s_mov_b32 m0, s45
	s_nop 0
	global_load_lds_dwordx4 v130, s[36:37]
	ds_read_b128 v[178:181], v149 offset:16384
	ds_read_b128 v[182:185], v149 offset:17408
	ds_read_b128 v[186:189], v149 offset:18432
	ds_read_b128 v[190:193], v149 offset:19456
	ds_read_b128 v[194:197], v149 offset:20480
	ds_read_b128 v[198:201], v149 offset:21504
	ds_read_b128 v[202:205], v149 offset:22528
	ds_read_b128 v[208:211], v149 offset:23552
	s_waitcnt vmcnt(8)
	s_waitcnt lgkmcnt(0)
	s_barrier
	s_waitcnt lgkmcnt(0)
	v_mfma_f32_16x16x32_bf16 v[60:63], v[140:143], v[178:181], v[60:63]
	v_mfma_f32_16x16x32_bf16 v[56:59], v[154:157], v[178:181], v[56:59]
	v_mfma_f32_16x16x32_bf16 v[44:47], v[140:143], v[186:189], v[44:47]
	v_mfma_f32_16x16x32_bf16 v[40:43], v[154:157], v[186:189], v[40:43]
	v_mfma_f32_16x16x32_bf16 v[28:31], v[140:143], v[194:197], v[28:31]
	v_mfma_f32_16x16x32_bf16 v[24:27], v[154:157], v[194:197], v[24:27]
	v_mfma_f32_16x16x32_bf16 v[12:15], v[140:143], v[202:205], v[12:15]
	v_mfma_f32_16x16x32_bf16 v[8:11], v[154:157], v[202:205], v[8:11]
	v_mfma_f32_16x16x32_bf16 v[60:63], v[150:153], v[182:185], v[60:63]
	v_mfma_f32_16x16x32_bf16 v[56:59], v[158:161], v[182:185], v[56:59]
	v_mfma_f32_16x16x32_bf16 v[44:47], v[150:153], v[190:193], v[44:47]
	v_mfma_f32_16x16x32_bf16 v[40:43], v[158:161], v[190:193], v[40:43]
	v_mfma_f32_16x16x32_bf16 v[28:31], v[150:153], v[198:201], v[28:31]
	v_mfma_f32_16x16x32_bf16 v[24:27], v[158:161], v[198:201], v[24:27]
	v_mfma_f32_16x16x32_bf16 v[12:15], v[150:153], v[208:211], v[12:15]
	v_mfma_f32_16x16x32_bf16 v[8:11], v[158:161], v[208:211], v[8:11]
	v_mfma_f32_16x16x32_bf16 v[52:55], v[162:165], v[178:181], v[52:55]
	v_mfma_f32_16x16x32_bf16 v[48:51], v[170:173], v[178:181], v[48:51]
	v_mfma_f32_16x16x32_bf16 v[36:39], v[162:165], v[186:189], v[36:39]
	v_mfma_f32_16x16x32_bf16 v[32:35], v[170:173], v[186:189], v[32:35]
	v_mfma_f32_16x16x32_bf16 v[20:23], v[162:165], v[194:197], v[20:23]
	v_mfma_f32_16x16x32_bf16 v[16:19], v[170:173], v[194:197], v[16:19]
	v_mfma_f32_16x16x32_bf16 v[4:7], v[162:165], v[202:205], v[4:7]
	v_mfma_f32_16x16x32_bf16 v[0:3], v[170:173], v[202:205], v[0:3]
	v_mfma_f32_16x16x32_bf16 v[52:55], v[166:169], v[182:185], v[52:55]
	v_mfma_f32_16x16x32_bf16 v[48:51], v[174:177], v[182:185], v[48:51]
	v_mfma_f32_16x16x32_bf16 v[36:39], v[166:169], v[190:193], v[36:39]
	v_mfma_f32_16x16x32_bf16 v[32:35], v[174:177], v[190:193], v[32:35]
	v_mfma_f32_16x16x32_bf16 v[20:23], v[166:169], v[198:201], v[20:23]
	v_mfma_f32_16x16x32_bf16 v[16:19], v[174:177], v[198:201], v[16:19]
	v_mfma_f32_16x16x32_bf16 v[4:7], v[166:169], v[208:211], v[4:7]
	v_mfma_f32_16x16x32_bf16 v[0:3], v[174:177], v[208:211], v[0:3]
	s_barrier
	s_add_i32 s59, 0, 0x18000
	s_add_i32 s60, 0, 0x1c000
	s_add_u32 s28, s36, 0x40000
	s_addc_u32 s29, s37, 0
	s_mov_b32 m0, s46
	s_nop 0
	global_load_lds_dwordx4 v128, s[28:29]
	s_mov_b32 m0, s47
	s_nop 0
	global_load_lds_dwordx4 v130, s[28:29]
	v_add_u32_e32 v158, s59, v145
	v_add_u32_e32 v174, s60, v145
	ds_read_b128 v[140:143], v158
	ds_read_b128 v[150:153], v158 offset:1024
	ds_read_b128 v[154:157], v158 offset:2048
	ds_read_b128 v[158:161], v158 offset:3072
	ds_read_b128 v[162:165], v174
	ds_read_b128 v[166:169], v174 offset:1024
	ds_read_b128 v[170:173], v174 offset:2048
	ds_read_b128 v[174:177], v174 offset:3072
	ds_read_b128 v[178:181], v149 offset:32768
	ds_read_b128 v[182:185], v149 offset:33792
	ds_read_b128 v[186:189], v149 offset:34816
	ds_read_b128 v[190:193], v149 offset:35840
	ds_read_b128 v[194:197], v149 offset:36864
	ds_read_b128 v[198:201], v149 offset:37888
	ds_read_b128 v[202:205], v149 offset:38912
	ds_read_b128 v[208:211], v149 offset:39936
	s_waitcnt vmcnt(8)
	s_waitcnt lgkmcnt(0)
	s_barrier
	s_waitcnt lgkmcnt(0)
	v_mfma_f32_16x16x32_bf16 v[124:127], v[140:143], v[178:181], v[124:127]
	v_mfma_f32_16x16x32_bf16 v[120:123], v[154:157], v[178:181], v[120:123]
	v_mfma_f32_16x16x32_bf16 v[108:111], v[140:143], v[186:189], v[108:111]
	v_mfma_f32_16x16x32_bf16 v[104:107], v[154:157], v[186:189], v[104:107]
	v_mfma_f32_16x16x32_bf16 v[92:95], v[140:143], v[194:197], v[92:95]
	v_mfma_f32_16x16x32_bf16 v[88:91], v[154:157], v[194:197], v[88:91]
	v_mfma_f32_16x16x32_bf16 v[76:79], v[140:143], v[202:205], v[76:79]
	v_mfma_f32_16x16x32_bf16 v[72:75], v[154:157], v[202:205], v[72:75]
	v_mfma_f32_16x16x32_bf16 v[124:127], v[150:153], v[182:185], v[124:127]
	v_mfma_f32_16x16x32_bf16 v[120:123], v[158:161], v[182:185], v[120:123]
	v_mfma_f32_16x16x32_bf16 v[108:111], v[150:153], v[190:193], v[108:111]
	v_mfma_f32_16x16x32_bf16 v[104:107], v[158:161], v[190:193], v[104:107]
	v_mfma_f32_16x16x32_bf16 v[92:95], v[150:153], v[198:201], v[92:95]
	v_mfma_f32_16x16x32_bf16 v[88:91], v[158:161], v[198:201], v[88:91]
	v_mfma_f32_16x16x32_bf16 v[76:79], v[150:153], v[208:211], v[76:79]
	v_mfma_f32_16x16x32_bf16 v[72:75], v[158:161], v[208:211], v[72:75]
	v_mfma_f32_16x16x32_bf16 v[116:119], v[162:165], v[178:181], v[116:119]
	v_mfma_f32_16x16x32_bf16 v[112:115], v[170:173], v[178:181], v[112:115]
	v_mfma_f32_16x16x32_bf16 v[100:103], v[162:165], v[186:189], v[100:103]
	v_mfma_f32_16x16x32_bf16 v[96:99], v[170:173], v[186:189], v[96:99]
	v_mfma_f32_16x16x32_bf16 v[84:87], v[162:165], v[194:197], v[84:87]
	v_mfma_f32_16x16x32_bf16 v[80:83], v[170:173], v[194:197], v[80:83]
	v_mfma_f32_16x16x32_bf16 v[68:71], v[162:165], v[202:205], v[68:71]
	v_mfma_f32_16x16x32_bf16 v[64:67], v[170:173], v[202:205], v[64:67]
	v_mfma_f32_16x16x32_bf16 v[116:119], v[166:169], v[182:185], v[116:119]
	v_mfma_f32_16x16x32_bf16 v[112:115], v[174:177], v[182:185], v[112:115]
	v_mfma_f32_16x16x32_bf16 v[100:103], v[166:169], v[190:193], v[100:103]
	v_mfma_f32_16x16x32_bf16 v[96:99], v[174:177], v[190:193], v[96:99]
	v_mfma_f32_16x16x32_bf16 v[84:87], v[166:169], v[198:201], v[84:87]
	v_mfma_f32_16x16x32_bf16 v[80:83], v[174:177], v[198:201], v[80:83]
	v_mfma_f32_16x16x32_bf16 v[68:71], v[166:169], v[208:211], v[68:71]
	v_mfma_f32_16x16x32_bf16 v[64:67], v[174:177], v[208:211], v[64:67]
	s_barrier
	s_add_i32 s28, s59, s43
	s_mov_b32 m0, s28
	s_nop 0
	global_load_lds_dwordx4 v212, s[34:35]
	s_add_i32 m0, s28, 0x2000
	s_add_u32 s28, s34, 0x40080
	s_addc_u32 s29, s35, 0
	s_add_i32 s34, s60, s43
	global_load_lds_dwordx4 v213, s[98:99]
	s_mov_b32 m0, s34
	s_nop 0
	global_load_lds_dwordx4 v128, s[28:29]
	s_add_i32 m0, s34, 0x2000
	s_nop 0
	global_load_lds_dwordx4 v130, s[28:29]
	s_mov_b32 m0, s49
	s_nop 0
	global_load_lds_dwordx4 v212, s[36:37]
	s_mov_b32 m0, s50
	s_nop 0
	global_load_lds_dwordx4 v213, s[36:37]
	ds_read_b128 v[178:181], v149 offset:49152
	ds_read_b128 v[182:185], v149 offset:50176
	ds_read_b128 v[186:189], v149 offset:51200
	ds_read_b128 v[190:193], v149 offset:52224
	ds_read_b128 v[194:197], v149 offset:53248
	ds_read_b128 v[198:201], v149 offset:54272
	ds_read_b128 v[202:205], v149 offset:55296
	ds_read_b128 v[208:211], v149 offset:56320
	s_waitcnt vmcnt(8)
	s_waitcnt lgkmcnt(0)
	s_barrier
	s_waitcnt lgkmcnt(0)
	v_mfma_f32_16x16x32_bf16 v[60:63], v[140:143], v[178:181], v[60:63]
	v_mfma_f32_16x16x32_bf16 v[56:59], v[154:157], v[178:181], v[56:59]
	v_mfma_f32_16x16x32_bf16 v[44:47], v[140:143], v[186:189], v[44:47]
	v_mfma_f32_16x16x32_bf16 v[40:43], v[154:157], v[186:189], v[40:43]
	v_mfma_f32_16x16x32_bf16 v[28:31], v[140:143], v[194:197], v[28:31]
	v_mfma_f32_16x16x32_bf16 v[24:27], v[154:157], v[194:197], v[24:27]
	v_mfma_f32_16x16x32_bf16 v[12:15], v[140:143], v[202:205], v[12:15]
	v_mfma_f32_16x16x32_bf16 v[8:11], v[154:157], v[202:205], v[8:11]
	v_mfma_f32_16x16x32_bf16 v[60:63], v[150:153], v[182:185], v[60:63]
	v_mfma_f32_16x16x32_bf16 v[56:59], v[158:161], v[182:185], v[56:59]
	v_mfma_f32_16x16x32_bf16 v[44:47], v[150:153], v[190:193], v[44:47]
	v_mfma_f32_16x16x32_bf16 v[40:43], v[158:161], v[190:193], v[40:43]
	v_mfma_f32_16x16x32_bf16 v[28:31], v[150:153], v[198:201], v[28:31]
	v_mfma_f32_16x16x32_bf16 v[24:27], v[158:161], v[198:201], v[24:27]
	v_mfma_f32_16x16x32_bf16 v[12:15], v[150:153], v[208:211], v[12:15]
	v_mfma_f32_16x16x32_bf16 v[8:11], v[158:161], v[208:211], v[8:11]
	v_mfma_f32_16x16x32_bf16 v[52:55], v[162:165], v[178:181], v[52:55]
	v_mfma_f32_16x16x32_bf16 v[48:51], v[170:173], v[178:181], v[48:51]
	v_mfma_f32_16x16x32_bf16 v[36:39], v[162:165], v[186:189], v[36:39]
	v_mfma_f32_16x16x32_bf16 v[32:35], v[170:173], v[186:189], v[32:35]
	v_mfma_f32_16x16x32_bf16 v[20:23], v[162:165], v[194:197], v[20:23]
	v_mfma_f32_16x16x32_bf16 v[16:19], v[170:173], v[194:197], v[16:19]
	v_mfma_f32_16x16x32_bf16 v[4:7], v[162:165], v[202:205], v[4:7]
	v_mfma_f32_16x16x32_bf16 v[0:3], v[170:173], v[202:205], v[0:3]
	v_mfma_f32_16x16x32_bf16 v[52:55], v[166:169], v[182:185], v[52:55]
	v_mfma_f32_16x16x32_bf16 v[48:51], v[174:177], v[182:185], v[48:51]
	v_mfma_f32_16x16x32_bf16 v[36:39], v[166:169], v[190:193], v[36:39]
	v_mfma_f32_16x16x32_bf16 v[32:35], v[174:177], v[190:193], v[32:35]
	v_mfma_f32_16x16x32_bf16 v[20:23], v[166:169], v[198:201], v[20:23]
	v_mfma_f32_16x16x32_bf16 v[16:19], v[174:177], v[198:201], v[16:19]
	v_mfma_f32_16x16x32_bf16 v[4:7], v[166:169], v[208:211], v[4:7]
	v_mfma_f32_16x16x32_bf16 v[0:3], v[174:177], v[208:211], v[0:3]
	s_barrier
	s_add_i32 s58, s58, 2
	s_add_u32 s56, s56, 0x100
	s_addc_u32 s57, s57, 0
	s_cmp_gt_u32 s58, 13
	s_mov_b64 s[28:29], s[30:31]
	s_cbranch_scc0 .LBB0_606
	s_setprio 0
	s_and_b64 vcc, exec, s[16:17]
	s_cbranch_vccz .LBB0_609
	s_barrier

.LBB0_699:
	s_add_u32 s28, s26, 0xfffc0080
	s_addc_u32 s29, s27, -1
	s_cmp_eq_u32 s53, 12
	s_cselect_b32 s31, s21, s29
	s_cselect_b32 s30, s49, s28
	s_cselect_b32 s29, s19, s52
	s_cselect_b32 s28, s50, s51
	s_add_i32 m0, s39, 0xc000
	s_nop 0
	global_load_lds_dwordx4 v138, s[26:27]
	s_add_i32 m0, s39, 0xe000
	s_nop 0
	global_load_lds_dwordx4 v136, s[26:27]
	ds_read_b128 v[144:147], v151
	ds_read_b128 v[156:159], v151 offset:1024
	ds_read_b128 v[160:163], v151 offset:2048
	ds_read_b128 v[164:167], v151 offset:3072
	ds_read_b128 v[168:171], v152
	ds_read_b128 v[172:175], v152 offset:1024
	ds_read_b128 v[176:179], v152 offset:2048
	ds_read_b128 v[180:183], v152 offset:3072
	ds_read_b128 v[184:187], v153
	ds_read_b128 v[188:191], v153 offset:1024
	ds_read_b128 v[192:195], v153 offset:2048
	ds_read_b128 v[196:199], v153 offset:3072
	ds_read_b128 v[200:203], v153 offset:4096
	ds_read_b128 v[208:211], v153 offset:5120
	ds_read_b128 v[212:215], v153 offset:6144
	ds_read_b128 v[216:219], v153 offset:7168
	s_waitcnt vmcnt(8)
	s_waitcnt lgkmcnt(0)
	s_barrier
	s_waitcnt lgkmcnt(0)
	v_mfma_f32_16x16x32_bf16 v[124:127], v[144:147], v[184:187], v[124:127]
	v_mfma_f32_16x16x32_bf16 v[120:123], v[160:163], v[184:187], v[120:123]
	v_mfma_f32_16x16x32_bf16 v[108:111], v[144:147], v[192:195], v[108:111]
	v_mfma_f32_16x16x32_bf16 v[104:107], v[160:163], v[192:195], v[104:107]
	v_mfma_f32_16x16x32_bf16 v[92:95], v[144:147], v[200:203], v[92:95]
	v_mfma_f32_16x16x32_bf16 v[88:91], v[160:163], v[200:203], v[88:91]
	v_mfma_f32_16x16x32_bf16 v[76:79], v[144:147], v[212:215], v[76:79]
	v_mfma_f32_16x16x32_bf16 v[72:75], v[160:163], v[212:215], v[72:75]
	v_mfma_f32_16x16x32_bf16 v[124:127], v[156:159], v[188:191], v[124:127]
	v_mfma_f32_16x16x32_bf16 v[120:123], v[164:167], v[188:191], v[120:123]
	v_mfma_f32_16x16x32_bf16 v[108:111], v[156:159], v[196:199], v[108:111]
	v_mfma_f32_16x16x32_bf16 v[104:107], v[164:167], v[196:199], v[104:107]
	v_mfma_f32_16x16x32_bf16 v[92:95], v[156:159], v[208:211], v[92:95]
	v_mfma_f32_16x16x32_bf16 v[88:91], v[164:167], v[208:211], v[88:91]
	v_mfma_f32_16x16x32_bf16 v[76:79], v[156:159], v[216:219], v[76:79]
	v_mfma_f32_16x16x32_bf16 v[72:75], v[164:167], v[216:219], v[72:75]
	v_mfma_f32_16x16x32_bf16 v[116:119], v[168:171], v[184:187], v[116:119]
	v_mfma_f32_16x16x32_bf16 v[112:115], v[176:179], v[184:187], v[112:115]
	v_mfma_f32_16x16x32_bf16 v[100:103], v[168:171], v[192:195], v[100:103]
	v_mfma_f32_16x16x32_bf16 v[96:99], v[176:179], v[192:195], v[96:99]
	v_mfma_f32_16x16x32_bf16 v[84:87], v[168:171], v[200:203], v[84:87]
	v_mfma_f32_16x16x32_bf16 v[80:83], v[176:179], v[200:203], v[80:83]
	v_mfma_f32_16x16x32_bf16 v[68:71], v[168:171], v[212:215], v[68:71]
	v_mfma_f32_16x16x32_bf16 v[64:67], v[176:179], v[212:215], v[64:67]
	v_mfma_f32_16x16x32_bf16 v[116:119], v[172:175], v[188:191], v[116:119]
	v_mfma_f32_16x16x32_bf16 v[112:115], v[180:183], v[188:191], v[112:115]
	v_mfma_f32_16x16x32_bf16 v[100:103], v[172:175], v[196:199], v[100:103]
	v_mfma_f32_16x16x32_bf16 v[96:99], v[180:183], v[196:199], v[96:99]
	v_mfma_f32_16x16x32_bf16 v[84:87], v[172:175], v[208:211], v[84:87]
	v_mfma_f32_16x16x32_bf16 v[80:83], v[180:183], v[208:211], v[80:83]
	v_mfma_f32_16x16x32_bf16 v[68:71], v[172:175], v[216:219], v[68:71]
	v_mfma_f32_16x16x32_bf16 v[64:67], v[180:183], v[216:219], v[64:67]
	s_barrier
	s_add_i32 s54, s46, s38
	s_mov_b32 m0, s54
	s_nop 0
	global_load_lds_dwordx4 v130, s[28:29]
	s_add_i32 m0, s54, 0x2000
	s_add_u32 s54, s28, 0x40000
	s_mov_b64 s[98:99], s[28:29]
	s_addc_u32 s55, s29, 0
	s_add_i32 s56, s47, s38
	global_load_lds_dwordx4 v134, s[28:29]
	s_mov_b32 m0, s56
	s_mov_b64 s[100:101], s[30:31]
	global_load_lds_dwordx4 v130, s[54:55]
	s_add_i32 m0, s56, 0x2000
	s_nop 0
	global_load_lds_dwordx4 v134, s[54:55]
	s_mov_b32 m0, s39
	s_nop 0
	global_load_lds_dwordx4 v128, s[30:31]
	s_mov_b32 m0, s40
	s_nop 0
	global_load_lds_dwordx4 v132, s[30:31]
	ds_read_b128 v[184:187], v153 offset:16384
	ds_read_b128 v[188:191], v153 offset:17408
	ds_read_b128 v[192:195], v153 offset:18432
	ds_read_b128 v[196:199], v153 offset:19456
	ds_read_b128 v[200:203], v153 offset:20480
	ds_read_b128 v[208:211], v153 offset:21504
	ds_read_b128 v[212:215], v153 offset:22528
	ds_read_b128 v[216:219], v153 offset:23552
	s_waitcnt vmcnt(8)
	s_waitcnt lgkmcnt(0)
	s_barrier
	s_waitcnt lgkmcnt(0)
	v_mfma_f32_16x16x32_bf16 v[60:63], v[144:147], v[184:187], v[60:63]
	v_mfma_f32_16x16x32_bf16 v[56:59], v[160:163], v[184:187], v[56:59]
	v_mfma_f32_16x16x32_bf16 v[44:47], v[144:147], v[192:195], v[44:47]
	v_mfma_f32_16x16x32_bf16 v[40:43], v[160:163], v[192:195], v[40:43]
	v_mfma_f32_16x16x32_bf16 v[28:31], v[144:147], v[200:203], v[28:31]
	v_mfma_f32_16x16x32_bf16 v[24:27], v[160:163], v[200:203], v[24:27]
	v_mfma_f32_16x16x32_bf16 v[12:15], v[144:147], v[212:215], v[12:15]
	v_mfma_f32_16x16x32_bf16 v[8:11], v[160:163], v[212:215], v[8:11]
	v_mfma_f32_16x16x32_bf16 v[60:63], v[156:159], v[188:191], v[60:63]
	v_mfma_f32_16x16x32_bf16 v[56:59], v[164:167], v[188:191], v[56:59]
	v_mfma_f32_16x16x32_bf16 v[44:47], v[156:159], v[196:199], v[44:47]
	v_mfma_f32_16x16x32_bf16 v[40:43], v[164:167], v[196:199], v[40:43]
	v_mfma_f32_16x16x32_bf16 v[28:31], v[156:159], v[208:211], v[28:31]
	v_mfma_f32_16x16x32_bf16 v[24:27], v[164:167], v[208:211], v[24:27]
	v_mfma_f32_16x16x32_bf16 v[12:15], v[156:159], v[216:219], v[12:15]
	v_mfma_f32_16x16x32_bf16 v[8:11], v[164:167], v[216:219], v[8:11]
	v_mfma_f32_16x16x32_bf16 v[52:55], v[168:171], v[184:187], v[52:55]
	v_mfma_f32_16x16x32_bf16 v[48:51], v[176:179], v[184:187], v[48:51]
	v_mfma_f32_16x16x32_bf16 v[36:39], v[168:171], v[192:195], v[36:39]
	v_mfma_f32_16x16x32_bf16 v[32:35], v[176:179], v[192:195], v[32:35]
	v_mfma_f32_16x16x32_bf16 v[20:23], v[168:171], v[200:203], v[20:23]
	v_mfma_f32_16x16x32_bf16 v[16:19], v[176:179], v[200:203], v[16:19]
	v_mfma_f32_16x16x32_bf16 v[4:7], v[168:171], v[212:215], v[4:7]
	v_mfma_f32_16x16x32_bf16 v[0:3], v[176:179], v[212:215], v[0:3]
	v_mfma_f32_16x16x32_bf16 v[52:55], v[172:175], v[188:191], v[52:55]
	v_mfma_f32_16x16x32_bf16 v[48:51], v[180:183], v[188:191], v[48:51]
	v_mfma_f32_16x16x32_bf16 v[36:39], v[172:175], v[196:199], v[36:39]
	v_mfma_f32_16x16x32_bf16 v[32:35], v[180:183], v[196:199], v[32:35]
	v_mfma_f32_16x16x32_bf16 v[20:23], v[172:175], v[208:211], v[20:23]
	v_mfma_f32_16x16x32_bf16 v[16:19], v[180:183], v[208:211], v[16:19]
	v_mfma_f32_16x16x32_bf16 v[4:7], v[172:175], v[216:219], v[4:7]
	v_mfma_f32_16x16x32_bf16 v[0:3], v[180:183], v[216:219], v[0:3]
	s_barrier
	s_add_i32 s54, 0, 0x18000
	s_add_i32 s55, 0, 0x1c000
	s_add_u32 s30, s30, 0x40000
	s_addc_u32 s31, s31, 0
	s_mov_b32 m0, s41
	s_nop 0
	global_load_lds_dwordx4 v128, s[30:31]
	s_mov_b32 m0, s42
	s_nop 0
	global_load_lds_dwordx4 v132, s[30:31]
	v_add_u32_e32 v155, s54, v149
	ds_read_b128 v[144:147], v155
	ds_read_b128 v[156:159], v155 offset:1024
	ds_read_b128 v[160:163], v155 offset:2048
	ds_read_b128 v[164:167], v155 offset:3072
	v_add_u32_e32 v155, s55, v149
	ds_read_b128 v[168:171], v155
	ds_read_b128 v[172:175], v155 offset:1024
	ds_read_b128 v[176:179], v155 offset:2048
	ds_read_b128 v[180:183], v155 offset:3072
	ds_read_b128 v[184:187], v153 offset:32768
	ds_read_b128 v[188:191], v153 offset:33792
	ds_read_b128 v[192:195], v153 offset:34816
	ds_read_b128 v[196:199], v153 offset:35840
	ds_read_b128 v[200:203], v153 offset:36864
	ds_read_b128 v[208:211], v153 offset:37888
	ds_read_b128 v[212:215], v153 offset:38912
	ds_read_b128 v[216:219], v153 offset:39936
	s_waitcnt vmcnt(8)
	s_waitcnt lgkmcnt(0)
	s_barrier
	s_waitcnt lgkmcnt(0)
	v_mfma_f32_16x16x32_bf16 v[124:127], v[144:147], v[184:187], v[124:127]
	v_mfma_f32_16x16x32_bf16 v[120:123], v[160:163], v[184:187], v[120:123]
	v_mfma_f32_16x16x32_bf16 v[108:111], v[144:147], v[192:195], v[108:111]
	v_mfma_f32_16x16x32_bf16 v[104:107], v[160:163], v[192:195], v[104:107]
	v_mfma_f32_16x16x32_bf16 v[92:95], v[144:147], v[200:203], v[92:95]
	v_mfma_f32_16x16x32_bf16 v[88:91], v[160:163], v[200:203], v[88:91]
	v_mfma_f32_16x16x32_bf16 v[76:79], v[144:147], v[212:215], v[76:79]
	v_mfma_f32_16x16x32_bf16 v[72:75], v[160:163], v[212:215], v[72:75]
	v_mfma_f32_16x16x32_bf16 v[124:127], v[156:159], v[188:191], v[124:127]
	v_mfma_f32_16x16x32_bf16 v[120:123], v[164:167], v[188:191], v[120:123]
	v_mfma_f32_16x16x32_bf16 v[108:111], v[156:159], v[196:199], v[108:111]
	v_mfma_f32_16x16x32_bf16 v[104:107], v[164:167], v[196:199], v[104:107]
	v_mfma_f32_16x16x32_bf16 v[92:95], v[156:159], v[208:211], v[92:95]
	v_mfma_f32_16x16x32_bf16 v[88:91], v[164:167], v[208:211], v[88:91]
	v_mfma_f32_16x16x32_bf16 v[76:79], v[156:159], v[216:219], v[76:79]
	v_mfma_f32_16x16x32_bf16 v[72:75], v[164:167], v[216:219], v[72:75]
	v_mfma_f32_16x16x32_bf16 v[116:119], v[168:171], v[184:187], v[116:119]
	v_mfma_f32_16x16x32_bf16 v[112:115], v[176:179], v[184:187], v[112:115]
	v_mfma_f32_16x16x32_bf16 v[100:103], v[168:171], v[192:195], v[100:103]
	v_mfma_f32_16x16x32_bf16 v[96:99], v[176:179], v[192:195], v[96:99]
	v_mfma_f32_16x16x32_bf16 v[84:87], v[168:171], v[200:203], v[84:87]
	v_mfma_f32_16x16x32_bf16 v[80:83], v[176:179], v[200:203], v[80:83]
	v_mfma_f32_16x16x32_bf16 v[68:71], v[168:171], v[212:215], v[68:71]
	v_mfma_f32_16x16x32_bf16 v[64:67], v[176:179], v[212:215], v[64:67]
	v_mfma_f32_16x16x32_bf16 v[116:119], v[172:175], v[188:191], v[116:119]
	v_mfma_f32_16x16x32_bf16 v[112:115], v[180:183], v[188:191], v[112:115]
	v_mfma_f32_16x16x32_bf16 v[100:103], v[172:175], v[196:199], v[100:103]
	v_mfma_f32_16x16x32_bf16 v[96:99], v[180:183], v[196:199], v[96:99]
	v_mfma_f32_16x16x32_bf16 v[84:87], v[172:175], v[208:211], v[84:87]
	v_mfma_f32_16x16x32_bf16 v[80:83], v[180:183], v[208:211], v[80:83]
	v_mfma_f32_16x16x32_bf16 v[68:71], v[172:175], v[216:219], v[68:71]
	v_mfma_f32_16x16x32_bf16 v[64:67], v[180:183], v[216:219], v[64:67]
	s_barrier
	s_add_i32 s30, s54, s38
	s_mov_b32 m0, s30
	s_nop 0
	global_load_lds_dwordx4 v205, s[28:29]
	s_add_i32 m0, s30, 0x2000
	s_add_u32 s28, s28, 0x40080
	s_addc_u32 s29, s29, 0
	s_add_i32 s30, s55, s38
	global_load_lds_dwordx4 v221, s[98:99]
	s_mov_b32 m0, s30
	s_nop 0
	global_load_lds_dwordx4 v130, s[28:29]
	s_add_i32 m0, s30, 0x2000
	s_nop 0
	global_load_lds_dwordx4 v134, s[28:29]
	s_mov_b32 m0, s44
	s_nop 0
	global_load_lds_dwordx4 v204, s[100:101]
	s_mov_b32 m0, s45
	s_nop 0
	global_load_lds_dwordx4 v220, s[100:101]
	ds_read_b128 v[184:187], v153 offset:49152
	ds_read_b128 v[188:191], v153 offset:50176
	ds_read_b128 v[192:195], v153 offset:51200
	ds_read_b128 v[196:199], v153 offset:52224
	ds_read_b128 v[200:203], v153 offset:53248
	ds_read_b128 v[208:211], v153 offset:54272
	ds_read_b128 v[212:215], v153 offset:55296
	ds_read_b128 v[216:219], v153 offset:56320
	s_waitcnt vmcnt(8)
	s_waitcnt lgkmcnt(0)
	s_barrier
	s_waitcnt lgkmcnt(0)
	v_mfma_f32_16x16x32_bf16 v[60:63], v[144:147], v[184:187], v[60:63]
	v_mfma_f32_16x16x32_bf16 v[56:59], v[160:163], v[184:187], v[56:59]
	v_mfma_f32_16x16x32_bf16 v[44:47], v[144:147], v[192:195], v[44:47]
	v_mfma_f32_16x16x32_bf16 v[40:43], v[160:163], v[192:195], v[40:43]
	v_mfma_f32_16x16x32_bf16 v[28:31], v[144:147], v[200:203], v[28:31]
	v_mfma_f32_16x16x32_bf16 v[24:27], v[160:163], v[200:203], v[24:27]
	v_mfma_f32_16x16x32_bf16 v[12:15], v[144:147], v[212:215], v[12:15]
	v_mfma_f32_16x16x32_bf16 v[8:11], v[160:163], v[212:215], v[8:11]
	v_mfma_f32_16x16x32_bf16 v[60:63], v[156:159], v[188:191], v[60:63]
	v_mfma_f32_16x16x32_bf16 v[56:59], v[164:167], v[188:191], v[56:59]
	v_mfma_f32_16x16x32_bf16 v[44:47], v[156:159], v[196:199], v[44:47]
	v_mfma_f32_16x16x32_bf16 v[40:43], v[164:167], v[196:199], v[40:43]
	v_mfma_f32_16x16x32_bf16 v[28:31], v[156:159], v[208:211], v[28:31]
	v_mfma_f32_16x16x32_bf16 v[24:27], v[164:167], v[208:211], v[24:27]
	v_mfma_f32_16x16x32_bf16 v[12:15], v[156:159], v[216:219], v[12:15]
	v_mfma_f32_16x16x32_bf16 v[8:11], v[164:167], v[216:219], v[8:11]
	v_mfma_f32_16x16x32_bf16 v[52:55], v[168:171], v[184:187], v[52:55]
	v_mfma_f32_16x16x32_bf16 v[48:51], v[176:179], v[184:187], v[48:51]
	v_mfma_f32_16x16x32_bf16 v[36:39], v[168:171], v[192:195], v[36:39]
	v_mfma_f32_16x16x32_bf16 v[32:35], v[176:179], v[192:195], v[32:35]
	v_mfma_f32_16x16x32_bf16 v[20:23], v[168:171], v[200:203], v[20:23]
	v_mfma_f32_16x16x32_bf16 v[16:19], v[176:179], v[200:203], v[16:19]
	v_mfma_f32_16x16x32_bf16 v[4:7], v[168:171], v[212:215], v[4:7]
	v_mfma_f32_16x16x32_bf16 v[0:3], v[176:179], v[212:215], v[0:3]
	v_mfma_f32_16x16x32_bf16 v[52:55], v[172:175], v[188:191], v[52:55]
	v_mfma_f32_16x16x32_bf16 v[48:51], v[180:183], v[188:191], v[48:51]
	v_mfma_f32_16x16x32_bf16 v[36:39], v[172:175], v[196:199], v[36:39]
	v_mfma_f32_16x16x32_bf16 v[32:35], v[180:183], v[196:199], v[32:35]
	v_mfma_f32_16x16x32_bf16 v[20:23], v[172:175], v[208:211], v[20:23]
	v_mfma_f32_16x16x32_bf16 v[16:19], v[180:183], v[208:211], v[16:19]
	v_mfma_f32_16x16x32_bf16 v[4:7], v[172:175], v[216:219], v[4:7]
	v_mfma_f32_16x16x32_bf16 v[0:3], v[180:183], v[216:219], v[0:3]
	s_barrier
	s_add_i32 s53, s53, 2
	s_add_u32 s51, s51, 0x100
	s_addc_u32 s52, s52, 0
	s_add_u32 s26, s26, 0x100
	s_addc_u32 s27, s27, 0
	s_cmp_gt_u32 s53, 13
	s_cbranch_scc0 .LBB0_699
	s_setprio 0
	s_and_b64 vcc, exec, s[16:17]
	s_cbranch_vccz .LBB0_702
	s_barrier

.LBB0_778:
	s_add_u32 s30, s28, 0x100
	s_addc_u32 s31, s29, 0
	s_cmp_eq_u32 s58, 60
	s_cselect_b32 s37, s21, s31
	s_cselect_b32 s36, s27, s30
	s_cselect_b32 s35, s19, s57
	s_cselect_b32 s34, s55, s56
	s_add_i32 m0, s44, 0xc000
	s_nop 0
	global_load_lds_dwordx4 v134, s[28:29]
	s_add_i32 m0, s44, 0xe000
	s_nop 0
	global_load_lds_dwordx4 v132, s[28:29]
	ds_read_b128 v[140:143], v147
	ds_read_b128 v[150:153], v147 offset:1024
	ds_read_b128 v[154:157], v147 offset:2048
	ds_read_b128 v[158:161], v147 offset:3072
	ds_read_b128 v[162:165], v148
	ds_read_b128 v[166:169], v148 offset:1024
	ds_read_b128 v[170:173], v148 offset:2048
	ds_read_b128 v[174:177], v148 offset:3072
	ds_read_b128 v[178:181], v149
	ds_read_b128 v[182:185], v149 offset:1024
	ds_read_b128 v[186:189], v149 offset:2048
	ds_read_b128 v[190:193], v149 offset:3072
	ds_read_b128 v[194:197], v149 offset:4096
	ds_read_b128 v[198:201], v149 offset:5120
	ds_read_b128 v[202:205], v149 offset:6144
	ds_read_b128 v[208:211], v149 offset:7168
	s_waitcnt vmcnt(8)
	s_waitcnt lgkmcnt(0)
	s_barrier
	s_waitcnt lgkmcnt(0)
	v_mfma_f32_16x16x32_bf16 v[124:127], v[140:143], v[178:181], v[124:127]
	v_mfma_f32_16x16x32_bf16 v[120:123], v[154:157], v[178:181], v[120:123]
	v_mfma_f32_16x16x32_bf16 v[108:111], v[140:143], v[186:189], v[108:111]
	v_mfma_f32_16x16x32_bf16 v[104:107], v[154:157], v[186:189], v[104:107]
	v_mfma_f32_16x16x32_bf16 v[92:95], v[140:143], v[194:197], v[92:95]
	v_mfma_f32_16x16x32_bf16 v[88:91], v[154:157], v[194:197], v[88:91]
	v_mfma_f32_16x16x32_bf16 v[76:79], v[140:143], v[202:205], v[76:79]
	v_mfma_f32_16x16x32_bf16 v[72:75], v[154:157], v[202:205], v[72:75]
	v_mfma_f32_16x16x32_bf16 v[124:127], v[150:153], v[182:185], v[124:127]
	v_mfma_f32_16x16x32_bf16 v[120:123], v[158:161], v[182:185], v[120:123]
	v_mfma_f32_16x16x32_bf16 v[108:111], v[150:153], v[190:193], v[108:111]
	v_mfma_f32_16x16x32_bf16 v[104:107], v[158:161], v[190:193], v[104:107]
	v_mfma_f32_16x16x32_bf16 v[92:95], v[150:153], v[198:201], v[92:95]
	v_mfma_f32_16x16x32_bf16 v[88:91], v[158:161], v[198:201], v[88:91]
	v_mfma_f32_16x16x32_bf16 v[76:79], v[150:153], v[208:211], v[76:79]
	v_mfma_f32_16x16x32_bf16 v[72:75], v[158:161], v[208:211], v[72:75]
	v_mfma_f32_16x16x32_bf16 v[116:119], v[162:165], v[178:181], v[116:119]
	v_mfma_f32_16x16x32_bf16 v[112:115], v[170:173], v[178:181], v[112:115]
	v_mfma_f32_16x16x32_bf16 v[100:103], v[162:165], v[186:189], v[100:103]
	v_mfma_f32_16x16x32_bf16 v[96:99], v[170:173], v[186:189], v[96:99]
	v_mfma_f32_16x16x32_bf16 v[84:87], v[162:165], v[194:197], v[84:87]
	v_mfma_f32_16x16x32_bf16 v[80:83], v[170:173], v[194:197], v[80:83]
	v_mfma_f32_16x16x32_bf16 v[68:71], v[162:165], v[202:205], v[68:71]
	v_mfma_f32_16x16x32_bf16 v[64:67], v[170:173], v[202:205], v[64:67]
	v_mfma_f32_16x16x32_bf16 v[116:119], v[166:169], v[182:185], v[116:119]
	v_mfma_f32_16x16x32_bf16 v[112:115], v[174:177], v[182:185], v[112:115]
	v_mfma_f32_16x16x32_bf16 v[100:103], v[166:169], v[190:193], v[100:103]
	v_mfma_f32_16x16x32_bf16 v[96:99], v[174:177], v[190:193], v[96:99]
	v_mfma_f32_16x16x32_bf16 v[84:87], v[166:169], v[198:201], v[84:87]
	v_mfma_f32_16x16x32_bf16 v[80:83], v[174:177], v[198:201], v[80:83]
	v_mfma_f32_16x16x32_bf16 v[68:71], v[166:169], v[208:211], v[68:71]
	v_mfma_f32_16x16x32_bf16 v[64:67], v[174:177], v[208:211], v[64:67]
	s_barrier
	s_add_i32 s28, s52, s43
	s_mov_b32 m0, s28
	s_nop 0
	global_load_lds_dwordx4 v128, s[34:35]
	s_add_i32 m0, s28, 0x2000
	s_add_u32 s28, s34, 0x100000
	s_mov_b64 s[98:99], s[34:35]
	s_addc_u32 s29, s35, 0
	s_add_i32 s59, s53, s43
	global_load_lds_dwordx4 v130, s[34:35]
	s_mov_b32 m0, s59
	s_nop 0
	global_load_lds_dwordx4 v128, s[28:29]
	s_add_i32 m0, s59, 0x2000
	s_nop 0
	global_load_lds_dwordx4 v130, s[28:29]
	s_mov_b32 m0, s44
	s_nop 0
	global_load_lds_dwordx4 v128, s[36:37]
	s_mov_b32 m0, s45
	s_nop 0
	global_load_lds_dwordx4 v130, s[36:37]
	ds_read_b128 v[178:181], v149 offset:16384
	ds_read_b128 v[182:185], v149 offset:17408
	ds_read_b128 v[186:189], v149 offset:18432
	ds_read_b128 v[190:193], v149 offset:19456
	ds_read_b128 v[194:197], v149 offset:20480
	ds_read_b128 v[198:201], v149 offset:21504
	ds_read_b128 v[202:205], v149 offset:22528
	ds_read_b128 v[208:211], v149 offset:23552
	s_waitcnt vmcnt(8)
	s_waitcnt lgkmcnt(0)
	s_barrier
	s_waitcnt lgkmcnt(0)
	v_mfma_f32_16x16x32_bf16 v[60:63], v[140:143], v[178:181], v[60:63]
	v_mfma_f32_16x16x32_bf16 v[56:59], v[154:157], v[178:181], v[56:59]
	v_mfma_f32_16x16x32_bf16 v[44:47], v[140:143], v[186:189], v[44:47]
	v_mfma_f32_16x16x32_bf16 v[40:43], v[154:157], v[186:189], v[40:43]
	v_mfma_f32_16x16x32_bf16 v[28:31], v[140:143], v[194:197], v[28:31]
	v_mfma_f32_16x16x32_bf16 v[24:27], v[154:157], v[194:197], v[24:27]
	v_mfma_f32_16x16x32_bf16 v[12:15], v[140:143], v[202:205], v[12:15]
	v_mfma_f32_16x16x32_bf16 v[8:11], v[154:157], v[202:205], v[8:11]
	v_mfma_f32_16x16x32_bf16 v[60:63], v[150:153], v[182:185], v[60:63]
	v_mfma_f32_16x16x32_bf16 v[56:59], v[158:161], v[182:185], v[56:59]
	v_mfma_f32_16x16x32_bf16 v[44:47], v[150:153], v[190:193], v[44:47]
	v_mfma_f32_16x16x32_bf16 v[40:43], v[158:161], v[190:193], v[40:43]
	v_mfma_f32_16x16x32_bf16 v[28:31], v[150:153], v[198:201], v[28:31]
	v_mfma_f32_16x16x32_bf16 v[24:27], v[158:161], v[198:201], v[24:27]
	v_mfma_f32_16x16x32_bf16 v[12:15], v[150:153], v[208:211], v[12:15]
	v_mfma_f32_16x16x32_bf16 v[8:11], v[158:161], v[208:211], v[8:11]
	v_mfma_f32_16x16x32_bf16 v[52:55], v[162:165], v[178:181], v[52:55]
	v_mfma_f32_16x16x32_bf16 v[48:51], v[170:173], v[178:181], v[48:51]
	v_mfma_f32_16x16x32_bf16 v[36:39], v[162:165], v[186:189], v[36:39]
	v_mfma_f32_16x16x32_bf16 v[32:35], v[170:173], v[186:189], v[32:35]
	v_mfma_f32_16x16x32_bf16 v[20:23], v[162:165], v[194:197], v[20:23]
	v_mfma_f32_16x16x32_bf16 v[16:19], v[170:173], v[194:197], v[16:19]
	v_mfma_f32_16x16x32_bf16 v[4:7], v[162:165], v[202:205], v[4:7]
	v_mfma_f32_16x16x32_bf16 v[0:3], v[170:173], v[202:205], v[0:3]
	v_mfma_f32_16x16x32_bf16 v[52:55], v[166:169], v[182:185], v[52:55]
	v_mfma_f32_16x16x32_bf16 v[48:51], v[174:177], v[182:185], v[48:51]
	v_mfma_f32_16x16x32_bf16 v[36:39], v[166:169], v[190:193], v[36:39]
	v_mfma_f32_16x16x32_bf16 v[32:35], v[174:177], v[190:193], v[32:35]
	v_mfma_f32_16x16x32_bf16 v[20:23], v[166:169], v[198:201], v[20:23]
	v_mfma_f32_16x16x32_bf16 v[16:19], v[174:177], v[198:201], v[16:19]
	v_mfma_f32_16x16x32_bf16 v[4:7], v[166:169], v[208:211], v[4:7]
	v_mfma_f32_16x16x32_bf16 v[0:3], v[174:177], v[208:211], v[0:3]
	s_barrier
	s_add_i32 s59, 0, 0x18000
	s_add_i32 s60, 0, 0x1c000
	s_add_u32 s28, s36, 0x100000
	s_addc_u32 s29, s37, 0
	s_mov_b32 m0, s46
	s_nop 0
	global_load_lds_dwordx4 v128, s[28:29]
	s_mov_b32 m0, s47
	s_nop 0
	global_load_lds_dwordx4 v130, s[28:29]
	v_add_u32_e32 v158, s59, v145
	v_add_u32_e32 v174, s60, v145
	ds_read_b128 v[140:143], v158
	ds_read_b128 v[150:153], v158 offset:1024
	ds_read_b128 v[154:157], v158 offset:2048
	ds_read_b128 v[158:161], v158 offset:3072
	ds_read_b128 v[162:165], v174
	ds_read_b128 v[166:169], v174 offset:1024
	ds_read_b128 v[170:173], v174 offset:2048
	ds_read_b128 v[174:177], v174 offset:3072
	ds_read_b128 v[178:181], v149 offset:32768
	ds_read_b128 v[182:185], v149 offset:33792
	ds_read_b128 v[186:189], v149 offset:34816
	ds_read_b128 v[190:193], v149 offset:35840
	ds_read_b128 v[194:197], v149 offset:36864
	ds_read_b128 v[198:201], v149 offset:37888
	ds_read_b128 v[202:205], v149 offset:38912
	ds_read_b128 v[208:211], v149 offset:39936
	s_waitcnt vmcnt(8)
	s_waitcnt lgkmcnt(0)
	s_barrier
	s_waitcnt lgkmcnt(0)
	v_mfma_f32_16x16x32_bf16 v[124:127], v[140:143], v[178:181], v[124:127]
	v_mfma_f32_16x16x32_bf16 v[120:123], v[154:157], v[178:181], v[120:123]
	v_mfma_f32_16x16x32_bf16 v[108:111], v[140:143], v[186:189], v[108:111]
	v_mfma_f32_16x16x32_bf16 v[104:107], v[154:157], v[186:189], v[104:107]
	v_mfma_f32_16x16x32_bf16 v[92:95], v[140:143], v[194:197], v[92:95]
	v_mfma_f32_16x16x32_bf16 v[88:91], v[154:157], v[194:197], v[88:91]
	v_mfma_f32_16x16x32_bf16 v[76:79], v[140:143], v[202:205], v[76:79]
	v_mfma_f32_16x16x32_bf16 v[72:75], v[154:157], v[202:205], v[72:75]
	v_mfma_f32_16x16x32_bf16 v[124:127], v[150:153], v[182:185], v[124:127]
	v_mfma_f32_16x16x32_bf16 v[120:123], v[158:161], v[182:185], v[120:123]
	v_mfma_f32_16x16x32_bf16 v[108:111], v[150:153], v[190:193], v[108:111]
	v_mfma_f32_16x16x32_bf16 v[104:107], v[158:161], v[190:193], v[104:107]
	v_mfma_f32_16x16x32_bf16 v[92:95], v[150:153], v[198:201], v[92:95]
	v_mfma_f32_16x16x32_bf16 v[88:91], v[158:161], v[198:201], v[88:91]
	v_mfma_f32_16x16x32_bf16 v[76:79], v[150:153], v[208:211], v[76:79]
	v_mfma_f32_16x16x32_bf16 v[72:75], v[158:161], v[208:211], v[72:75]
	v_mfma_f32_16x16x32_bf16 v[116:119], v[162:165], v[178:181], v[116:119]
	v_mfma_f32_16x16x32_bf16 v[112:115], v[170:173], v[178:181], v[112:115]
	v_mfma_f32_16x16x32_bf16 v[100:103], v[162:165], v[186:189], v[100:103]
	v_mfma_f32_16x16x32_bf16 v[96:99], v[170:173], v[186:189], v[96:99]
	v_mfma_f32_16x16x32_bf16 v[84:87], v[162:165], v[194:197], v[84:87]
	v_mfma_f32_16x16x32_bf16 v[80:83], v[170:173], v[194:197], v[80:83]
	v_mfma_f32_16x16x32_bf16 v[68:71], v[162:165], v[202:205], v[68:71]
	v_mfma_f32_16x16x32_bf16 v[64:67], v[170:173], v[202:205], v[64:67]
	v_mfma_f32_16x16x32_bf16 v[116:119], v[166:169], v[182:185], v[116:119]
	v_mfma_f32_16x16x32_bf16 v[112:115], v[174:177], v[182:185], v[112:115]
	v_mfma_f32_16x16x32_bf16 v[100:103], v[166:169], v[190:193], v[100:103]
	v_mfma_f32_16x16x32_bf16 v[96:99], v[174:177], v[190:193], v[96:99]
	v_mfma_f32_16x16x32_bf16 v[84:87], v[166:169], v[198:201], v[84:87]
	v_mfma_f32_16x16x32_bf16 v[80:83], v[174:177], v[198:201], v[80:83]
	v_mfma_f32_16x16x32_bf16 v[68:71], v[166:169], v[208:211], v[68:71]
	v_mfma_f32_16x16x32_bf16 v[64:67], v[174:177], v[208:211], v[64:67]
	s_barrier
	s_add_i32 s28, s59, s43
	s_mov_b32 m0, s28
	s_nop 0
	global_load_lds_dwordx4 v212, s[34:35]
	s_add_i32 m0, s28, 0x2000
	s_add_u32 s28, s34, 0x100080
	s_addc_u32 s29, s35, 0
	s_add_i32 s34, s60, s43
	global_load_lds_dwordx4 v213, s[98:99]
	s_mov_b32 m0, s34
	s_nop 0
	global_load_lds_dwordx4 v128, s[28:29]
	s_add_i32 m0, s34, 0x2000
	s_nop 0
	global_load_lds_dwordx4 v130, s[28:29]
	s_mov_b32 m0, s49
	s_nop 0
	global_load_lds_dwordx4 v212, s[36:37]
	s_mov_b32 m0, s50
	s_nop 0
	global_load_lds_dwordx4 v213, s[36:37]
	ds_read_b128 v[178:181], v149 offset:49152
	ds_read_b128 v[182:185], v149 offset:50176
	ds_read_b128 v[186:189], v149 offset:51200
	ds_read_b128 v[190:193], v149 offset:52224
	ds_read_b128 v[194:197], v149 offset:53248
	ds_read_b128 v[198:201], v149 offset:54272
	ds_read_b128 v[202:205], v149 offset:55296
	ds_read_b128 v[208:211], v149 offset:56320
	s_waitcnt vmcnt(8)
	s_waitcnt lgkmcnt(0)
	s_barrier
	s_waitcnt lgkmcnt(0)
	v_mfma_f32_16x16x32_bf16 v[60:63], v[140:143], v[178:181], v[60:63]
	v_mfma_f32_16x16x32_bf16 v[56:59], v[154:157], v[178:181], v[56:59]
	v_mfma_f32_16x16x32_bf16 v[44:47], v[140:143], v[186:189], v[44:47]
	v_mfma_f32_16x16x32_bf16 v[40:43], v[154:157], v[186:189], v[40:43]
	v_mfma_f32_16x16x32_bf16 v[28:31], v[140:143], v[194:197], v[28:31]
	v_mfma_f32_16x16x32_bf16 v[24:27], v[154:157], v[194:197], v[24:27]
	v_mfma_f32_16x16x32_bf16 v[12:15], v[140:143], v[202:205], v[12:15]
	v_mfma_f32_16x16x32_bf16 v[8:11], v[154:157], v[202:205], v[8:11]
	v_mfma_f32_16x16x32_bf16 v[60:63], v[150:153], v[182:185], v[60:63]
	v_mfma_f32_16x16x32_bf16 v[56:59], v[158:161], v[182:185], v[56:59]
	v_mfma_f32_16x16x32_bf16 v[44:47], v[150:153], v[190:193], v[44:47]
	v_mfma_f32_16x16x32_bf16 v[40:43], v[158:161], v[190:193], v[40:43]
	v_mfma_f32_16x16x32_bf16 v[28:31], v[150:153], v[198:201], v[28:31]
	v_mfma_f32_16x16x32_bf16 v[24:27], v[158:161], v[198:201], v[24:27]
	v_mfma_f32_16x16x32_bf16 v[12:15], v[150:153], v[208:211], v[12:15]
	v_mfma_f32_16x16x32_bf16 v[8:11], v[158:161], v[208:211], v[8:11]
	v_mfma_f32_16x16x32_bf16 v[52:55], v[162:165], v[178:181], v[52:55]
	v_mfma_f32_16x16x32_bf16 v[48:51], v[170:173], v[178:181], v[48:51]
	v_mfma_f32_16x16x32_bf16 v[36:39], v[162:165], v[186:189], v[36:39]
	v_mfma_f32_16x16x32_bf16 v[32:35], v[170:173], v[186:189], v[32:35]
	v_mfma_f32_16x16x32_bf16 v[20:23], v[162:165], v[194:197], v[20:23]
	v_mfma_f32_16x16x32_bf16 v[16:19], v[170:173], v[194:197], v[16:19]
	v_mfma_f32_16x16x32_bf16 v[4:7], v[162:165], v[202:205], v[4:7]
	v_mfma_f32_16x16x32_bf16 v[0:3], v[170:173], v[202:205], v[0:3]
	v_mfma_f32_16x16x32_bf16 v[52:55], v[166:169], v[182:185], v[52:55]
	v_mfma_f32_16x16x32_bf16 v[48:51], v[174:177], v[182:185], v[48:51]
	v_mfma_f32_16x16x32_bf16 v[36:39], v[166:169], v[190:193], v[36:39]
	v_mfma_f32_16x16x32_bf16 v[32:35], v[174:177], v[190:193], v[32:35]
	v_mfma_f32_16x16x32_bf16 v[20:23], v[166:169], v[198:201], v[20:23]
	v_mfma_f32_16x16x32_bf16 v[16:19], v[174:177], v[198:201], v[16:19]
	v_mfma_f32_16x16x32_bf16 v[4:7], v[166:169], v[208:211], v[4:7]
	v_mfma_f32_16x16x32_bf16 v[0:3], v[174:177], v[208:211], v[0:3]
	s_barrier
	s_add_i32 s58, s58, 2
	s_add_u32 s56, s56, 0x100
	s_addc_u32 s57, s57, 0
	s_cmp_gt_u32 s58, 61
	s_mov_b64 s[28:29], s[30:31]
	s_cbranch_scc0 .LBB0_778
	s_setprio 0
	s_and_b64 vcc, exec, s[16:17]
	s_cbranch_vccz .LBB0_781
	s_barrier

.LBB0_895:
	s_add_u32 s38, s36, 0xfffc0080
	s_addc_u32 s39, s37, -1
	s_cmp_eq_u32 s61, 12
	s_cselect_b32 s41, s3, s39
	s_cselect_b32 s40, s29, s38
	s_cselect_b32 s39, s27, s60
	s_cselect_b32 s38, s58, s59
	s_add_i32 m0, s46, 0xc000
	s_nop 0
	global_load_lds_dwordx4 v134, s[36:37]
	s_add_i32 m0, s46, 0xe000
	s_nop 0
	global_load_lds_dwordx4 v132, s[36:37]
	ds_read_b128 v[140:143], v153
	ds_read_b128 v[144:147], v153 offset:1024
	ds_read_b128 v[158:161], v153 offset:2048
	ds_read_b128 v[162:165], v153 offset:3072
	ds_read_b128 v[166:169], v154
	ds_read_b128 v[170:173], v154 offset:1024
	ds_read_b128 v[174:177], v154 offset:2048
	ds_read_b128 v[178:181], v154 offset:3072
	ds_read_b128 v[182:185], v155
	ds_read_b128 v[186:189], v155 offset:1024
	ds_read_b128 v[190:193], v155 offset:2048
	ds_read_b128 v[194:197], v155 offset:3072
	ds_read_b128 v[198:201], v155 offset:4096
	ds_read_b128 v[202:205], v155 offset:5120
	ds_read_b128 v[208:211], v155 offset:6144
	ds_read_b128 v[212:215], v155 offset:7168
	s_waitcnt vmcnt(8)
	s_waitcnt lgkmcnt(0)
	s_barrier
	s_waitcnt lgkmcnt(0)
	v_mfma_f32_16x16x32_bf16 v[124:127], v[140:143], v[182:185], v[124:127]
	v_mfma_f32_16x16x32_bf16 v[120:123], v[158:161], v[182:185], v[120:123]
	v_mfma_f32_16x16x32_bf16 v[108:111], v[140:143], v[190:193], v[108:111]
	v_mfma_f32_16x16x32_bf16 v[104:107], v[158:161], v[190:193], v[104:107]
	v_mfma_f32_16x16x32_bf16 v[92:95], v[140:143], v[198:201], v[92:95]
	v_mfma_f32_16x16x32_bf16 v[88:91], v[158:161], v[198:201], v[88:91]
	v_mfma_f32_16x16x32_bf16 v[76:79], v[140:143], v[208:211], v[76:79]
	v_mfma_f32_16x16x32_bf16 v[72:75], v[158:161], v[208:211], v[72:75]
	v_mfma_f32_16x16x32_bf16 v[124:127], v[144:147], v[186:189], v[124:127]
	v_mfma_f32_16x16x32_bf16 v[120:123], v[162:165], v[186:189], v[120:123]
	v_mfma_f32_16x16x32_bf16 v[108:111], v[144:147], v[194:197], v[108:111]
	v_mfma_f32_16x16x32_bf16 v[104:107], v[162:165], v[194:197], v[104:107]
	v_mfma_f32_16x16x32_bf16 v[92:95], v[144:147], v[202:205], v[92:95]
	v_mfma_f32_16x16x32_bf16 v[88:91], v[162:165], v[202:205], v[88:91]
	v_mfma_f32_16x16x32_bf16 v[76:79], v[144:147], v[212:215], v[76:79]
	v_mfma_f32_16x16x32_bf16 v[72:75], v[162:165], v[212:215], v[72:75]
	v_mfma_f32_16x16x32_bf16 v[116:119], v[166:169], v[182:185], v[116:119]
	v_mfma_f32_16x16x32_bf16 v[112:115], v[174:177], v[182:185], v[112:115]
	v_mfma_f32_16x16x32_bf16 v[100:103], v[166:169], v[190:193], v[100:103]
	v_mfma_f32_16x16x32_bf16 v[96:99], v[174:177], v[190:193], v[96:99]
	v_mfma_f32_16x16x32_bf16 v[84:87], v[166:169], v[198:201], v[84:87]
	v_mfma_f32_16x16x32_bf16 v[80:83], v[174:177], v[198:201], v[80:83]
	v_mfma_f32_16x16x32_bf16 v[68:71], v[166:169], v[208:211], v[68:71]
	v_mfma_f32_16x16x32_bf16 v[64:67], v[174:177], v[208:211], v[64:67]
	v_mfma_f32_16x16x32_bf16 v[116:119], v[170:173], v[186:189], v[116:119]
	v_mfma_f32_16x16x32_bf16 v[112:115], v[178:181], v[186:189], v[112:115]
	v_mfma_f32_16x16x32_bf16 v[100:103], v[170:173], v[194:197], v[100:103]
	v_mfma_f32_16x16x32_bf16 v[96:99], v[178:181], v[194:197], v[96:99]
	v_mfma_f32_16x16x32_bf16 v[84:87], v[170:173], v[202:205], v[84:87]
	v_mfma_f32_16x16x32_bf16 v[80:83], v[178:181], v[202:205], v[80:83]
	v_mfma_f32_16x16x32_bf16 v[68:71], v[170:173], v[212:215], v[68:71]
	v_mfma_f32_16x16x32_bf16 v[64:67], v[178:181], v[212:215], v[64:67]
	s_barrier
	s_add_i32 s62, s54, s45
	s_mov_b32 m0, s62
	s_nop 0
	global_load_lds_dwordx4 v128, s[38:39]
	s_add_i32 m0, s62, 0x2000
	s_add_u32 s62, s38, 0x40000
	s_mov_b64 s[98:99], s[38:39]
	s_addc_u32 s63, s39, 0
	s_add_i32 s64, s55, s45
	global_load_lds_dwordx4 v130, s[38:39]
	s_mov_b32 m0, s64
	s_mov_b64 s[100:101], s[40:41]
	global_load_lds_dwordx4 v128, s[62:63]
	s_add_i32 m0, s64, 0x2000
	s_nop 0
	global_load_lds_dwordx4 v130, s[62:63]
	s_mov_b32 m0, s46
	s_nop 0
	global_load_lds_dwordx4 v128, s[40:41]
	s_mov_b32 m0, s47
	s_nop 0
	global_load_lds_dwordx4 v130, s[40:41]
	ds_read_b128 v[182:185], v155 offset:16384
	ds_read_b128 v[186:189], v155 offset:17408
	ds_read_b128 v[190:193], v155 offset:18432
	ds_read_b128 v[194:197], v155 offset:19456
	ds_read_b128 v[198:201], v155 offset:20480
	ds_read_b128 v[202:205], v155 offset:21504
	ds_read_b128 v[208:211], v155 offset:22528
	ds_read_b128 v[212:215], v155 offset:23552
	s_waitcnt vmcnt(8)
	s_waitcnt lgkmcnt(0)
	s_barrier
	s_waitcnt lgkmcnt(0)
	v_mfma_f32_16x16x32_bf16 v[60:63], v[140:143], v[182:185], v[60:63]
	v_mfma_f32_16x16x32_bf16 v[56:59], v[158:161], v[182:185], v[56:59]
	v_mfma_f32_16x16x32_bf16 v[44:47], v[140:143], v[190:193], v[44:47]
	v_mfma_f32_16x16x32_bf16 v[40:43], v[158:161], v[190:193], v[40:43]
	v_mfma_f32_16x16x32_bf16 v[28:31], v[140:143], v[198:201], v[28:31]
	v_mfma_f32_16x16x32_bf16 v[24:27], v[158:161], v[198:201], v[24:27]
	v_mfma_f32_16x16x32_bf16 v[12:15], v[140:143], v[208:211], v[12:15]
	v_mfma_f32_16x16x32_bf16 v[8:11], v[158:161], v[208:211], v[8:11]
	v_mfma_f32_16x16x32_bf16 v[60:63], v[144:147], v[186:189], v[60:63]
	v_mfma_f32_16x16x32_bf16 v[56:59], v[162:165], v[186:189], v[56:59]
	v_mfma_f32_16x16x32_bf16 v[44:47], v[144:147], v[194:197], v[44:47]
	v_mfma_f32_16x16x32_bf16 v[40:43], v[162:165], v[194:197], v[40:43]
	v_mfma_f32_16x16x32_bf16 v[28:31], v[144:147], v[202:205], v[28:31]
	v_mfma_f32_16x16x32_bf16 v[24:27], v[162:165], v[202:205], v[24:27]
	v_mfma_f32_16x16x32_bf16 v[12:15], v[144:147], v[212:215], v[12:15]
	v_mfma_f32_16x16x32_bf16 v[8:11], v[162:165], v[212:215], v[8:11]
	v_mfma_f32_16x16x32_bf16 v[52:55], v[166:169], v[182:185], v[52:55]
	v_mfma_f32_16x16x32_bf16 v[48:51], v[174:177], v[182:185], v[48:51]
	v_mfma_f32_16x16x32_bf16 v[36:39], v[166:169], v[190:193], v[36:39]
	v_mfma_f32_16x16x32_bf16 v[32:35], v[174:177], v[190:193], v[32:35]
	v_mfma_f32_16x16x32_bf16 v[20:23], v[166:169], v[198:201], v[20:23]
	v_mfma_f32_16x16x32_bf16 v[16:19], v[174:177], v[198:201], v[16:19]
	v_mfma_f32_16x16x32_bf16 v[4:7], v[166:169], v[208:211], v[4:7]
	v_mfma_f32_16x16x32_bf16 v[0:3], v[174:177], v[208:211], v[0:3]
	v_mfma_f32_16x16x32_bf16 v[52:55], v[170:173], v[186:189], v[52:55]
	v_mfma_f32_16x16x32_bf16 v[48:51], v[178:181], v[186:189], v[48:51]
	v_mfma_f32_16x16x32_bf16 v[36:39], v[170:173], v[194:197], v[36:39]
	v_mfma_f32_16x16x32_bf16 v[32:35], v[178:181], v[194:197], v[32:35]
	v_mfma_f32_16x16x32_bf16 v[20:23], v[170:173], v[202:205], v[20:23]
	v_mfma_f32_16x16x32_bf16 v[16:19], v[178:181], v[202:205], v[16:19]
	v_mfma_f32_16x16x32_bf16 v[4:7], v[170:173], v[212:215], v[4:7]
	v_mfma_f32_16x16x32_bf16 v[0:3], v[178:181], v[212:215], v[0:3]
	s_barrier
	s_add_i32 s62, 0, 0x18000
	s_add_i32 s63, 0, 0x1c000
	s_add_u32 s40, s40, 0x40000
	s_addc_u32 s41, s41, 0
	s_mov_b32 m0, s48
	s_nop 0
	global_load_lds_dwordx4 v128, s[40:41]
	s_mov_b32 m0, s49
	s_nop 0
	global_load_lds_dwordx4 v130, s[40:41]
	v_add_u32_e32 v157, s62, v151
	ds_read_b128 v[140:143], v157
	ds_read_b128 v[144:147], v157 offset:1024
	ds_read_b128 v[158:161], v157 offset:2048
	ds_read_b128 v[162:165], v157 offset:3072
	v_add_u32_e32 v157, s63, v151
	ds_read_b128 v[166:169], v157
	ds_read_b128 v[170:173], v157 offset:1024
	ds_read_b128 v[174:177], v157 offset:2048
	ds_read_b128 v[178:181], v157 offset:3072
	ds_read_b128 v[182:185], v155 offset:32768
	ds_read_b128 v[186:189], v155 offset:33792
	ds_read_b128 v[190:193], v155 offset:34816
	ds_read_b128 v[194:197], v155 offset:35840
	ds_read_b128 v[198:201], v155 offset:36864
	ds_read_b128 v[202:205], v155 offset:37888
	ds_read_b128 v[208:211], v155 offset:38912
	ds_read_b128 v[212:215], v155 offset:39936
	s_waitcnt vmcnt(8)
	s_waitcnt lgkmcnt(0)
	s_barrier
	s_waitcnt lgkmcnt(0)
	v_mfma_f32_16x16x32_bf16 v[124:127], v[140:143], v[182:185], v[124:127]
	v_mfma_f32_16x16x32_bf16 v[120:123], v[158:161], v[182:185], v[120:123]
	v_mfma_f32_16x16x32_bf16 v[108:111], v[140:143], v[190:193], v[108:111]
	v_mfma_f32_16x16x32_bf16 v[104:107], v[158:161], v[190:193], v[104:107]
	v_mfma_f32_16x16x32_bf16 v[92:95], v[140:143], v[198:201], v[92:95]
	v_mfma_f32_16x16x32_bf16 v[88:91], v[158:161], v[198:201], v[88:91]
	v_mfma_f32_16x16x32_bf16 v[76:79], v[140:143], v[208:211], v[76:79]
	v_mfma_f32_16x16x32_bf16 v[72:75], v[158:161], v[208:211], v[72:75]
	v_mfma_f32_16x16x32_bf16 v[124:127], v[144:147], v[186:189], v[124:127]
	v_mfma_f32_16x16x32_bf16 v[120:123], v[162:165], v[186:189], v[120:123]
	v_mfma_f32_16x16x32_bf16 v[108:111], v[144:147], v[194:197], v[108:111]
	v_mfma_f32_16x16x32_bf16 v[104:107], v[162:165], v[194:197], v[104:107]
	v_mfma_f32_16x16x32_bf16 v[92:95], v[144:147], v[202:205], v[92:95]
	v_mfma_f32_16x16x32_bf16 v[88:91], v[162:165], v[202:205], v[88:91]
	v_mfma_f32_16x16x32_bf16 v[76:79], v[144:147], v[212:215], v[76:79]
	v_mfma_f32_16x16x32_bf16 v[72:75], v[162:165], v[212:215], v[72:75]
	v_mfma_f32_16x16x32_bf16 v[116:119], v[166:169], v[182:185], v[116:119]
	v_mfma_f32_16x16x32_bf16 v[112:115], v[174:177], v[182:185], v[112:115]
	v_mfma_f32_16x16x32_bf16 v[100:103], v[166:169], v[190:193], v[100:103]
	v_mfma_f32_16x16x32_bf16 v[96:99], v[174:177], v[190:193], v[96:99]
	v_mfma_f32_16x16x32_bf16 v[84:87], v[166:169], v[198:201], v[84:87]
	v_mfma_f32_16x16x32_bf16 v[80:83], v[174:177], v[198:201], v[80:83]
	v_mfma_f32_16x16x32_bf16 v[68:71], v[166:169], v[208:211], v[68:71]
	v_mfma_f32_16x16x32_bf16 v[64:67], v[174:177], v[208:211], v[64:67]
	v_mfma_f32_16x16x32_bf16 v[116:119], v[170:173], v[186:189], v[116:119]
	v_mfma_f32_16x16x32_bf16 v[112:115], v[178:181], v[186:189], v[112:115]
	v_mfma_f32_16x16x32_bf16 v[100:103], v[170:173], v[194:197], v[100:103]
	v_mfma_f32_16x16x32_bf16 v[96:99], v[178:181], v[194:197], v[96:99]
	v_mfma_f32_16x16x32_bf16 v[84:87], v[170:173], v[202:205], v[84:87]
	v_mfma_f32_16x16x32_bf16 v[80:83], v[178:181], v[202:205], v[80:83]
	v_mfma_f32_16x16x32_bf16 v[68:71], v[170:173], v[212:215], v[68:71]
	v_mfma_f32_16x16x32_bf16 v[64:67], v[178:181], v[212:215], v[64:67]
	s_barrier
	s_add_i32 s40, s62, s45
	s_mov_b32 m0, s40
	s_nop 0
	global_load_lds_dwordx4 v148, s[38:39]
	s_add_i32 m0, s40, 0x2000
	s_add_u32 s38, s38, 0x40080
	s_addc_u32 s39, s39, 0
	s_add_i32 s40, s63, s45
	global_load_lds_dwordx4 v149, s[98:99]
	s_mov_b32 m0, s40
	s_nop 0
	global_load_lds_dwordx4 v128, s[38:39]
	s_add_i32 m0, s40, 0x2000
	s_nop 0
	global_load_lds_dwordx4 v130, s[38:39]
	s_mov_b32 m0, s51
	s_nop 0
	global_load_lds_dwordx4 v148, s[100:101]
	s_mov_b32 m0, s52
	s_nop 0
	global_load_lds_dwordx4 v149, s[100:101]
	ds_read_b128 v[182:185], v155 offset:49152
	ds_read_b128 v[186:189], v155 offset:50176
	ds_read_b128 v[190:193], v155 offset:51200
	ds_read_b128 v[194:197], v155 offset:52224
	ds_read_b128 v[198:201], v155 offset:53248
	ds_read_b128 v[202:205], v155 offset:54272
	ds_read_b128 v[208:211], v155 offset:55296
	ds_read_b128 v[212:215], v155 offset:56320
	s_waitcnt vmcnt(8)
	s_waitcnt lgkmcnt(0)
	s_barrier
	s_waitcnt lgkmcnt(0)
	v_mfma_f32_16x16x32_bf16 v[60:63], v[140:143], v[182:185], v[60:63]
	v_mfma_f32_16x16x32_bf16 v[56:59], v[158:161], v[182:185], v[56:59]
	v_mfma_f32_16x16x32_bf16 v[44:47], v[140:143], v[190:193], v[44:47]
	v_mfma_f32_16x16x32_bf16 v[40:43], v[158:161], v[190:193], v[40:43]
	v_mfma_f32_16x16x32_bf16 v[28:31], v[140:143], v[198:201], v[28:31]
	v_mfma_f32_16x16x32_bf16 v[24:27], v[158:161], v[198:201], v[24:27]
	v_mfma_f32_16x16x32_bf16 v[12:15], v[140:143], v[208:211], v[12:15]
	v_mfma_f32_16x16x32_bf16 v[8:11], v[158:161], v[208:211], v[8:11]
	v_mfma_f32_16x16x32_bf16 v[60:63], v[144:147], v[186:189], v[60:63]
	v_mfma_f32_16x16x32_bf16 v[56:59], v[162:165], v[186:189], v[56:59]
	v_mfma_f32_16x16x32_bf16 v[44:47], v[144:147], v[194:197], v[44:47]
	v_mfma_f32_16x16x32_bf16 v[40:43], v[162:165], v[194:197], v[40:43]
	v_mfma_f32_16x16x32_bf16 v[28:31], v[144:147], v[202:205], v[28:31]
	v_mfma_f32_16x16x32_bf16 v[24:27], v[162:165], v[202:205], v[24:27]
	v_mfma_f32_16x16x32_bf16 v[12:15], v[144:147], v[212:215], v[12:15]
	v_mfma_f32_16x16x32_bf16 v[8:11], v[162:165], v[212:215], v[8:11]
	v_mfma_f32_16x16x32_bf16 v[52:55], v[166:169], v[182:185], v[52:55]
	v_mfma_f32_16x16x32_bf16 v[48:51], v[174:177], v[182:185], v[48:51]
	v_mfma_f32_16x16x32_bf16 v[36:39], v[166:169], v[190:193], v[36:39]
	v_mfma_f32_16x16x32_bf16 v[32:35], v[174:177], v[190:193], v[32:35]
	v_mfma_f32_16x16x32_bf16 v[20:23], v[166:169], v[198:201], v[20:23]
	v_mfma_f32_16x16x32_bf16 v[16:19], v[174:177], v[198:201], v[16:19]
	v_mfma_f32_16x16x32_bf16 v[4:7], v[166:169], v[208:211], v[4:7]
	v_mfma_f32_16x16x32_bf16 v[0:3], v[174:177], v[208:211], v[0:3]
	v_mfma_f32_16x16x32_bf16 v[52:55], v[170:173], v[186:189], v[52:55]
	v_mfma_f32_16x16x32_bf16 v[48:51], v[178:181], v[186:189], v[48:51]
	v_mfma_f32_16x16x32_bf16 v[36:39], v[170:173], v[194:197], v[36:39]
	v_mfma_f32_16x16x32_bf16 v[32:35], v[178:181], v[194:197], v[32:35]
	v_mfma_f32_16x16x32_bf16 v[20:23], v[170:173], v[202:205], v[20:23]
	v_mfma_f32_16x16x32_bf16 v[16:19], v[178:181], v[202:205], v[16:19]
	v_mfma_f32_16x16x32_bf16 v[4:7], v[170:173], v[212:215], v[4:7]
	v_mfma_f32_16x16x32_bf16 v[0:3], v[178:181], v[212:215], v[0:3]
	s_barrier
	s_add_i32 s61, s61, 2
	s_add_u32 s59, s59, 0x100
	s_addc_u32 s60, s60, 0
	s_add_u32 s36, s36, 0x100
	s_addc_u32 s37, s37, 0
	s_cmp_gt_u32 s61, 13
	s_cbranch_scc0 .LBB0_895
	s_setprio 0
	s_and_b64 vcc, exec, s[24:25]
	s_cbranch_vccz .LBB0_898
	s_barrier

.LBB0_988:
	s_add_u32 s26, s6, 0xfffc0080
	s_addc_u32 s27, s7, -1
	s_cmp_eq_u32 s53, 12
	s_cselect_b32 s29, s19, s27
	s_cselect_b32 s28, s49, s26
	s_cselect_b32 s27, s17, s52
	s_cselect_b32 s26, s50, s51
	s_add_i32 m0, s25, 0xc000
	s_nop 0
	global_load_lds_dwordx4 v138, s[6:7]
	s_add_i32 m0, s25, 0xe000
	s_nop 0
	global_load_lds_dwordx4 v136, s[6:7]
	ds_read_b128 v[144:147], v151
	ds_read_b128 v[156:159], v151 offset:1024
	ds_read_b128 v[160:163], v151 offset:2048
	ds_read_b128 v[164:167], v151 offset:3072
	ds_read_b128 v[168:171], v152
	ds_read_b128 v[172:175], v152 offset:1024
	ds_read_b128 v[176:179], v152 offset:2048
	ds_read_b128 v[180:183], v152 offset:3072
	ds_read_b128 v[184:187], v153
	ds_read_b128 v[188:191], v153 offset:1024
	ds_read_b128 v[192:195], v153 offset:2048
	ds_read_b128 v[196:199], v153 offset:3072
	ds_read_b128 v[200:203], v153 offset:4096
	ds_read_b128 v[208:211], v153 offset:5120
	ds_read_b128 v[212:215], v153 offset:6144
	ds_read_b128 v[216:219], v153 offset:7168
	s_waitcnt vmcnt(8)
	s_waitcnt lgkmcnt(0)
	s_barrier
	s_waitcnt lgkmcnt(0)
	v_mfma_f32_16x16x32_bf16 v[124:127], v[144:147], v[184:187], v[124:127]
	v_mfma_f32_16x16x32_bf16 v[120:123], v[160:163], v[184:187], v[120:123]
	v_mfma_f32_16x16x32_bf16 v[108:111], v[144:147], v[192:195], v[108:111]
	v_mfma_f32_16x16x32_bf16 v[104:107], v[160:163], v[192:195], v[104:107]
	v_mfma_f32_16x16x32_bf16 v[92:95], v[144:147], v[200:203], v[92:95]
	v_mfma_f32_16x16x32_bf16 v[88:91], v[160:163], v[200:203], v[88:91]
	v_mfma_f32_16x16x32_bf16 v[76:79], v[144:147], v[212:215], v[76:79]
	v_mfma_f32_16x16x32_bf16 v[72:75], v[160:163], v[212:215], v[72:75]
	v_mfma_f32_16x16x32_bf16 v[124:127], v[156:159], v[188:191], v[124:127]
	v_mfma_f32_16x16x32_bf16 v[120:123], v[164:167], v[188:191], v[120:123]
	v_mfma_f32_16x16x32_bf16 v[108:111], v[156:159], v[196:199], v[108:111]
	v_mfma_f32_16x16x32_bf16 v[104:107], v[164:167], v[196:199], v[104:107]
	v_mfma_f32_16x16x32_bf16 v[92:95], v[156:159], v[208:211], v[92:95]
	v_mfma_f32_16x16x32_bf16 v[88:91], v[164:167], v[208:211], v[88:91]
	v_mfma_f32_16x16x32_bf16 v[76:79], v[156:159], v[216:219], v[76:79]
	v_mfma_f32_16x16x32_bf16 v[72:75], v[164:167], v[216:219], v[72:75]
	v_mfma_f32_16x16x32_bf16 v[116:119], v[168:171], v[184:187], v[116:119]
	v_mfma_f32_16x16x32_bf16 v[112:115], v[176:179], v[184:187], v[112:115]
	v_mfma_f32_16x16x32_bf16 v[100:103], v[168:171], v[192:195], v[100:103]
	v_mfma_f32_16x16x32_bf16 v[96:99], v[176:179], v[192:195], v[96:99]
	v_mfma_f32_16x16x32_bf16 v[84:87], v[168:171], v[200:203], v[84:87]
	v_mfma_f32_16x16x32_bf16 v[80:83], v[176:179], v[200:203], v[80:83]
	v_mfma_f32_16x16x32_bf16 v[68:71], v[168:171], v[212:215], v[68:71]
	v_mfma_f32_16x16x32_bf16 v[64:67], v[176:179], v[212:215], v[64:67]
	v_mfma_f32_16x16x32_bf16 v[116:119], v[172:175], v[188:191], v[116:119]
	v_mfma_f32_16x16x32_bf16 v[112:115], v[180:183], v[188:191], v[112:115]
	v_mfma_f32_16x16x32_bf16 v[100:103], v[172:175], v[196:199], v[100:103]
	v_mfma_f32_16x16x32_bf16 v[96:99], v[180:183], v[196:199], v[96:99]
	v_mfma_f32_16x16x32_bf16 v[84:87], v[172:175], v[208:211], v[84:87]
	v_mfma_f32_16x16x32_bf16 v[80:83], v[180:183], v[208:211], v[80:83]
	v_mfma_f32_16x16x32_bf16 v[68:71], v[172:175], v[216:219], v[68:71]
	v_mfma_f32_16x16x32_bf16 v[64:67], v[180:183], v[216:219], v[64:67]
	s_barrier
	s_add_i32 s54, s45, s38
	s_mov_b32 m0, s54
	s_nop 0
	global_load_lds_dwordx4 v130, s[26:27]
	s_add_i32 m0, s54, 0x2000
	s_add_u32 s54, s26, 0x40000
	s_mov_b64 s[98:99], s[26:27]
	s_addc_u32 s55, s27, 0
	s_add_i32 s56, s46, s38
	global_load_lds_dwordx4 v134, s[26:27]
	s_mov_b32 m0, s56
	s_mov_b64 s[100:101], s[28:29]
	global_load_lds_dwordx4 v130, s[54:55]
	s_add_i32 m0, s56, 0x2000
	s_nop 0
	global_load_lds_dwordx4 v134, s[54:55]
	s_mov_b32 m0, s25
	s_nop 0
	global_load_lds_dwordx4 v128, s[28:29]
	s_mov_b32 m0, s39
	s_nop 0
	global_load_lds_dwordx4 v132, s[28:29]
	ds_read_b128 v[184:187], v153 offset:16384
	ds_read_b128 v[188:191], v153 offset:17408
	ds_read_b128 v[192:195], v153 offset:18432
	ds_read_b128 v[196:199], v153 offset:19456
	ds_read_b128 v[200:203], v153 offset:20480
	ds_read_b128 v[208:211], v153 offset:21504
	ds_read_b128 v[212:215], v153 offset:22528
	ds_read_b128 v[216:219], v153 offset:23552
	s_waitcnt vmcnt(8)
	s_waitcnt lgkmcnt(0)
	s_barrier
	s_waitcnt lgkmcnt(0)
	v_mfma_f32_16x16x32_bf16 v[60:63], v[144:147], v[184:187], v[60:63]
	v_mfma_f32_16x16x32_bf16 v[56:59], v[160:163], v[184:187], v[56:59]
	v_mfma_f32_16x16x32_bf16 v[44:47], v[144:147], v[192:195], v[44:47]
	v_mfma_f32_16x16x32_bf16 v[40:43], v[160:163], v[192:195], v[40:43]
	v_mfma_f32_16x16x32_bf16 v[28:31], v[144:147], v[200:203], v[28:31]
	v_mfma_f32_16x16x32_bf16 v[24:27], v[160:163], v[200:203], v[24:27]
	v_mfma_f32_16x16x32_bf16 v[12:15], v[144:147], v[212:215], v[12:15]
	v_mfma_f32_16x16x32_bf16 v[8:11], v[160:163], v[212:215], v[8:11]
	v_mfma_f32_16x16x32_bf16 v[60:63], v[156:159], v[188:191], v[60:63]
	v_mfma_f32_16x16x32_bf16 v[56:59], v[164:167], v[188:191], v[56:59]
	v_mfma_f32_16x16x32_bf16 v[44:47], v[156:159], v[196:199], v[44:47]
	v_mfma_f32_16x16x32_bf16 v[40:43], v[164:167], v[196:199], v[40:43]
	v_mfma_f32_16x16x32_bf16 v[28:31], v[156:159], v[208:211], v[28:31]
	v_mfma_f32_16x16x32_bf16 v[24:27], v[164:167], v[208:211], v[24:27]
	v_mfma_f32_16x16x32_bf16 v[12:15], v[156:159], v[216:219], v[12:15]
	v_mfma_f32_16x16x32_bf16 v[8:11], v[164:167], v[216:219], v[8:11]
	v_mfma_f32_16x16x32_bf16 v[52:55], v[168:171], v[184:187], v[52:55]
	v_mfma_f32_16x16x32_bf16 v[48:51], v[176:179], v[184:187], v[48:51]
	v_mfma_f32_16x16x32_bf16 v[36:39], v[168:171], v[192:195], v[36:39]
	v_mfma_f32_16x16x32_bf16 v[32:35], v[176:179], v[192:195], v[32:35]
	v_mfma_f32_16x16x32_bf16 v[20:23], v[168:171], v[200:203], v[20:23]
	v_mfma_f32_16x16x32_bf16 v[16:19], v[176:179], v[200:203], v[16:19]
	v_mfma_f32_16x16x32_bf16 v[4:7], v[168:171], v[212:215], v[4:7]
	v_mfma_f32_16x16x32_bf16 v[0:3], v[176:179], v[212:215], v[0:3]
	v_mfma_f32_16x16x32_bf16 v[52:55], v[172:175], v[188:191], v[52:55]
	v_mfma_f32_16x16x32_bf16 v[48:51], v[180:183], v[188:191], v[48:51]
	v_mfma_f32_16x16x32_bf16 v[36:39], v[172:175], v[196:199], v[36:39]
	v_mfma_f32_16x16x32_bf16 v[32:35], v[180:183], v[196:199], v[32:35]
	v_mfma_f32_16x16x32_bf16 v[20:23], v[172:175], v[208:211], v[20:23]
	v_mfma_f32_16x16x32_bf16 v[16:19], v[180:183], v[208:211], v[16:19]
	v_mfma_f32_16x16x32_bf16 v[4:7], v[172:175], v[216:219], v[4:7]
	v_mfma_f32_16x16x32_bf16 v[0:3], v[180:183], v[216:219], v[0:3]
	s_barrier
	s_add_i32 s54, 0, 0x18000
	s_add_i32 s55, 0, 0x1c000
	s_add_u32 s28, s28, 0x40000
	s_addc_u32 s29, s29, 0
	s_mov_b32 m0, s40
	s_nop 0
	global_load_lds_dwordx4 v128, s[28:29]
	s_mov_b32 m0, s41
	s_nop 0
	global_load_lds_dwordx4 v132, s[28:29]
	v_add_u32_e32 v155, s54, v149
	ds_read_b128 v[144:147], v155
	ds_read_b128 v[156:159], v155 offset:1024
	ds_read_b128 v[160:163], v155 offset:2048
	ds_read_b128 v[164:167], v155 offset:3072
	v_add_u32_e32 v155, s55, v149
	ds_read_b128 v[168:171], v155
	ds_read_b128 v[172:175], v155 offset:1024
	ds_read_b128 v[176:179], v155 offset:2048
	ds_read_b128 v[180:183], v155 offset:3072
	ds_read_b128 v[184:187], v153 offset:32768
	ds_read_b128 v[188:191], v153 offset:33792
	ds_read_b128 v[192:195], v153 offset:34816
	ds_read_b128 v[196:199], v153 offset:35840
	ds_read_b128 v[200:203], v153 offset:36864
	ds_read_b128 v[208:211], v153 offset:37888
	ds_read_b128 v[212:215], v153 offset:38912
	ds_read_b128 v[216:219], v153 offset:39936
	s_waitcnt vmcnt(8)
	s_waitcnt lgkmcnt(0)
	s_barrier
	s_waitcnt lgkmcnt(0)
	v_mfma_f32_16x16x32_bf16 v[124:127], v[144:147], v[184:187], v[124:127]
	v_mfma_f32_16x16x32_bf16 v[120:123], v[160:163], v[184:187], v[120:123]
	v_mfma_f32_16x16x32_bf16 v[108:111], v[144:147], v[192:195], v[108:111]
	v_mfma_f32_16x16x32_bf16 v[104:107], v[160:163], v[192:195], v[104:107]
	v_mfma_f32_16x16x32_bf16 v[92:95], v[144:147], v[200:203], v[92:95]
	v_mfma_f32_16x16x32_bf16 v[88:91], v[160:163], v[200:203], v[88:91]
	v_mfma_f32_16x16x32_bf16 v[76:79], v[144:147], v[212:215], v[76:79]
	v_mfma_f32_16x16x32_bf16 v[72:75], v[160:163], v[212:215], v[72:75]
	v_mfma_f32_16x16x32_bf16 v[124:127], v[156:159], v[188:191], v[124:127]
	v_mfma_f32_16x16x32_bf16 v[120:123], v[164:167], v[188:191], v[120:123]
	v_mfma_f32_16x16x32_bf16 v[108:111], v[156:159], v[196:199], v[108:111]
	v_mfma_f32_16x16x32_bf16 v[104:107], v[164:167], v[196:199], v[104:107]
	v_mfma_f32_16x16x32_bf16 v[92:95], v[156:159], v[208:211], v[92:95]
	v_mfma_f32_16x16x32_bf16 v[88:91], v[164:167], v[208:211], v[88:91]
	v_mfma_f32_16x16x32_bf16 v[76:79], v[156:159], v[216:219], v[76:79]
	v_mfma_f32_16x16x32_bf16 v[72:75], v[164:167], v[216:219], v[72:75]
	v_mfma_f32_16x16x32_bf16 v[116:119], v[168:171], v[184:187], v[116:119]
	v_mfma_f32_16x16x32_bf16 v[112:115], v[176:179], v[184:187], v[112:115]
	v_mfma_f32_16x16x32_bf16 v[100:103], v[168:171], v[192:195], v[100:103]
	v_mfma_f32_16x16x32_bf16 v[96:99], v[176:179], v[192:195], v[96:99]
	v_mfma_f32_16x16x32_bf16 v[84:87], v[168:171], v[200:203], v[84:87]
	v_mfma_f32_16x16x32_bf16 v[80:83], v[176:179], v[200:203], v[80:83]
	v_mfma_f32_16x16x32_bf16 v[68:71], v[168:171], v[212:215], v[68:71]
	v_mfma_f32_16x16x32_bf16 v[64:67], v[176:179], v[212:215], v[64:67]
	v_mfma_f32_16x16x32_bf16 v[116:119], v[172:175], v[188:191], v[116:119]
	v_mfma_f32_16x16x32_bf16 v[112:115], v[180:183], v[188:191], v[112:115]
	v_mfma_f32_16x16x32_bf16 v[100:103], v[172:175], v[196:199], v[100:103]
	v_mfma_f32_16x16x32_bf16 v[96:99], v[180:183], v[196:199], v[96:99]
	v_mfma_f32_16x16x32_bf16 v[84:87], v[172:175], v[208:211], v[84:87]
	v_mfma_f32_16x16x32_bf16 v[80:83], v[180:183], v[208:211], v[80:83]
	v_mfma_f32_16x16x32_bf16 v[68:71], v[172:175], v[216:219], v[68:71]
	v_mfma_f32_16x16x32_bf16 v[64:67], v[180:183], v[216:219], v[64:67]
	s_barrier
	s_add_i32 s28, s54, s38
	s_mov_b32 m0, s28
	s_nop 0
	global_load_lds_dwordx4 v205, s[26:27]
	s_add_i32 m0, s28, 0x2000
	s_add_u32 s26, s26, 0x40080
	s_addc_u32 s27, s27, 0
	s_add_i32 s28, s55, s38
	global_load_lds_dwordx4 v221, s[98:99]
	s_mov_b32 m0, s28
	s_nop 0
	global_load_lds_dwordx4 v130, s[26:27]
	s_add_i32 m0, s28, 0x2000
	s_nop 0
	global_load_lds_dwordx4 v134, s[26:27]
	s_mov_b32 m0, s43
	s_nop 0
	global_load_lds_dwordx4 v204, s[100:101]
	s_mov_b32 m0, s44
	s_nop 0
	global_load_lds_dwordx4 v220, s[100:101]
	ds_read_b128 v[184:187], v153 offset:49152
	ds_read_b128 v[188:191], v153 offset:50176
	ds_read_b128 v[192:195], v153 offset:51200
	ds_read_b128 v[196:199], v153 offset:52224
	ds_read_b128 v[200:203], v153 offset:53248
	ds_read_b128 v[208:211], v153 offset:54272
	ds_read_b128 v[212:215], v153 offset:55296
	ds_read_b128 v[216:219], v153 offset:56320
	s_waitcnt vmcnt(8)
	s_waitcnt lgkmcnt(0)
	s_barrier
	s_waitcnt lgkmcnt(0)
	v_mfma_f32_16x16x32_bf16 v[60:63], v[144:147], v[184:187], v[60:63]
	v_mfma_f32_16x16x32_bf16 v[56:59], v[160:163], v[184:187], v[56:59]
	v_mfma_f32_16x16x32_bf16 v[44:47], v[144:147], v[192:195], v[44:47]
	v_mfma_f32_16x16x32_bf16 v[40:43], v[160:163], v[192:195], v[40:43]
	v_mfma_f32_16x16x32_bf16 v[28:31], v[144:147], v[200:203], v[28:31]
	v_mfma_f32_16x16x32_bf16 v[24:27], v[160:163], v[200:203], v[24:27]
	v_mfma_f32_16x16x32_bf16 v[12:15], v[144:147], v[212:215], v[12:15]
	v_mfma_f32_16x16x32_bf16 v[8:11], v[160:163], v[212:215], v[8:11]
	v_mfma_f32_16x16x32_bf16 v[60:63], v[156:159], v[188:191], v[60:63]
	v_mfma_f32_16x16x32_bf16 v[56:59], v[164:167], v[188:191], v[56:59]
	v_mfma_f32_16x16x32_bf16 v[44:47], v[156:159], v[196:199], v[44:47]
	v_mfma_f32_16x16x32_bf16 v[40:43], v[164:167], v[196:199], v[40:43]
	v_mfma_f32_16x16x32_bf16 v[28:31], v[156:159], v[208:211], v[28:31]
	v_mfma_f32_16x16x32_bf16 v[24:27], v[164:167], v[208:211], v[24:27]
	v_mfma_f32_16x16x32_bf16 v[12:15], v[156:159], v[216:219], v[12:15]
	v_mfma_f32_16x16x32_bf16 v[8:11], v[164:167], v[216:219], v[8:11]
	v_mfma_f32_16x16x32_bf16 v[52:55], v[168:171], v[184:187], v[52:55]
	v_mfma_f32_16x16x32_bf16 v[48:51], v[176:179], v[184:187], v[48:51]
	v_mfma_f32_16x16x32_bf16 v[36:39], v[168:171], v[192:195], v[36:39]
	v_mfma_f32_16x16x32_bf16 v[32:35], v[176:179], v[192:195], v[32:35]
	v_mfma_f32_16x16x32_bf16 v[20:23], v[168:171], v[200:203], v[20:23]
	v_mfma_f32_16x16x32_bf16 v[16:19], v[176:179], v[200:203], v[16:19]
	v_mfma_f32_16x16x32_bf16 v[4:7], v[168:171], v[212:215], v[4:7]
	v_mfma_f32_16x16x32_bf16 v[0:3], v[176:179], v[212:215], v[0:3]
	v_mfma_f32_16x16x32_bf16 v[52:55], v[172:175], v[188:191], v[52:55]
	v_mfma_f32_16x16x32_bf16 v[48:51], v[180:183], v[188:191], v[48:51]
	v_mfma_f32_16x16x32_bf16 v[36:39], v[172:175], v[196:199], v[36:39]
	v_mfma_f32_16x16x32_bf16 v[32:35], v[180:183], v[196:199], v[32:35]
	v_mfma_f32_16x16x32_bf16 v[20:23], v[172:175], v[208:211], v[20:23]
	v_mfma_f32_16x16x32_bf16 v[16:19], v[180:183], v[208:211], v[16:19]
	v_mfma_f32_16x16x32_bf16 v[4:7], v[172:175], v[216:219], v[4:7]
	v_mfma_f32_16x16x32_bf16 v[0:3], v[180:183], v[216:219], v[0:3]
	s_barrier
	s_add_i32 s53, s53, 2
	s_add_u32 s51, s51, 0x100
	s_addc_u32 s52, s52, 0
	s_add_u32 s6, s6, 0x100
	s_addc_u32 s7, s7, 0
	s_cmp_gt_u32 s53, 13
	s_cbranch_scc0 .LBB0_988
	s_setprio 0
	s_and_b64 vcc, exec, s[14:15]
	s_cbranch_vccz .LBB0_991
	s_barrier

.LBB0_1193:
	s_add_u32 s26, s24, 0xfffe0080
	s_addc_u32 s27, s25, -1
	s_cmp_eq_u32 s50, 4
	s_cselect_b32 s29, s17, s27
	s_cselect_b32 s28, s46, s26
	s_cselect_b32 s27, s15, s49
	s_cselect_b32 s26, s47, s48
	s_add_i32 m0, s23, 0xc000
	s_nop 0
	global_load_lds_dwordx4 v138, s[24:25]
	s_add_i32 m0, s23, 0xe000
	s_nop 0
	global_load_lds_dwordx4 v136, s[24:25]
	ds_read_b128 v[144:147], v151
	ds_read_b128 v[154:157], v151 offset:1024
	ds_read_b128 v[158:161], v151 offset:2048
	ds_read_b128 v[162:165], v151 offset:3072
	ds_read_b128 v[166:169], v152
	ds_read_b128 v[170:173], v152 offset:1024
	ds_read_b128 v[174:177], v152 offset:2048
	ds_read_b128 v[178:181], v152 offset:3072
	ds_read_b128 v[182:185], v153
	ds_read_b128 v[186:189], v153 offset:1024
	ds_read_b128 v[190:193], v153 offset:2048
	ds_read_b128 v[194:197], v153 offset:3072
	ds_read_b128 v[198:201], v153 offset:4096
	ds_read_b128 v[202:205], v153 offset:5120
	ds_read_b128 v[208:211], v153 offset:6144
	ds_read_b128 v[212:215], v153 offset:7168
	s_waitcnt vmcnt(8)
	s_waitcnt lgkmcnt(0)
	s_barrier
	s_waitcnt lgkmcnt(0)
	v_mfma_f32_16x16x32_bf16 v[124:127], v[144:147], v[182:185], v[124:127]
	v_mfma_f32_16x16x32_bf16 v[120:123], v[158:161], v[182:185], v[120:123]
	v_mfma_f32_16x16x32_bf16 v[108:111], v[144:147], v[190:193], v[108:111]
	v_mfma_f32_16x16x32_bf16 v[104:107], v[158:161], v[190:193], v[104:107]
	v_mfma_f32_16x16x32_bf16 v[92:95], v[144:147], v[198:201], v[92:95]
	v_mfma_f32_16x16x32_bf16 v[88:91], v[158:161], v[198:201], v[88:91]
	v_mfma_f32_16x16x32_bf16 v[76:79], v[144:147], v[208:211], v[76:79]
	v_mfma_f32_16x16x32_bf16 v[72:75], v[158:161], v[208:211], v[72:75]
	v_mfma_f32_16x16x32_bf16 v[124:127], v[154:157], v[186:189], v[124:127]
	v_mfma_f32_16x16x32_bf16 v[120:123], v[162:165], v[186:189], v[120:123]
	v_mfma_f32_16x16x32_bf16 v[108:111], v[154:157], v[194:197], v[108:111]
	v_mfma_f32_16x16x32_bf16 v[104:107], v[162:165], v[194:197], v[104:107]
	v_mfma_f32_16x16x32_bf16 v[92:95], v[154:157], v[202:205], v[92:95]
	v_mfma_f32_16x16x32_bf16 v[88:91], v[162:165], v[202:205], v[88:91]
	v_mfma_f32_16x16x32_bf16 v[76:79], v[154:157], v[212:215], v[76:79]
	v_mfma_f32_16x16x32_bf16 v[72:75], v[162:165], v[212:215], v[72:75]
	v_mfma_f32_16x16x32_bf16 v[116:119], v[166:169], v[182:185], v[116:119]
	v_mfma_f32_16x16x32_bf16 v[112:115], v[174:177], v[182:185], v[112:115]
	v_mfma_f32_16x16x32_bf16 v[100:103], v[166:169], v[190:193], v[100:103]
	v_mfma_f32_16x16x32_bf16 v[96:99], v[174:177], v[190:193], v[96:99]
	v_mfma_f32_16x16x32_bf16 v[84:87], v[166:169], v[198:201], v[84:87]
	v_mfma_f32_16x16x32_bf16 v[80:83], v[174:177], v[198:201], v[80:83]
	v_mfma_f32_16x16x32_bf16 v[68:71], v[166:169], v[208:211], v[68:71]
	v_mfma_f32_16x16x32_bf16 v[64:67], v[174:177], v[208:211], v[64:67]
	v_mfma_f32_16x16x32_bf16 v[116:119], v[170:173], v[186:189], v[116:119]
	v_mfma_f32_16x16x32_bf16 v[112:115], v[178:181], v[186:189], v[112:115]
	v_mfma_f32_16x16x32_bf16 v[100:103], v[170:173], v[194:197], v[100:103]
	v_mfma_f32_16x16x32_bf16 v[96:99], v[178:181], v[194:197], v[96:99]
	v_mfma_f32_16x16x32_bf16 v[84:87], v[170:173], v[202:205], v[84:87]
	v_mfma_f32_16x16x32_bf16 v[80:83], v[178:181], v[202:205], v[80:83]
	v_mfma_f32_16x16x32_bf16 v[68:71], v[170:173], v[212:215], v[68:71]
	v_mfma_f32_16x16x32_bf16 v[64:67], v[178:181], v[212:215], v[64:67]
	s_barrier
	s_add_i32 s51, s43, s36
	s_mov_b32 m0, s51
	s_nop 0
	global_load_lds_dwordx4 v130, s[26:27]
	s_add_i32 m0, s51, 0x2000
	s_add_u32 s52, s26, 0x20000
	s_mov_b64 s[98:99], s[26:27]
	s_addc_u32 s53, s27, 0
	s_add_i32 s51, s44, s36
	global_load_lds_dwordx4 v134, s[26:27]
	s_mov_b32 m0, s51
	s_mov_b64 s[100:101], s[28:29]
	global_load_lds_dwordx4 v130, s[52:53]
	s_add_i32 m0, s51, 0x2000
	s_nop 0
	global_load_lds_dwordx4 v134, s[52:53]
	s_mov_b32 m0, s23
	s_nop 0
	global_load_lds_dwordx4 v128, s[28:29]
	s_mov_b32 m0, s37
	s_nop 0
	global_load_lds_dwordx4 v132, s[28:29]
	ds_read_b128 v[182:185], v153 offset:16384
	ds_read_b128 v[186:189], v153 offset:17408
	ds_read_b128 v[190:193], v153 offset:18432
	ds_read_b128 v[194:197], v153 offset:19456
	ds_read_b128 v[198:201], v153 offset:20480
	ds_read_b128 v[202:205], v153 offset:21504
	ds_read_b128 v[208:211], v153 offset:22528
	ds_read_b128 v[212:215], v153 offset:23552
	s_waitcnt vmcnt(8)
	s_waitcnt lgkmcnt(0)
	s_barrier
	s_waitcnt lgkmcnt(0)
	v_mfma_f32_16x16x32_bf16 v[60:63], v[144:147], v[182:185], v[60:63]
	v_mfma_f32_16x16x32_bf16 v[56:59], v[158:161], v[182:185], v[56:59]
	v_mfma_f32_16x16x32_bf16 v[44:47], v[144:147], v[190:193], v[44:47]
	v_mfma_f32_16x16x32_bf16 v[40:43], v[158:161], v[190:193], v[40:43]
	v_mfma_f32_16x16x32_bf16 v[28:31], v[144:147], v[198:201], v[28:31]
	v_mfma_f32_16x16x32_bf16 v[24:27], v[158:161], v[198:201], v[24:27]
	v_mfma_f32_16x16x32_bf16 v[12:15], v[144:147], v[208:211], v[12:15]
	v_mfma_f32_16x16x32_bf16 v[8:11], v[158:161], v[208:211], v[8:11]
	v_mfma_f32_16x16x32_bf16 v[60:63], v[154:157], v[186:189], v[60:63]
	v_mfma_f32_16x16x32_bf16 v[56:59], v[162:165], v[186:189], v[56:59]
	v_mfma_f32_16x16x32_bf16 v[44:47], v[154:157], v[194:197], v[44:47]
	v_mfma_f32_16x16x32_bf16 v[40:43], v[162:165], v[194:197], v[40:43]
	v_mfma_f32_16x16x32_bf16 v[28:31], v[154:157], v[202:205], v[28:31]
	v_mfma_f32_16x16x32_bf16 v[24:27], v[162:165], v[202:205], v[24:27]
	v_mfma_f32_16x16x32_bf16 v[12:15], v[154:157], v[212:215], v[12:15]
	v_mfma_f32_16x16x32_bf16 v[8:11], v[162:165], v[212:215], v[8:11]
	v_mfma_f32_16x16x32_bf16 v[52:55], v[166:169], v[182:185], v[52:55]
	v_mfma_f32_16x16x32_bf16 v[48:51], v[174:177], v[182:185], v[48:51]
	v_mfma_f32_16x16x32_bf16 v[36:39], v[166:169], v[190:193], v[36:39]
	v_mfma_f32_16x16x32_bf16 v[32:35], v[174:177], v[190:193], v[32:35]
	v_mfma_f32_16x16x32_bf16 v[20:23], v[166:169], v[198:201], v[20:23]
	v_mfma_f32_16x16x32_bf16 v[16:19], v[174:177], v[198:201], v[16:19]
	v_mfma_f32_16x16x32_bf16 v[4:7], v[166:169], v[208:211], v[4:7]
	v_mfma_f32_16x16x32_bf16 v[0:3], v[174:177], v[208:211], v[0:3]
	v_mfma_f32_16x16x32_bf16 v[52:55], v[170:173], v[186:189], v[52:55]
	v_mfma_f32_16x16x32_bf16 v[48:51], v[178:181], v[186:189], v[48:51]
	v_mfma_f32_16x16x32_bf16 v[36:39], v[170:173], v[194:197], v[36:39]
	v_mfma_f32_16x16x32_bf16 v[32:35], v[178:181], v[194:197], v[32:35]
	v_mfma_f32_16x16x32_bf16 v[20:23], v[170:173], v[202:205], v[20:23]
	v_mfma_f32_16x16x32_bf16 v[16:19], v[178:181], v[202:205], v[16:19]
	v_mfma_f32_16x16x32_bf16 v[4:7], v[170:173], v[212:215], v[4:7]
	v_mfma_f32_16x16x32_bf16 v[0:3], v[178:181], v[212:215], v[0:3]
	s_barrier
	s_add_i32 s51, 0, 0x18000
	s_add_i32 s52, 0, 0x1c000
	s_add_u32 s28, s28, 0x20000
	s_addc_u32 s29, s29, 0
	s_mov_b32 m0, s38
	s_nop 0
	global_load_lds_dwordx4 v128, s[28:29]
	s_mov_b32 m0, s39
	s_nop 0
	global_load_lds_dwordx4 v132, s[28:29]
	v_add_u32_e32 v162, s51, v149
	v_add_u32_e32 v178, s52, v149
	ds_read_b128 v[144:147], v162
	ds_read_b128 v[154:157], v162 offset:1024
	ds_read_b128 v[158:161], v162 offset:2048
	ds_read_b128 v[162:165], v162 offset:3072
	ds_read_b128 v[166:169], v178
	ds_read_b128 v[170:173], v178 offset:1024
	ds_read_b128 v[174:177], v178 offset:2048
	ds_read_b128 v[178:181], v178 offset:3072
	ds_read_b128 v[182:185], v153 offset:32768
	ds_read_b128 v[186:189], v153 offset:33792
	ds_read_b128 v[190:193], v153 offset:34816
	ds_read_b128 v[194:197], v153 offset:35840
	ds_read_b128 v[198:201], v153 offset:36864
	ds_read_b128 v[202:205], v153 offset:37888
	ds_read_b128 v[208:211], v153 offset:38912
	ds_read_b128 v[212:215], v153 offset:39936
	s_waitcnt vmcnt(8)
	s_waitcnt lgkmcnt(0)
	s_barrier
	s_waitcnt lgkmcnt(0)
	v_mfma_f32_16x16x32_bf16 v[124:127], v[144:147], v[182:185], v[124:127]
	v_mfma_f32_16x16x32_bf16 v[120:123], v[158:161], v[182:185], v[120:123]
	v_mfma_f32_16x16x32_bf16 v[108:111], v[144:147], v[190:193], v[108:111]
	v_mfma_f32_16x16x32_bf16 v[104:107], v[158:161], v[190:193], v[104:107]
	v_mfma_f32_16x16x32_bf16 v[92:95], v[144:147], v[198:201], v[92:95]
	v_mfma_f32_16x16x32_bf16 v[88:91], v[158:161], v[198:201], v[88:91]
	v_mfma_f32_16x16x32_bf16 v[76:79], v[144:147], v[208:211], v[76:79]
	v_mfma_f32_16x16x32_bf16 v[72:75], v[158:161], v[208:211], v[72:75]
	v_mfma_f32_16x16x32_bf16 v[124:127], v[154:157], v[186:189], v[124:127]
	v_mfma_f32_16x16x32_bf16 v[120:123], v[162:165], v[186:189], v[120:123]
	v_mfma_f32_16x16x32_bf16 v[108:111], v[154:157], v[194:197], v[108:111]
	v_mfma_f32_16x16x32_bf16 v[104:107], v[162:165], v[194:197], v[104:107]
	v_mfma_f32_16x16x32_bf16 v[92:95], v[154:157], v[202:205], v[92:95]
	v_mfma_f32_16x16x32_bf16 v[88:91], v[162:165], v[202:205], v[88:91]
	v_mfma_f32_16x16x32_bf16 v[76:79], v[154:157], v[212:215], v[76:79]
	v_mfma_f32_16x16x32_bf16 v[72:75], v[162:165], v[212:215], v[72:75]
	v_mfma_f32_16x16x32_bf16 v[116:119], v[166:169], v[182:185], v[116:119]
	v_mfma_f32_16x16x32_bf16 v[112:115], v[174:177], v[182:185], v[112:115]
	v_mfma_f32_16x16x32_bf16 v[100:103], v[166:169], v[190:193], v[100:103]
	v_mfma_f32_16x16x32_bf16 v[96:99], v[174:177], v[190:193], v[96:99]
	v_mfma_f32_16x16x32_bf16 v[84:87], v[166:169], v[198:201], v[84:87]
	v_mfma_f32_16x16x32_bf16 v[80:83], v[174:177], v[198:201], v[80:83]
	v_mfma_f32_16x16x32_bf16 v[68:71], v[166:169], v[208:211], v[68:71]
	v_mfma_f32_16x16x32_bf16 v[64:67], v[174:177], v[208:211], v[64:67]
	v_mfma_f32_16x16x32_bf16 v[116:119], v[170:173], v[186:189], v[116:119]
	v_mfma_f32_16x16x32_bf16 v[112:115], v[178:181], v[186:189], v[112:115]
	v_mfma_f32_16x16x32_bf16 v[100:103], v[170:173], v[194:197], v[100:103]
	v_mfma_f32_16x16x32_bf16 v[96:99], v[178:181], v[194:197], v[96:99]
	v_mfma_f32_16x16x32_bf16 v[84:87], v[170:173], v[202:205], v[84:87]
	v_mfma_f32_16x16x32_bf16 v[80:83], v[178:181], v[202:205], v[80:83]
	v_mfma_f32_16x16x32_bf16 v[68:71], v[170:173], v[212:215], v[68:71]
	v_mfma_f32_16x16x32_bf16 v[64:67], v[178:181], v[212:215], v[64:67]
	s_barrier
	s_add_i32 s28, s51, s36
	s_mov_b32 m0, s28
	s_nop 0
	global_load_lds_dwordx4 v217, s[26:27]
	s_add_i32 m0, s28, 0x2000
	s_add_u32 s26, s26, 0x20080
	s_addc_u32 s27, s27, 0
	s_add_i32 s28, s52, s36
	global_load_lds_dwordx4 v219, s[98:99]
	s_mov_b32 m0, s28
	s_nop 0
	global_load_lds_dwordx4 v130, s[26:27]
	s_add_i32 m0, s28, 0x2000
	s_nop 0
	global_load_lds_dwordx4 v134, s[26:27]
	s_mov_b32 m0, s41
	s_nop 0
	global_load_lds_dwordx4 v216, s[100:101]
	s_mov_b32 m0, s42
	s_nop 0
	global_load_lds_dwordx4 v218, s[100:101]
	ds_read_b128 v[182:185], v153 offset:49152
	ds_read_b128 v[186:189], v153 offset:50176
	ds_read_b128 v[190:193], v153 offset:51200
	ds_read_b128 v[194:197], v153 offset:52224
	ds_read_b128 v[198:201], v153 offset:53248
	ds_read_b128 v[202:205], v153 offset:54272
	ds_read_b128 v[208:211], v153 offset:55296
	ds_read_b128 v[212:215], v153 offset:56320
	s_waitcnt vmcnt(8)
	s_waitcnt lgkmcnt(0)
	s_barrier
	s_waitcnt lgkmcnt(0)
	v_mfma_f32_16x16x32_bf16 v[60:63], v[144:147], v[182:185], v[60:63]
	v_mfma_f32_16x16x32_bf16 v[56:59], v[158:161], v[182:185], v[56:59]
	v_mfma_f32_16x16x32_bf16 v[44:47], v[144:147], v[190:193], v[44:47]
	v_mfma_f32_16x16x32_bf16 v[40:43], v[158:161], v[190:193], v[40:43]
	v_mfma_f32_16x16x32_bf16 v[28:31], v[144:147], v[198:201], v[28:31]
	v_mfma_f32_16x16x32_bf16 v[24:27], v[158:161], v[198:201], v[24:27]
	v_mfma_f32_16x16x32_bf16 v[12:15], v[144:147], v[208:211], v[12:15]
	v_mfma_f32_16x16x32_bf16 v[8:11], v[158:161], v[208:211], v[8:11]
	v_mfma_f32_16x16x32_bf16 v[60:63], v[154:157], v[186:189], v[60:63]
	v_mfma_f32_16x16x32_bf16 v[56:59], v[162:165], v[186:189], v[56:59]
	v_mfma_f32_16x16x32_bf16 v[44:47], v[154:157], v[194:197], v[44:47]
	v_mfma_f32_16x16x32_bf16 v[40:43], v[162:165], v[194:197], v[40:43]
	v_mfma_f32_16x16x32_bf16 v[28:31], v[154:157], v[202:205], v[28:31]
	v_mfma_f32_16x16x32_bf16 v[24:27], v[162:165], v[202:205], v[24:27]
	v_mfma_f32_16x16x32_bf16 v[12:15], v[154:157], v[212:215], v[12:15]
	v_mfma_f32_16x16x32_bf16 v[8:11], v[162:165], v[212:215], v[8:11]
	v_mfma_f32_16x16x32_bf16 v[52:55], v[166:169], v[182:185], v[52:55]
	v_mfma_f32_16x16x32_bf16 v[48:51], v[174:177], v[182:185], v[48:51]
	v_mfma_f32_16x16x32_bf16 v[36:39], v[166:169], v[190:193], v[36:39]
	v_mfma_f32_16x16x32_bf16 v[32:35], v[174:177], v[190:193], v[32:35]
	v_mfma_f32_16x16x32_bf16 v[20:23], v[166:169], v[198:201], v[20:23]
	v_mfma_f32_16x16x32_bf16 v[16:19], v[174:177], v[198:201], v[16:19]
	v_mfma_f32_16x16x32_bf16 v[4:7], v[166:169], v[208:211], v[4:7]
	v_mfma_f32_16x16x32_bf16 v[0:3], v[174:177], v[208:211], v[0:3]
	v_mfma_f32_16x16x32_bf16 v[52:55], v[170:173], v[186:189], v[52:55]
	v_mfma_f32_16x16x32_bf16 v[48:51], v[178:181], v[186:189], v[48:51]
	v_mfma_f32_16x16x32_bf16 v[36:39], v[170:173], v[194:197], v[36:39]
	v_mfma_f32_16x16x32_bf16 v[32:35], v[178:181], v[194:197], v[32:35]
	v_mfma_f32_16x16x32_bf16 v[20:23], v[170:173], v[202:205], v[20:23]
	v_mfma_f32_16x16x32_bf16 v[16:19], v[178:181], v[202:205], v[16:19]
	v_mfma_f32_16x16x32_bf16 v[4:7], v[170:173], v[212:215], v[4:7]
	v_mfma_f32_16x16x32_bf16 v[0:3], v[178:181], v[212:215], v[0:3]
	s_barrier
	s_add_i32 s50, s50, 2
	s_add_u32 s48, s48, 0x100
	s_addc_u32 s49, s49, 0
	s_add_u32 s24, s24, 0x100
	s_addc_u32 s25, s25, 0
	s_cmp_gt_u32 s50, 5
	s_cbranch_scc0 .LBB0_1193
	s_setprio 0
	s_and_b64 vcc, exec, s[12:13]
	s_cbranch_vccz .LBB0_1196
	s_barrier

.LBB0_1365:
	s_add_u32 s26, s24, 0xfffc0080
	s_addc_u32 s27, s25, -1
	s_cmp_eq_u32 s53, 12
	s_cselect_b32 s29, s19, s27
	s_cselect_b32 s28, s49, s26
	s_cselect_b32 s27, s17, s52
	s_cselect_b32 s26, s50, s51
	s_add_i32 m0, s39, 0xc000
	s_nop 0
	global_load_lds_dwordx4 v138, s[24:25]
	s_add_i32 m0, s39, 0xe000
	s_nop 0
	global_load_lds_dwordx4 v136, s[24:25]
	ds_read_b128 v[144:147], v151
	ds_read_b128 v[156:159], v151 offset:1024
	ds_read_b128 v[160:163], v151 offset:2048
	ds_read_b128 v[164:167], v151 offset:3072
	ds_read_b128 v[168:171], v152
	ds_read_b128 v[172:175], v152 offset:1024
	ds_read_b128 v[176:179], v152 offset:2048
	ds_read_b128 v[180:183], v152 offset:3072
	ds_read_b128 v[184:187], v153
	ds_read_b128 v[188:191], v153 offset:1024
	ds_read_b128 v[192:195], v153 offset:2048
	ds_read_b128 v[196:199], v153 offset:3072
	ds_read_b128 v[200:203], v153 offset:4096
	ds_read_b128 v[208:211], v153 offset:5120
	ds_read_b128 v[212:215], v153 offset:6144
	ds_read_b128 v[216:219], v153 offset:7168
	s_waitcnt vmcnt(8)
	s_waitcnt lgkmcnt(0)
	s_barrier
	s_waitcnt lgkmcnt(0)
	v_mfma_f32_16x16x32_bf16 v[124:127], v[144:147], v[184:187], v[124:127]
	v_mfma_f32_16x16x32_bf16 v[120:123], v[160:163], v[184:187], v[120:123]
	v_mfma_f32_16x16x32_bf16 v[108:111], v[144:147], v[192:195], v[108:111]
	v_mfma_f32_16x16x32_bf16 v[104:107], v[160:163], v[192:195], v[104:107]
	v_mfma_f32_16x16x32_bf16 v[92:95], v[144:147], v[200:203], v[92:95]
	v_mfma_f32_16x16x32_bf16 v[88:91], v[160:163], v[200:203], v[88:91]
	v_mfma_f32_16x16x32_bf16 v[76:79], v[144:147], v[212:215], v[76:79]
	v_mfma_f32_16x16x32_bf16 v[72:75], v[160:163], v[212:215], v[72:75]
	v_mfma_f32_16x16x32_bf16 v[124:127], v[156:159], v[188:191], v[124:127]
	v_mfma_f32_16x16x32_bf16 v[120:123], v[164:167], v[188:191], v[120:123]
	v_mfma_f32_16x16x32_bf16 v[108:111], v[156:159], v[196:199], v[108:111]
	v_mfma_f32_16x16x32_bf16 v[104:107], v[164:167], v[196:199], v[104:107]
	v_mfma_f32_16x16x32_bf16 v[92:95], v[156:159], v[208:211], v[92:95]
	v_mfma_f32_16x16x32_bf16 v[88:91], v[164:167], v[208:211], v[88:91]
	v_mfma_f32_16x16x32_bf16 v[76:79], v[156:159], v[216:219], v[76:79]
	v_mfma_f32_16x16x32_bf16 v[72:75], v[164:167], v[216:219], v[72:75]
	v_mfma_f32_16x16x32_bf16 v[116:119], v[168:171], v[184:187], v[116:119]
	v_mfma_f32_16x16x32_bf16 v[112:115], v[176:179], v[184:187], v[112:115]
	v_mfma_f32_16x16x32_bf16 v[100:103], v[168:171], v[192:195], v[100:103]
	v_mfma_f32_16x16x32_bf16 v[96:99], v[176:179], v[192:195], v[96:99]
	v_mfma_f32_16x16x32_bf16 v[84:87], v[168:171], v[200:203], v[84:87]
	v_mfma_f32_16x16x32_bf16 v[80:83], v[176:179], v[200:203], v[80:83]
	v_mfma_f32_16x16x32_bf16 v[68:71], v[168:171], v[212:215], v[68:71]
	v_mfma_f32_16x16x32_bf16 v[64:67], v[176:179], v[212:215], v[64:67]
	v_mfma_f32_16x16x32_bf16 v[116:119], v[172:175], v[188:191], v[116:119]
	v_mfma_f32_16x16x32_bf16 v[112:115], v[180:183], v[188:191], v[112:115]
	v_mfma_f32_16x16x32_bf16 v[100:103], v[172:175], v[196:199], v[100:103]
	v_mfma_f32_16x16x32_bf16 v[96:99], v[180:183], v[196:199], v[96:99]
	v_mfma_f32_16x16x32_bf16 v[84:87], v[172:175], v[208:211], v[84:87]
	v_mfma_f32_16x16x32_bf16 v[80:83], v[180:183], v[208:211], v[80:83]
	v_mfma_f32_16x16x32_bf16 v[68:71], v[172:175], v[216:219], v[68:71]
	v_mfma_f32_16x16x32_bf16 v[64:67], v[180:183], v[216:219], v[64:67]
	s_barrier
	s_add_i32 s54, s46, s38
	s_mov_b32 m0, s54
	s_nop 0
	global_load_lds_dwordx4 v130, s[26:27]
	s_add_i32 m0, s54, 0x2000
	s_add_u32 s54, s26, 0x40000
	s_mov_b64 s[98:99], s[26:27]
	s_addc_u32 s55, s27, 0
	s_add_i32 s56, s47, s38
	global_load_lds_dwordx4 v134, s[26:27]
	s_mov_b32 m0, s56
	s_mov_b64 s[100:101], s[28:29]
	global_load_lds_dwordx4 v130, s[54:55]
	s_add_i32 m0, s56, 0x2000
	s_nop 0
	global_load_lds_dwordx4 v134, s[54:55]
	s_mov_b32 m0, s39
	s_nop 0
	global_load_lds_dwordx4 v128, s[28:29]
	s_mov_b32 m0, s40
	s_nop 0
	global_load_lds_dwordx4 v132, s[28:29]
	ds_read_b128 v[184:187], v153 offset:16384
	ds_read_b128 v[188:191], v153 offset:17408
	ds_read_b128 v[192:195], v153 offset:18432
	ds_read_b128 v[196:199], v153 offset:19456
	ds_read_b128 v[200:203], v153 offset:20480
	ds_read_b128 v[208:211], v153 offset:21504
	ds_read_b128 v[212:215], v153 offset:22528
	ds_read_b128 v[216:219], v153 offset:23552
	s_waitcnt vmcnt(8)
	s_waitcnt lgkmcnt(0)
	s_barrier
	s_waitcnt lgkmcnt(0)
	v_mfma_f32_16x16x32_bf16 v[60:63], v[144:147], v[184:187], v[60:63]
	v_mfma_f32_16x16x32_bf16 v[56:59], v[160:163], v[184:187], v[56:59]
	v_mfma_f32_16x16x32_bf16 v[44:47], v[144:147], v[192:195], v[44:47]
	v_mfma_f32_16x16x32_bf16 v[40:43], v[160:163], v[192:195], v[40:43]
	v_mfma_f32_16x16x32_bf16 v[28:31], v[144:147], v[200:203], v[28:31]
	v_mfma_f32_16x16x32_bf16 v[24:27], v[160:163], v[200:203], v[24:27]
	v_mfma_f32_16x16x32_bf16 v[12:15], v[144:147], v[212:215], v[12:15]
	v_mfma_f32_16x16x32_bf16 v[8:11], v[160:163], v[212:215], v[8:11]
	v_mfma_f32_16x16x32_bf16 v[60:63], v[156:159], v[188:191], v[60:63]
	v_mfma_f32_16x16x32_bf16 v[56:59], v[164:167], v[188:191], v[56:59]
	v_mfma_f32_16x16x32_bf16 v[44:47], v[156:159], v[196:199], v[44:47]
	v_mfma_f32_16x16x32_bf16 v[40:43], v[164:167], v[196:199], v[40:43]
	v_mfma_f32_16x16x32_bf16 v[28:31], v[156:159], v[208:211], v[28:31]
	v_mfma_f32_16x16x32_bf16 v[24:27], v[164:167], v[208:211], v[24:27]
	v_mfma_f32_16x16x32_bf16 v[12:15], v[156:159], v[216:219], v[12:15]
	v_mfma_f32_16x16x32_bf16 v[8:11], v[164:167], v[216:219], v[8:11]
	v_mfma_f32_16x16x32_bf16 v[52:55], v[168:171], v[184:187], v[52:55]
	v_mfma_f32_16x16x32_bf16 v[48:51], v[176:179], v[184:187], v[48:51]
	v_mfma_f32_16x16x32_bf16 v[36:39], v[168:171], v[192:195], v[36:39]
	v_mfma_f32_16x16x32_bf16 v[32:35], v[176:179], v[192:195], v[32:35]
	v_mfma_f32_16x16x32_bf16 v[20:23], v[168:171], v[200:203], v[20:23]
	v_mfma_f32_16x16x32_bf16 v[16:19], v[176:179], v[200:203], v[16:19]
	v_mfma_f32_16x16x32_bf16 v[4:7], v[168:171], v[212:215], v[4:7]
	v_mfma_f32_16x16x32_bf16 v[0:3], v[176:179], v[212:215], v[0:3]
	v_mfma_f32_16x16x32_bf16 v[52:55], v[172:175], v[188:191], v[52:55]
	v_mfma_f32_16x16x32_bf16 v[48:51], v[180:183], v[188:191], v[48:51]
	v_mfma_f32_16x16x32_bf16 v[36:39], v[172:175], v[196:199], v[36:39]
	v_mfma_f32_16x16x32_bf16 v[32:35], v[180:183], v[196:199], v[32:35]
	v_mfma_f32_16x16x32_bf16 v[20:23], v[172:175], v[208:211], v[20:23]
	v_mfma_f32_16x16x32_bf16 v[16:19], v[180:183], v[208:211], v[16:19]
	v_mfma_f32_16x16x32_bf16 v[4:7], v[172:175], v[216:219], v[4:7]
	v_mfma_f32_16x16x32_bf16 v[0:3], v[180:183], v[216:219], v[0:3]
	s_barrier
	s_add_i32 s54, 0, 0x18000
	s_add_i32 s55, 0, 0x1c000
	s_add_u32 s28, s28, 0x40000
	s_addc_u32 s29, s29, 0
	s_mov_b32 m0, s41
	s_nop 0
	global_load_lds_dwordx4 v128, s[28:29]
	s_mov_b32 m0, s42
	s_nop 0
	global_load_lds_dwordx4 v132, s[28:29]
	v_add_u32_e32 v155, s54, v149
	ds_read_b128 v[144:147], v155
	ds_read_b128 v[156:159], v155 offset:1024
	ds_read_b128 v[160:163], v155 offset:2048
	ds_read_b128 v[164:167], v155 offset:3072
	v_add_u32_e32 v155, s55, v149
	ds_read_b128 v[168:171], v155
	ds_read_b128 v[172:175], v155 offset:1024
	ds_read_b128 v[176:179], v155 offset:2048
	ds_read_b128 v[180:183], v155 offset:3072
	ds_read_b128 v[184:187], v153 offset:32768
	ds_read_b128 v[188:191], v153 offset:33792
	ds_read_b128 v[192:195], v153 offset:34816
	ds_read_b128 v[196:199], v153 offset:35840
	ds_read_b128 v[200:203], v153 offset:36864
	ds_read_b128 v[208:211], v153 offset:37888
	ds_read_b128 v[212:215], v153 offset:38912
	ds_read_b128 v[216:219], v153 offset:39936
	s_waitcnt vmcnt(8)
	s_waitcnt lgkmcnt(0)
	s_barrier
	s_waitcnt lgkmcnt(0)
	v_mfma_f32_16x16x32_bf16 v[124:127], v[144:147], v[184:187], v[124:127]
	v_mfma_f32_16x16x32_bf16 v[120:123], v[160:163], v[184:187], v[120:123]
	v_mfma_f32_16x16x32_bf16 v[108:111], v[144:147], v[192:195], v[108:111]
	v_mfma_f32_16x16x32_bf16 v[104:107], v[160:163], v[192:195], v[104:107]
	v_mfma_f32_16x16x32_bf16 v[92:95], v[144:147], v[200:203], v[92:95]
	v_mfma_f32_16x16x32_bf16 v[88:91], v[160:163], v[200:203], v[88:91]
	v_mfma_f32_16x16x32_bf16 v[76:79], v[144:147], v[212:215], v[76:79]
	v_mfma_f32_16x16x32_bf16 v[72:75], v[160:163], v[212:215], v[72:75]
	v_mfma_f32_16x16x32_bf16 v[124:127], v[156:159], v[188:191], v[124:127]
	v_mfma_f32_16x16x32_bf16 v[120:123], v[164:167], v[188:191], v[120:123]
	v_mfma_f32_16x16x32_bf16 v[108:111], v[156:159], v[196:199], v[108:111]
	v_mfma_f32_16x16x32_bf16 v[104:107], v[164:167], v[196:199], v[104:107]
	v_mfma_f32_16x16x32_bf16 v[92:95], v[156:159], v[208:211], v[92:95]
	v_mfma_f32_16x16x32_bf16 v[88:91], v[164:167], v[208:211], v[88:91]
	v_mfma_f32_16x16x32_bf16 v[76:79], v[156:159], v[216:219], v[76:79]
	v_mfma_f32_16x16x32_bf16 v[72:75], v[164:167], v[216:219], v[72:75]
	v_mfma_f32_16x16x32_bf16 v[116:119], v[168:171], v[184:187], v[116:119]
	v_mfma_f32_16x16x32_bf16 v[112:115], v[176:179], v[184:187], v[112:115]
	v_mfma_f32_16x16x32_bf16 v[100:103], v[168:171], v[192:195], v[100:103]
	v_mfma_f32_16x16x32_bf16 v[96:99], v[176:179], v[192:195], v[96:99]
	v_mfma_f32_16x16x32_bf16 v[84:87], v[168:171], v[200:203], v[84:87]
	v_mfma_f32_16x16x32_bf16 v[80:83], v[176:179], v[200:203], v[80:83]
	v_mfma_f32_16x16x32_bf16 v[68:71], v[168:171], v[212:215], v[68:71]
	v_mfma_f32_16x16x32_bf16 v[64:67], v[176:179], v[212:215], v[64:67]
	v_mfma_f32_16x16x32_bf16 v[116:119], v[172:175], v[188:191], v[116:119]
	v_mfma_f32_16x16x32_bf16 v[112:115], v[180:183], v[188:191], v[112:115]
	v_mfma_f32_16x16x32_bf16 v[100:103], v[172:175], v[196:199], v[100:103]
	v_mfma_f32_16x16x32_bf16 v[96:99], v[180:183], v[196:199], v[96:99]
	v_mfma_f32_16x16x32_bf16 v[84:87], v[172:175], v[208:211], v[84:87]
	v_mfma_f32_16x16x32_bf16 v[80:83], v[180:183], v[208:211], v[80:83]
	v_mfma_f32_16x16x32_bf16 v[68:71], v[172:175], v[216:219], v[68:71]
	v_mfma_f32_16x16x32_bf16 v[64:67], v[180:183], v[216:219], v[64:67]
	s_barrier
	s_add_i32 s28, s54, s38
	s_mov_b32 m0, s28
	s_nop 0
	global_load_lds_dwordx4 v205, s[26:27]
	s_add_i32 m0, s28, 0x2000
	s_add_u32 s26, s26, 0x40080
	s_addc_u32 s27, s27, 0
	s_add_i32 s28, s55, s38
	global_load_lds_dwordx4 v221, s[98:99]
	s_mov_b32 m0, s28
	s_nop 0
	global_load_lds_dwordx4 v130, s[26:27]
	s_add_i32 m0, s28, 0x2000
	s_nop 0
	global_load_lds_dwordx4 v134, s[26:27]
	s_mov_b32 m0, s44
	s_nop 0
	global_load_lds_dwordx4 v204, s[100:101]
	s_mov_b32 m0, s45
	s_nop 0
	global_load_lds_dwordx4 v220, s[100:101]
	ds_read_b128 v[184:187], v153 offset:49152
	ds_read_b128 v[188:191], v153 offset:50176
	ds_read_b128 v[192:195], v153 offset:51200
	ds_read_b128 v[196:199], v153 offset:52224
	ds_read_b128 v[200:203], v153 offset:53248
	ds_read_b128 v[208:211], v153 offset:54272
	ds_read_b128 v[212:215], v153 offset:55296
	ds_read_b128 v[216:219], v153 offset:56320
	s_waitcnt vmcnt(8)
	s_waitcnt lgkmcnt(0)
	s_barrier
	s_waitcnt lgkmcnt(0)
	v_mfma_f32_16x16x32_bf16 v[60:63], v[144:147], v[184:187], v[60:63]
	v_mfma_f32_16x16x32_bf16 v[56:59], v[160:163], v[184:187], v[56:59]
	v_mfma_f32_16x16x32_bf16 v[44:47], v[144:147], v[192:195], v[44:47]
	v_mfma_f32_16x16x32_bf16 v[40:43], v[160:163], v[192:195], v[40:43]
	v_mfma_f32_16x16x32_bf16 v[28:31], v[144:147], v[200:203], v[28:31]
	v_mfma_f32_16x16x32_bf16 v[24:27], v[160:163], v[200:203], v[24:27]
	v_mfma_f32_16x16x32_bf16 v[12:15], v[144:147], v[212:215], v[12:15]
	v_mfma_f32_16x16x32_bf16 v[8:11], v[160:163], v[212:215], v[8:11]
	v_mfma_f32_16x16x32_bf16 v[60:63], v[156:159], v[188:191], v[60:63]
	v_mfma_f32_16x16x32_bf16 v[56:59], v[164:167], v[188:191], v[56:59]
	v_mfma_f32_16x16x32_bf16 v[44:47], v[156:159], v[196:199], v[44:47]
	v_mfma_f32_16x16x32_bf16 v[40:43], v[164:167], v[196:199], v[40:43]
	v_mfma_f32_16x16x32_bf16 v[28:31], v[156:159], v[208:211], v[28:31]
	v_mfma_f32_16x16x32_bf16 v[24:27], v[164:167], v[208:211], v[24:27]
	v_mfma_f32_16x16x32_bf16 v[12:15], v[156:159], v[216:219], v[12:15]
	v_mfma_f32_16x16x32_bf16 v[8:11], v[164:167], v[216:219], v[8:11]
	v_mfma_f32_16x16x32_bf16 v[52:55], v[168:171], v[184:187], v[52:55]
	v_mfma_f32_16x16x32_bf16 v[48:51], v[176:179], v[184:187], v[48:51]
	v_mfma_f32_16x16x32_bf16 v[36:39], v[168:171], v[192:195], v[36:39]
	v_mfma_f32_16x16x32_bf16 v[32:35], v[176:179], v[192:195], v[32:35]
	v_mfma_f32_16x16x32_bf16 v[20:23], v[168:171], v[200:203], v[20:23]
	v_mfma_f32_16x16x32_bf16 v[16:19], v[176:179], v[200:203], v[16:19]
	v_mfma_f32_16x16x32_bf16 v[4:7], v[168:171], v[212:215], v[4:7]
	v_mfma_f32_16x16x32_bf16 v[0:3], v[176:179], v[212:215], v[0:3]
	v_mfma_f32_16x16x32_bf16 v[52:55], v[172:175], v[188:191], v[52:55]
	v_mfma_f32_16x16x32_bf16 v[48:51], v[180:183], v[188:191], v[48:51]
	v_mfma_f32_16x16x32_bf16 v[36:39], v[172:175], v[196:199], v[36:39]
	v_mfma_f32_16x16x32_bf16 v[32:35], v[180:183], v[196:199], v[32:35]
	v_mfma_f32_16x16x32_bf16 v[20:23], v[172:175], v[208:211], v[20:23]
	v_mfma_f32_16x16x32_bf16 v[16:19], v[180:183], v[208:211], v[16:19]
	v_mfma_f32_16x16x32_bf16 v[4:7], v[172:175], v[216:219], v[4:7]
	v_mfma_f32_16x16x32_bf16 v[0:3], v[180:183], v[216:219], v[0:3]
	s_barrier
	s_add_i32 s53, s53, 2
	s_add_u32 s51, s51, 0x100
	s_addc_u32 s52, s52, 0
	s_add_u32 s24, s24, 0x100
	s_addc_u32 s25, s25, 0
	s_cmp_gt_u32 s53, 13
	s_cbranch_scc0 .LBB0_1365
	s_setprio 0
	s_and_b64 vcc, exec, s[14:15]
	s_cbranch_vccz .LBB0_1368
	s_barrier

.LBB0_1561:
	s_add_u32 s38, s36, 0xfffc0080
	s_addc_u32 s39, s37, -1
	s_cmp_eq_u32 s61, 12
	s_cselect_b32 s41, s3, s39
	s_cselect_b32 s40, s29, s38
	s_cselect_b32 s39, s27, s60
	s_cselect_b32 s38, s58, s59
	s_add_i32 m0, s46, 0xc000
	s_nop 0
	global_load_lds_dwordx4 v134, s[36:37]
	s_add_i32 m0, s46, 0xe000
	s_nop 0
	global_load_lds_dwordx4 v132, s[36:37]
	ds_read_b128 v[140:143], v151
	ds_read_b128 v[144:147], v151 offset:1024
	ds_read_b128 v[156:159], v151 offset:2048
	ds_read_b128 v[160:163], v151 offset:3072
	ds_read_b128 v[164:167], v152
	ds_read_b128 v[168:171], v152 offset:1024
	ds_read_b128 v[172:175], v152 offset:2048
	ds_read_b128 v[176:179], v152 offset:3072
	ds_read_b128 v[180:183], v153
	ds_read_b128 v[184:187], v153 offset:1024
	ds_read_b128 v[188:191], v153 offset:2048
	ds_read_b128 v[192:195], v153 offset:3072
	ds_read_b128 v[196:199], v153 offset:4096
	ds_read_b128 v[200:203], v153 offset:5120
	ds_read_b128 v[208:211], v153 offset:6144
	ds_read_b128 v[212:215], v153 offset:7168
	s_waitcnt vmcnt(8)
	s_waitcnt lgkmcnt(0)
	s_barrier
	s_waitcnt lgkmcnt(0)
	v_mfma_f32_16x16x32_bf16 v[124:127], v[140:143], v[180:183], v[124:127]
	v_mfma_f32_16x16x32_bf16 v[120:123], v[156:159], v[180:183], v[120:123]
	v_mfma_f32_16x16x32_bf16 v[108:111], v[140:143], v[188:191], v[108:111]
	v_mfma_f32_16x16x32_bf16 v[104:107], v[156:159], v[188:191], v[104:107]
	v_mfma_f32_16x16x32_bf16 v[92:95], v[140:143], v[196:199], v[92:95]
	v_mfma_f32_16x16x32_bf16 v[88:91], v[156:159], v[196:199], v[88:91]
	v_mfma_f32_16x16x32_bf16 v[76:79], v[140:143], v[208:211], v[76:79]
	v_mfma_f32_16x16x32_bf16 v[72:75], v[156:159], v[208:211], v[72:75]
	v_mfma_f32_16x16x32_bf16 v[124:127], v[144:147], v[184:187], v[124:127]
	v_mfma_f32_16x16x32_bf16 v[120:123], v[160:163], v[184:187], v[120:123]
	v_mfma_f32_16x16x32_bf16 v[108:111], v[144:147], v[192:195], v[108:111]
	v_mfma_f32_16x16x32_bf16 v[104:107], v[160:163], v[192:195], v[104:107]
	v_mfma_f32_16x16x32_bf16 v[92:95], v[144:147], v[200:203], v[92:95]
	v_mfma_f32_16x16x32_bf16 v[88:91], v[160:163], v[200:203], v[88:91]
	v_mfma_f32_16x16x32_bf16 v[76:79], v[144:147], v[212:215], v[76:79]
	v_mfma_f32_16x16x32_bf16 v[72:75], v[160:163], v[212:215], v[72:75]
	v_mfma_f32_16x16x32_bf16 v[116:119], v[164:167], v[180:183], v[116:119]
	v_mfma_f32_16x16x32_bf16 v[112:115], v[172:175], v[180:183], v[112:115]
	v_mfma_f32_16x16x32_bf16 v[100:103], v[164:167], v[188:191], v[100:103]
	v_mfma_f32_16x16x32_bf16 v[96:99], v[172:175], v[188:191], v[96:99]
	v_mfma_f32_16x16x32_bf16 v[84:87], v[164:167], v[196:199], v[84:87]
	v_mfma_f32_16x16x32_bf16 v[80:83], v[172:175], v[196:199], v[80:83]
	v_mfma_f32_16x16x32_bf16 v[68:71], v[164:167], v[208:211], v[68:71]
	v_mfma_f32_16x16x32_bf16 v[64:67], v[172:175], v[208:211], v[64:67]
	v_mfma_f32_16x16x32_bf16 v[116:119], v[168:171], v[184:187], v[116:119]
	v_mfma_f32_16x16x32_bf16 v[112:115], v[176:179], v[184:187], v[112:115]
	v_mfma_f32_16x16x32_bf16 v[100:103], v[168:171], v[192:195], v[100:103]
	v_mfma_f32_16x16x32_bf16 v[96:99], v[176:179], v[192:195], v[96:99]
	v_mfma_f32_16x16x32_bf16 v[84:87], v[168:171], v[200:203], v[84:87]
	v_mfma_f32_16x16x32_bf16 v[80:83], v[176:179], v[200:203], v[80:83]
	v_mfma_f32_16x16x32_bf16 v[68:71], v[168:171], v[212:215], v[68:71]
	v_mfma_f32_16x16x32_bf16 v[64:67], v[176:179], v[212:215], v[64:67]
	s_barrier
	s_add_i32 s62, s54, s45
	s_mov_b32 m0, s62
	s_nop 0
	global_load_lds_dwordx4 v128, s[38:39]
	s_add_i32 m0, s62, 0x2000
	s_add_u32 s62, s38, 0x40000
	s_mov_b64 s[98:99], s[38:39]
	s_addc_u32 s63, s39, 0
	s_add_i32 s64, s55, s45
	global_load_lds_dwordx4 v130, s[38:39]
	s_mov_b32 m0, s64
	s_mov_b64 s[100:101], s[40:41]
	global_load_lds_dwordx4 v128, s[62:63]
	s_add_i32 m0, s64, 0x2000
	s_nop 0
	global_load_lds_dwordx4 v130, s[62:63]
	s_mov_b32 m0, s46
	s_nop 0
	global_load_lds_dwordx4 v128, s[40:41]
	s_mov_b32 m0, s47
	s_nop 0
	global_load_lds_dwordx4 v130, s[40:41]
	ds_read_b128 v[180:183], v153 offset:16384
	ds_read_b128 v[184:187], v153 offset:17408
	ds_read_b128 v[188:191], v153 offset:18432
	ds_read_b128 v[192:195], v153 offset:19456
	ds_read_b128 v[196:199], v153 offset:20480
	ds_read_b128 v[200:203], v153 offset:21504
	ds_read_b128 v[208:211], v153 offset:22528
	ds_read_b128 v[212:215], v153 offset:23552
	s_waitcnt vmcnt(8)
	s_waitcnt lgkmcnt(0)
	s_barrier
	s_waitcnt lgkmcnt(0)
	v_mfma_f32_16x16x32_bf16 v[60:63], v[140:143], v[180:183], v[60:63]
	v_mfma_f32_16x16x32_bf16 v[56:59], v[156:159], v[180:183], v[56:59]
	v_mfma_f32_16x16x32_bf16 v[44:47], v[140:143], v[188:191], v[44:47]
	v_mfma_f32_16x16x32_bf16 v[40:43], v[156:159], v[188:191], v[40:43]
	v_mfma_f32_16x16x32_bf16 v[28:31], v[140:143], v[196:199], v[28:31]
	v_mfma_f32_16x16x32_bf16 v[24:27], v[156:159], v[196:199], v[24:27]
	v_mfma_f32_16x16x32_bf16 v[12:15], v[140:143], v[208:211], v[12:15]
	v_mfma_f32_16x16x32_bf16 v[8:11], v[156:159], v[208:211], v[8:11]
	v_mfma_f32_16x16x32_bf16 v[60:63], v[144:147], v[184:187], v[60:63]
	v_mfma_f32_16x16x32_bf16 v[56:59], v[160:163], v[184:187], v[56:59]
	v_mfma_f32_16x16x32_bf16 v[44:47], v[144:147], v[192:195], v[44:47]
	v_mfma_f32_16x16x32_bf16 v[40:43], v[160:163], v[192:195], v[40:43]
	v_mfma_f32_16x16x32_bf16 v[28:31], v[144:147], v[200:203], v[28:31]
	v_mfma_f32_16x16x32_bf16 v[24:27], v[160:163], v[200:203], v[24:27]
	v_mfma_f32_16x16x32_bf16 v[12:15], v[144:147], v[212:215], v[12:15]
	v_mfma_f32_16x16x32_bf16 v[8:11], v[160:163], v[212:215], v[8:11]
	v_mfma_f32_16x16x32_bf16 v[52:55], v[164:167], v[180:183], v[52:55]
	v_mfma_f32_16x16x32_bf16 v[48:51], v[172:175], v[180:183], v[48:51]
	v_mfma_f32_16x16x32_bf16 v[36:39], v[164:167], v[188:191], v[36:39]
	v_mfma_f32_16x16x32_bf16 v[32:35], v[172:175], v[188:191], v[32:35]
	v_mfma_f32_16x16x32_bf16 v[20:23], v[164:167], v[196:199], v[20:23]
	v_mfma_f32_16x16x32_bf16 v[16:19], v[172:175], v[196:199], v[16:19]
	v_mfma_f32_16x16x32_bf16 v[4:7], v[164:167], v[208:211], v[4:7]
	v_mfma_f32_16x16x32_bf16 v[0:3], v[172:175], v[208:211], v[0:3]
	v_mfma_f32_16x16x32_bf16 v[52:55], v[168:171], v[184:187], v[52:55]
	v_mfma_f32_16x16x32_bf16 v[48:51], v[176:179], v[184:187], v[48:51]
	v_mfma_f32_16x16x32_bf16 v[36:39], v[168:171], v[192:195], v[36:39]
	v_mfma_f32_16x16x32_bf16 v[32:35], v[176:179], v[192:195], v[32:35]
	v_mfma_f32_16x16x32_bf16 v[20:23], v[168:171], v[200:203], v[20:23]
	v_mfma_f32_16x16x32_bf16 v[16:19], v[176:179], v[200:203], v[16:19]
	v_mfma_f32_16x16x32_bf16 v[4:7], v[168:171], v[212:215], v[4:7]
	v_mfma_f32_16x16x32_bf16 v[0:3], v[176:179], v[212:215], v[0:3]
	s_barrier
	s_add_i32 s62, 0, 0x18000
	s_add_i32 s63, 0, 0x1c000
	s_add_u32 s40, s40, 0x40000
	s_addc_u32 s41, s41, 0
	s_mov_b32 m0, s48
	s_nop 0
	global_load_lds_dwordx4 v128, s[40:41]
	s_mov_b32 m0, s49
	s_nop 0
	global_load_lds_dwordx4 v130, s[40:41]
	v_add_u32_e32 v155, s62, v149
	ds_read_b128 v[140:143], v155
	ds_read_b128 v[144:147], v155 offset:1024
	ds_read_b128 v[156:159], v155 offset:2048
	ds_read_b128 v[160:163], v155 offset:3072
	v_add_u32_e32 v155, s63, v149
	ds_read_b128 v[164:167], v155
	ds_read_b128 v[168:171], v155 offset:1024
	ds_read_b128 v[172:175], v155 offset:2048
	ds_read_b128 v[176:179], v155 offset:3072
	ds_read_b128 v[180:183], v153 offset:32768
	ds_read_b128 v[184:187], v153 offset:33792
	ds_read_b128 v[188:191], v153 offset:34816
	ds_read_b128 v[192:195], v153 offset:35840
	ds_read_b128 v[196:199], v153 offset:36864
	ds_read_b128 v[200:203], v153 offset:37888
	ds_read_b128 v[208:211], v153 offset:38912
	ds_read_b128 v[212:215], v153 offset:39936
	s_waitcnt vmcnt(8)
	s_waitcnt lgkmcnt(0)
	s_barrier
	s_waitcnt lgkmcnt(0)
	v_mfma_f32_16x16x32_bf16 v[124:127], v[140:143], v[180:183], v[124:127]
	v_mfma_f32_16x16x32_bf16 v[120:123], v[156:159], v[180:183], v[120:123]
	v_mfma_f32_16x16x32_bf16 v[108:111], v[140:143], v[188:191], v[108:111]
	v_mfma_f32_16x16x32_bf16 v[104:107], v[156:159], v[188:191], v[104:107]
	v_mfma_f32_16x16x32_bf16 v[92:95], v[140:143], v[196:199], v[92:95]
	v_mfma_f32_16x16x32_bf16 v[88:91], v[156:159], v[196:199], v[88:91]
	v_mfma_f32_16x16x32_bf16 v[76:79], v[140:143], v[208:211], v[76:79]
	v_mfma_f32_16x16x32_bf16 v[72:75], v[156:159], v[208:211], v[72:75]
	v_mfma_f32_16x16x32_bf16 v[124:127], v[144:147], v[184:187], v[124:127]
	v_mfma_f32_16x16x32_bf16 v[120:123], v[160:163], v[184:187], v[120:123]
	v_mfma_f32_16x16x32_bf16 v[108:111], v[144:147], v[192:195], v[108:111]
	v_mfma_f32_16x16x32_bf16 v[104:107], v[160:163], v[192:195], v[104:107]
	v_mfma_f32_16x16x32_bf16 v[92:95], v[144:147], v[200:203], v[92:95]
	v_mfma_f32_16x16x32_bf16 v[88:91], v[160:163], v[200:203], v[88:91]
	v_mfma_f32_16x16x32_bf16 v[76:79], v[144:147], v[212:215], v[76:79]
	v_mfma_f32_16x16x32_bf16 v[72:75], v[160:163], v[212:215], v[72:75]
	v_mfma_f32_16x16x32_bf16 v[116:119], v[164:167], v[180:183], v[116:119]
	v_mfma_f32_16x16x32_bf16 v[112:115], v[172:175], v[180:183], v[112:115]
	v_mfma_f32_16x16x32_bf16 v[100:103], v[164:167], v[188:191], v[100:103]
	v_mfma_f32_16x16x32_bf16 v[96:99], v[172:175], v[188:191], v[96:99]
	v_mfma_f32_16x16x32_bf16 v[84:87], v[164:167], v[196:199], v[84:87]
	v_mfma_f32_16x16x32_bf16 v[80:83], v[172:175], v[196:199], v[80:83]
	v_mfma_f32_16x16x32_bf16 v[68:71], v[164:167], v[208:211], v[68:71]
	v_mfma_f32_16x16x32_bf16 v[64:67], v[172:175], v[208:211], v[64:67]
	v_mfma_f32_16x16x32_bf16 v[116:119], v[168:171], v[184:187], v[116:119]
	v_mfma_f32_16x16x32_bf16 v[112:115], v[176:179], v[184:187], v[112:115]
	v_mfma_f32_16x16x32_bf16 v[100:103], v[168:171], v[192:195], v[100:103]
	v_mfma_f32_16x16x32_bf16 v[96:99], v[176:179], v[192:195], v[96:99]
	v_mfma_f32_16x16x32_bf16 v[84:87], v[168:171], v[200:203], v[84:87]
	v_mfma_f32_16x16x32_bf16 v[80:83], v[176:179], v[200:203], v[80:83]
	v_mfma_f32_16x16x32_bf16 v[68:71], v[168:171], v[212:215], v[68:71]
	v_mfma_f32_16x16x32_bf16 v[64:67], v[176:179], v[212:215], v[64:67]
	s_barrier
	s_add_i32 s40, s62, s45
	s_mov_b32 m0, s40
	s_nop 0
	global_load_lds_dwordx4 v204, s[38:39]
	s_add_i32 m0, s40, 0x2000
	s_add_u32 s38, s38, 0x40080
	s_addc_u32 s39, s39, 0
	s_add_i32 s40, s63, s45
	global_load_lds_dwordx4 v205, s[98:99]
	s_mov_b32 m0, s40
	s_nop 0
	global_load_lds_dwordx4 v128, s[38:39]
	s_add_i32 m0, s40, 0x2000
	s_nop 0
	global_load_lds_dwordx4 v130, s[38:39]
	s_mov_b32 m0, s51
	s_nop 0
	global_load_lds_dwordx4 v204, s[100:101]
	s_mov_b32 m0, s52
	s_nop 0
	global_load_lds_dwordx4 v205, s[100:101]
	ds_read_b128 v[180:183], v153 offset:49152
	ds_read_b128 v[184:187], v153 offset:50176
	ds_read_b128 v[188:191], v153 offset:51200
	ds_read_b128 v[192:195], v153 offset:52224
	ds_read_b128 v[196:199], v153 offset:53248
	ds_read_b128 v[200:203], v153 offset:54272
	ds_read_b128 v[208:211], v153 offset:55296
	ds_read_b128 v[212:215], v153 offset:56320
	s_waitcnt vmcnt(8)
	s_waitcnt lgkmcnt(0)
	s_barrier
	s_waitcnt lgkmcnt(0)
	v_mfma_f32_16x16x32_bf16 v[60:63], v[140:143], v[180:183], v[60:63]
	v_mfma_f32_16x16x32_bf16 v[56:59], v[156:159], v[180:183], v[56:59]
	v_mfma_f32_16x16x32_bf16 v[44:47], v[140:143], v[188:191], v[44:47]
	v_mfma_f32_16x16x32_bf16 v[40:43], v[156:159], v[188:191], v[40:43]
	v_mfma_f32_16x16x32_bf16 v[28:31], v[140:143], v[196:199], v[28:31]
	v_mfma_f32_16x16x32_bf16 v[24:27], v[156:159], v[196:199], v[24:27]
	v_mfma_f32_16x16x32_bf16 v[12:15], v[140:143], v[208:211], v[12:15]
	v_mfma_f32_16x16x32_bf16 v[8:11], v[156:159], v[208:211], v[8:11]
	v_mfma_f32_16x16x32_bf16 v[60:63], v[144:147], v[184:187], v[60:63]
	v_mfma_f32_16x16x32_bf16 v[56:59], v[160:163], v[184:187], v[56:59]
	v_mfma_f32_16x16x32_bf16 v[44:47], v[144:147], v[192:195], v[44:47]
	v_mfma_f32_16x16x32_bf16 v[40:43], v[160:163], v[192:195], v[40:43]
	v_mfma_f32_16x16x32_bf16 v[28:31], v[144:147], v[200:203], v[28:31]
	v_mfma_f32_16x16x32_bf16 v[24:27], v[160:163], v[200:203], v[24:27]
	v_mfma_f32_16x16x32_bf16 v[12:15], v[144:147], v[212:215], v[12:15]
	v_mfma_f32_16x16x32_bf16 v[8:11], v[160:163], v[212:215], v[8:11]
	v_mfma_f32_16x16x32_bf16 v[52:55], v[164:167], v[180:183], v[52:55]
	v_mfma_f32_16x16x32_bf16 v[48:51], v[172:175], v[180:183], v[48:51]
	v_mfma_f32_16x16x32_bf16 v[36:39], v[164:167], v[188:191], v[36:39]
	v_mfma_f32_16x16x32_bf16 v[32:35], v[172:175], v[188:191], v[32:35]
	v_mfma_f32_16x16x32_bf16 v[20:23], v[164:167], v[196:199], v[20:23]
	v_mfma_f32_16x16x32_bf16 v[16:19], v[172:175], v[196:199], v[16:19]
	v_mfma_f32_16x16x32_bf16 v[4:7], v[164:167], v[208:211], v[4:7]
	v_mfma_f32_16x16x32_bf16 v[0:3], v[172:175], v[208:211], v[0:3]
	v_mfma_f32_16x16x32_bf16 v[52:55], v[168:171], v[184:187], v[52:55]
	v_mfma_f32_16x16x32_bf16 v[48:51], v[176:179], v[184:187], v[48:51]
	v_mfma_f32_16x16x32_bf16 v[36:39], v[168:171], v[192:195], v[36:39]
	v_mfma_f32_16x16x32_bf16 v[32:35], v[176:179], v[192:195], v[32:35]
	v_mfma_f32_16x16x32_bf16 v[20:23], v[168:171], v[200:203], v[20:23]
	v_mfma_f32_16x16x32_bf16 v[16:19], v[176:179], v[200:203], v[16:19]
	v_mfma_f32_16x16x32_bf16 v[4:7], v[168:171], v[212:215], v[4:7]
	v_mfma_f32_16x16x32_bf16 v[0:3], v[176:179], v[212:215], v[0:3]
	s_barrier
	s_add_i32 s61, s61, 2
	s_add_u32 s59, s59, 0x100
	s_addc_u32 s60, s60, 0
	s_add_u32 s36, s36, 0x100
	s_addc_u32 s37, s37, 0
	s_cmp_gt_u32 s61, 13
	s_cbranch_scc0 .LBB0_1561
	s_setprio 0
	s_and_b64 vcc, exec, s[24:25]
	s_cbranch_vccz .LBB0_1564
	s_barrier

.LBB0_1646:
	s_add_u32 s26, s24, 0xfffc0080
	s_addc_u32 s27, s25, -1
	s_cmp_eq_u32 s54, 12
	s_cselect_b32 s29, s19, s27
	s_cselect_b32 s28, s50, s26
	s_cselect_b32 s27, s17, s53
	s_cselect_b32 s26, s51, s52
	s_add_i32 m0, s38, 0xc000
	s_nop 0
	global_load_lds_dwordx4 v138, s[24:25]
	s_add_i32 m0, s38, 0xe000
	s_nop 0
	global_load_lds_dwordx4 v136, s[24:25]
	ds_read_b128 v[144:147], v151
	ds_read_b128 v[156:159], v151 offset:1024
	ds_read_b128 v[160:163], v151 offset:2048
	ds_read_b128 v[164:167], v151 offset:3072
	ds_read_b128 v[168:171], v152
	ds_read_b128 v[172:175], v152 offset:1024
	ds_read_b128 v[176:179], v152 offset:2048
	ds_read_b128 v[180:183], v152 offset:3072
	ds_read_b128 v[184:187], v153
	ds_read_b128 v[188:191], v153 offset:1024
	ds_read_b128 v[192:195], v153 offset:2048
	ds_read_b128 v[196:199], v153 offset:3072
	ds_read_b128 v[200:203], v153 offset:4096
	ds_read_b128 v[208:211], v153 offset:5120
	ds_read_b128 v[212:215], v153 offset:6144
	ds_read_b128 v[216:219], v153 offset:7168
	s_waitcnt vmcnt(8)
	s_waitcnt lgkmcnt(0)
	s_barrier
	s_waitcnt lgkmcnt(0)
	v_mfma_f32_16x16x32_bf16 v[124:127], v[144:147], v[184:187], v[124:127]
	v_mfma_f32_16x16x32_bf16 v[120:123], v[160:163], v[184:187], v[120:123]
	v_mfma_f32_16x16x32_bf16 v[108:111], v[144:147], v[192:195], v[108:111]
	v_mfma_f32_16x16x32_bf16 v[104:107], v[160:163], v[192:195], v[104:107]
	v_mfma_f32_16x16x32_bf16 v[92:95], v[144:147], v[200:203], v[92:95]
	v_mfma_f32_16x16x32_bf16 v[88:91], v[160:163], v[200:203], v[88:91]
	v_mfma_f32_16x16x32_bf16 v[76:79], v[144:147], v[212:215], v[76:79]
	v_mfma_f32_16x16x32_bf16 v[72:75], v[160:163], v[212:215], v[72:75]
	v_mfma_f32_16x16x32_bf16 v[124:127], v[156:159], v[188:191], v[124:127]
	v_mfma_f32_16x16x32_bf16 v[120:123], v[164:167], v[188:191], v[120:123]
	v_mfma_f32_16x16x32_bf16 v[108:111], v[156:159], v[196:199], v[108:111]
	v_mfma_f32_16x16x32_bf16 v[104:107], v[164:167], v[196:199], v[104:107]
	v_mfma_f32_16x16x32_bf16 v[92:95], v[156:159], v[208:211], v[92:95]
	v_mfma_f32_16x16x32_bf16 v[88:91], v[164:167], v[208:211], v[88:91]
	v_mfma_f32_16x16x32_bf16 v[76:79], v[156:159], v[216:219], v[76:79]
	v_mfma_f32_16x16x32_bf16 v[72:75], v[164:167], v[216:219], v[72:75]
	v_mfma_f32_16x16x32_bf16 v[116:119], v[168:171], v[184:187], v[116:119]
	v_mfma_f32_16x16x32_bf16 v[112:115], v[176:179], v[184:187], v[112:115]
	v_mfma_f32_16x16x32_bf16 v[100:103], v[168:171], v[192:195], v[100:103]
	v_mfma_f32_16x16x32_bf16 v[96:99], v[176:179], v[192:195], v[96:99]
	v_mfma_f32_16x16x32_bf16 v[84:87], v[168:171], v[200:203], v[84:87]
	v_mfma_f32_16x16x32_bf16 v[80:83], v[176:179], v[200:203], v[80:83]
	v_mfma_f32_16x16x32_bf16 v[68:71], v[168:171], v[212:215], v[68:71]
	v_mfma_f32_16x16x32_bf16 v[64:67], v[176:179], v[212:215], v[64:67]
	v_mfma_f32_16x16x32_bf16 v[116:119], v[172:175], v[188:191], v[116:119]
	v_mfma_f32_16x16x32_bf16 v[112:115], v[180:183], v[188:191], v[112:115]
	v_mfma_f32_16x16x32_bf16 v[100:103], v[172:175], v[196:199], v[100:103]
	v_mfma_f32_16x16x32_bf16 v[96:99], v[180:183], v[196:199], v[96:99]
	v_mfma_f32_16x16x32_bf16 v[84:87], v[172:175], v[208:211], v[84:87]
	v_mfma_f32_16x16x32_bf16 v[80:83], v[180:183], v[208:211], v[80:83]
	v_mfma_f32_16x16x32_bf16 v[68:71], v[172:175], v[216:219], v[68:71]
	v_mfma_f32_16x16x32_bf16 v[64:67], v[180:183], v[216:219], v[64:67]
	s_barrier
	s_add_i32 s55, s47, s35
	s_mov_b32 m0, s55
	s_nop 0
	global_load_lds_dwordx4 v132, s[26:27]
	s_add_i32 m0, s55, 0x2000
	s_add_u32 s56, s26, 0x40000
	s_mov_b64 s[98:99], s[26:27]
	s_addc_u32 s57, s27, 0
	s_add_i32 s55, s48, s35
	global_load_lds_dwordx4 v128, s[26:27]
	s_mov_b32 m0, s55
	s_mov_b64 s[100:101], s[28:29]
	global_load_lds_dwordx4 v132, s[56:57]
	s_add_i32 m0, s55, 0x2000
	s_nop 0
	global_load_lds_dwordx4 v128, s[56:57]
	s_mov_b32 m0, s38
	s_nop 0
	global_load_lds_dwordx4 v134, s[28:29]
	s_mov_b32 m0, s39
	s_nop 0
	global_load_lds_dwordx4 v130, s[28:29]
	ds_read_b128 v[184:187], v153 offset:16384
	ds_read_b128 v[188:191], v153 offset:17408
	ds_read_b128 v[192:195], v153 offset:18432
	ds_read_b128 v[196:199], v153 offset:19456
	ds_read_b128 v[200:203], v153 offset:20480
	ds_read_b128 v[208:211], v153 offset:21504
	ds_read_b128 v[212:215], v153 offset:22528
	ds_read_b128 v[216:219], v153 offset:23552
	s_waitcnt vmcnt(8)
	s_waitcnt lgkmcnt(0)
	s_barrier
	s_waitcnt lgkmcnt(0)
	v_mfma_f32_16x16x32_bf16 v[60:63], v[144:147], v[184:187], v[60:63]
	v_mfma_f32_16x16x32_bf16 v[56:59], v[160:163], v[184:187], v[56:59]
	v_mfma_f32_16x16x32_bf16 v[44:47], v[144:147], v[192:195], v[44:47]
	v_mfma_f32_16x16x32_bf16 v[40:43], v[160:163], v[192:195], v[40:43]
	v_mfma_f32_16x16x32_bf16 v[28:31], v[144:147], v[200:203], v[28:31]
	v_mfma_f32_16x16x32_bf16 v[24:27], v[160:163], v[200:203], v[24:27]
	v_mfma_f32_16x16x32_bf16 v[12:15], v[144:147], v[212:215], v[12:15]
	v_mfma_f32_16x16x32_bf16 v[8:11], v[160:163], v[212:215], v[8:11]
	v_mfma_f32_16x16x32_bf16 v[60:63], v[156:159], v[188:191], v[60:63]
	v_mfma_f32_16x16x32_bf16 v[56:59], v[164:167], v[188:191], v[56:59]
	v_mfma_f32_16x16x32_bf16 v[44:47], v[156:159], v[196:199], v[44:47]
	v_mfma_f32_16x16x32_bf16 v[40:43], v[164:167], v[196:199], v[40:43]
	v_mfma_f32_16x16x32_bf16 v[28:31], v[156:159], v[208:211], v[28:31]
	v_mfma_f32_16x16x32_bf16 v[24:27], v[164:167], v[208:211], v[24:27]
	v_mfma_f32_16x16x32_bf16 v[12:15], v[156:159], v[216:219], v[12:15]
	v_mfma_f32_16x16x32_bf16 v[8:11], v[164:167], v[216:219], v[8:11]
	v_mfma_f32_16x16x32_bf16 v[52:55], v[168:171], v[184:187], v[52:55]
	v_mfma_f32_16x16x32_bf16 v[48:51], v[176:179], v[184:187], v[48:51]
	v_mfma_f32_16x16x32_bf16 v[36:39], v[168:171], v[192:195], v[36:39]
	v_mfma_f32_16x16x32_bf16 v[32:35], v[176:179], v[192:195], v[32:35]
	v_mfma_f32_16x16x32_bf16 v[20:23], v[168:171], v[200:203], v[20:23]
	v_mfma_f32_16x16x32_bf16 v[16:19], v[176:179], v[200:203], v[16:19]
	v_mfma_f32_16x16x32_bf16 v[4:7], v[168:171], v[212:215], v[4:7]
	v_mfma_f32_16x16x32_bf16 v[0:3], v[176:179], v[212:215], v[0:3]
	v_mfma_f32_16x16x32_bf16 v[52:55], v[172:175], v[188:191], v[52:55]
	v_mfma_f32_16x16x32_bf16 v[48:51], v[180:183], v[188:191], v[48:51]
	v_mfma_f32_16x16x32_bf16 v[36:39], v[172:175], v[196:199], v[36:39]
	v_mfma_f32_16x16x32_bf16 v[32:35], v[180:183], v[196:199], v[32:35]
	v_mfma_f32_16x16x32_bf16 v[20:23], v[172:175], v[208:211], v[20:23]
	v_mfma_f32_16x16x32_bf16 v[16:19], v[180:183], v[208:211], v[16:19]
	v_mfma_f32_16x16x32_bf16 v[4:7], v[172:175], v[216:219], v[4:7]
	v_mfma_f32_16x16x32_bf16 v[0:3], v[180:183], v[216:219], v[0:3]
	s_barrier
	s_add_i32 s55, 0, 0x18000
	s_add_i32 s56, 0, 0x1c000
	s_add_u32 s28, s28, 0x40000
	s_addc_u32 s29, s29, 0
	s_mov_b32 m0, s40
	s_nop 0
	global_load_lds_dwordx4 v134, s[28:29]
	s_mov_b32 m0, s41
	s_nop 0
	global_load_lds_dwordx4 v130, s[28:29]
	v_add_u32_e32 v164, s55, v149
	v_add_u32_e32 v180, s56, v149
	ds_read_b128 v[144:147], v164
	ds_read_b128 v[156:159], v164 offset:1024
	ds_read_b128 v[160:163], v164 offset:2048
	ds_read_b128 v[164:167], v164 offset:3072
	ds_read_b128 v[168:171], v180
	ds_read_b128 v[172:175], v180 offset:1024
	ds_read_b128 v[176:179], v180 offset:2048
	ds_read_b128 v[180:183], v180 offset:3072
	ds_read_b128 v[184:187], v153 offset:32768
	ds_read_b128 v[188:191], v153 offset:33792
	ds_read_b128 v[192:195], v153 offset:34816
	ds_read_b128 v[196:199], v153 offset:35840
	ds_read_b128 v[200:203], v153 offset:36864
	ds_read_b128 v[208:211], v153 offset:37888
	ds_read_b128 v[212:215], v153 offset:38912
	ds_read_b128 v[216:219], v153 offset:39936
	s_waitcnt vmcnt(8)
	s_waitcnt lgkmcnt(0)
	s_barrier
	s_waitcnt lgkmcnt(0)
	v_mfma_f32_16x16x32_bf16 v[124:127], v[144:147], v[184:187], v[124:127]
	v_mfma_f32_16x16x32_bf16 v[120:123], v[160:163], v[184:187], v[120:123]
	v_mfma_f32_16x16x32_bf16 v[108:111], v[144:147], v[192:195], v[108:111]
	v_mfma_f32_16x16x32_bf16 v[104:107], v[160:163], v[192:195], v[104:107]
	v_mfma_f32_16x16x32_bf16 v[92:95], v[144:147], v[200:203], v[92:95]
	v_mfma_f32_16x16x32_bf16 v[88:91], v[160:163], v[200:203], v[88:91]
	v_mfma_f32_16x16x32_bf16 v[76:79], v[144:147], v[212:215], v[76:79]
	v_mfma_f32_16x16x32_bf16 v[72:75], v[160:163], v[212:215], v[72:75]
	v_mfma_f32_16x16x32_bf16 v[124:127], v[156:159], v[188:191], v[124:127]
	v_mfma_f32_16x16x32_bf16 v[120:123], v[164:167], v[188:191], v[120:123]
	v_mfma_f32_16x16x32_bf16 v[108:111], v[156:159], v[196:199], v[108:111]
	v_mfma_f32_16x16x32_bf16 v[104:107], v[164:167], v[196:199], v[104:107]
	v_mfma_f32_16x16x32_bf16 v[92:95], v[156:159], v[208:211], v[92:95]
	v_mfma_f32_16x16x32_bf16 v[88:91], v[164:167], v[208:211], v[88:91]
	v_mfma_f32_16x16x32_bf16 v[76:79], v[156:159], v[216:219], v[76:79]
	v_mfma_f32_16x16x32_bf16 v[72:75], v[164:167], v[216:219], v[72:75]
	v_mfma_f32_16x16x32_bf16 v[116:119], v[168:171], v[184:187], v[116:119]
	v_mfma_f32_16x16x32_bf16 v[112:115], v[176:179], v[184:187], v[112:115]
	v_mfma_f32_16x16x32_bf16 v[100:103], v[168:171], v[192:195], v[100:103]
	v_mfma_f32_16x16x32_bf16 v[96:99], v[176:179], v[192:195], v[96:99]
	v_mfma_f32_16x16x32_bf16 v[84:87], v[168:171], v[200:203], v[84:87]
	v_mfma_f32_16x16x32_bf16 v[80:83], v[176:179], v[200:203], v[80:83]
	v_mfma_f32_16x16x32_bf16 v[68:71], v[168:171], v[212:215], v[68:71]
	v_mfma_f32_16x16x32_bf16 v[64:67], v[176:179], v[212:215], v[64:67]
	v_mfma_f32_16x16x32_bf16 v[116:119], v[172:175], v[188:191], v[116:119]
	v_mfma_f32_16x16x32_bf16 v[112:115], v[180:183], v[188:191], v[112:115]
	v_mfma_f32_16x16x32_bf16 v[100:103], v[172:175], v[196:199], v[100:103]
	v_mfma_f32_16x16x32_bf16 v[96:99], v[180:183], v[196:199], v[96:99]
	v_mfma_f32_16x16x32_bf16 v[84:87], v[172:175], v[208:211], v[84:87]
	v_mfma_f32_16x16x32_bf16 v[80:83], v[180:183], v[208:211], v[80:83]
	v_mfma_f32_16x16x32_bf16 v[68:71], v[172:175], v[216:219], v[68:71]
	v_mfma_f32_16x16x32_bf16 v[64:67], v[180:183], v[216:219], v[64:67]
	s_barrier
	s_add_i32 s28, s55, s35
	s_mov_b32 m0, s28
	s_nop 0
	global_load_lds_dwordx4 v220, s[26:27]
	s_add_i32 m0, s28, 0x2000
	s_add_u32 s26, s26, 0x40080
	s_addc_u32 s27, s27, 0
	s_add_i32 s28, s56, s35
	global_load_lds_dwordx4 v204, s[98:99]
	s_mov_b32 m0, s28
	s_nop 0
	global_load_lds_dwordx4 v132, s[26:27]
	s_add_i32 m0, s28, 0x2000
	s_nop 0
	global_load_lds_dwordx4 v128, s[26:27]
	s_mov_b32 m0, s45
	s_nop 0
	global_load_lds_dwordx4 v221, s[100:101]
	s_mov_b32 m0, s46
	s_nop 0
	global_load_lds_dwordx4 v205, s[100:101]
	ds_read_b128 v[184:187], v153 offset:49152
	ds_read_b128 v[188:191], v153 offset:50176
	ds_read_b128 v[192:195], v153 offset:51200
	ds_read_b128 v[196:199], v153 offset:52224
	ds_read_b128 v[200:203], v153 offset:53248
	ds_read_b128 v[208:211], v153 offset:54272
	ds_read_b128 v[212:215], v153 offset:55296
	ds_read_b128 v[216:219], v153 offset:56320
	s_waitcnt vmcnt(8)
	s_waitcnt lgkmcnt(0)
	s_barrier
	s_waitcnt lgkmcnt(0)
	v_mfma_f32_16x16x32_bf16 v[60:63], v[144:147], v[184:187], v[60:63]
	v_mfma_f32_16x16x32_bf16 v[56:59], v[160:163], v[184:187], v[56:59]
	v_mfma_f32_16x16x32_bf16 v[44:47], v[144:147], v[192:195], v[44:47]
	v_mfma_f32_16x16x32_bf16 v[40:43], v[160:163], v[192:195], v[40:43]
	v_mfma_f32_16x16x32_bf16 v[28:31], v[144:147], v[200:203], v[28:31]
	v_mfma_f32_16x16x32_bf16 v[24:27], v[160:163], v[200:203], v[24:27]
	v_mfma_f32_16x16x32_bf16 v[12:15], v[144:147], v[212:215], v[12:15]
	v_mfma_f32_16x16x32_bf16 v[8:11], v[160:163], v[212:215], v[8:11]
	v_mfma_f32_16x16x32_bf16 v[60:63], v[156:159], v[188:191], v[60:63]
	v_mfma_f32_16x16x32_bf16 v[56:59], v[164:167], v[188:191], v[56:59]
	v_mfma_f32_16x16x32_bf16 v[44:47], v[156:159], v[196:199], v[44:47]
	v_mfma_f32_16x16x32_bf16 v[40:43], v[164:167], v[196:199], v[40:43]
	v_mfma_f32_16x16x32_bf16 v[28:31], v[156:159], v[208:211], v[28:31]
	v_mfma_f32_16x16x32_bf16 v[24:27], v[164:167], v[208:211], v[24:27]
	v_mfma_f32_16x16x32_bf16 v[12:15], v[156:159], v[216:219], v[12:15]
	v_mfma_f32_16x16x32_bf16 v[8:11], v[164:167], v[216:219], v[8:11]
	v_mfma_f32_16x16x32_bf16 v[52:55], v[168:171], v[184:187], v[52:55]
	v_mfma_f32_16x16x32_bf16 v[48:51], v[176:179], v[184:187], v[48:51]
	v_mfma_f32_16x16x32_bf16 v[36:39], v[168:171], v[192:195], v[36:39]
	v_mfma_f32_16x16x32_bf16 v[32:35], v[176:179], v[192:195], v[32:35]
	v_mfma_f32_16x16x32_bf16 v[20:23], v[168:171], v[200:203], v[20:23]
	v_mfma_f32_16x16x32_bf16 v[16:19], v[176:179], v[200:203], v[16:19]
	v_mfma_f32_16x16x32_bf16 v[4:7], v[168:171], v[212:215], v[4:7]
	v_mfma_f32_16x16x32_bf16 v[0:3], v[176:179], v[212:215], v[0:3]
	v_mfma_f32_16x16x32_bf16 v[52:55], v[172:175], v[188:191], v[52:55]
	v_mfma_f32_16x16x32_bf16 v[48:51], v[180:183], v[188:191], v[48:51]
	v_mfma_f32_16x16x32_bf16 v[36:39], v[172:175], v[196:199], v[36:39]
	v_mfma_f32_16x16x32_bf16 v[32:35], v[180:183], v[196:199], v[32:35]
	v_mfma_f32_16x16x32_bf16 v[20:23], v[172:175], v[208:211], v[20:23]
	v_mfma_f32_16x16x32_bf16 v[16:19], v[180:183], v[208:211], v[16:19]
	v_mfma_f32_16x16x32_bf16 v[4:7], v[172:175], v[216:219], v[4:7]
	v_mfma_f32_16x16x32_bf16 v[0:3], v[180:183], v[216:219], v[0:3]
	s_barrier
	s_add_i32 s54, s54, 2
	s_add_u32 s52, s52, 0x100
	s_addc_u32 s53, s53, 0
	s_add_u32 s24, s24, 0x100
	s_addc_u32 s25, s25, 0
	s_cmp_gt_u32 s54, 13
	s_cbranch_scc0 .LBB0_1646
	s_setprio 0
	s_and_b64 vcc, exec, s[14:15]
	s_cbranch_vccz .LBB0_1649
	s_barrier
